# GEMM 8-phase loops: pre-barrier s_waitcnt lgkmcnt(8) removed (the lgkmcnt(0) behind the barrier covers the reads)
# speedup vs baseline: 1.0038x; 1.0038x over previous
.LBB0_190:
	ds_read_b128 v[180:183], v172
	ds_read_b128 v[184:187], v172 offset:1024
	ds_read_b128 v[188:191], v172 offset:2048
	ds_read_b128 v[192:195], v172 offset:3072
	v_add_u32_e32 v178, 0xc000, v152
	v_lshl_add_u64 v[244:245], s[20:21], 0, v[146:147]
	v_readfirstlane_b32 s1, v178
	v_add_u32_e32 v179, 0xe000, v152
	v_lshl_add_u64 v[224:225], v[244:245], 0, s[48:49]
	s_mov_b32 m0, s1
	v_lshl_add_u64 v[246:247], s[20:21], 0, v[148:149]
	v_readfirstlane_b32 s1, v179
	ds_read_b128 v[174:177], v161
	ds_read_b128 v[196:199], v161 offset:1024
	ds_read_b128 v[200:203], v160
	ds_read_b128 v[204:207], v160 offset:1024
	ds_read_b128 v[208:211], v159
	ds_read_b128 v[212:215], v159 offset:1024
	ds_read_b128 v[216:219], v158
	ds_read_b128 v[220:223], v158 offset:1024
	global_load_lds_dwordx4 v[224:225], off
	v_lshl_add_u64 v[224:225], v[246:247], 0, s[48:49]
	s_mov_b32 m0, s1
	s_nop 0
	global_load_lds_dwordx4 v[224:225], off
	s_barrier
	s_waitcnt lgkmcnt(0)
	v_mfma_f32_16x16x32_bf16 v[124:127], v[180:183], v[174:177], v[124:127]
	v_mfma_f32_16x16x32_bf16 v[120:123], v[188:191], v[174:177], v[120:123]
	v_mfma_f32_16x16x32_bf16 v[116:119], v[180:183], v[200:203], v[116:119]
	v_mfma_f32_16x16x32_bf16 v[112:115], v[188:191], v[200:203], v[112:115]
	v_mfma_f32_16x16x32_bf16 v[108:111], v[180:183], v[208:211], v[108:111]
	v_mfma_f32_16x16x32_bf16 v[104:107], v[188:191], v[208:211], v[104:107]
	v_mfma_f32_16x16x32_bf16 v[100:103], v[180:183], v[216:219], v[100:103]
	v_mfma_f32_16x16x32_bf16 v[96:99], v[188:191], v[216:219], v[96:99]
	v_mfma_f32_16x16x32_bf16 v[124:127], v[184:187], v[196:199], v[124:127]
	v_mfma_f32_16x16x32_bf16 v[120:123], v[192:195], v[196:199], v[120:123]
	v_mfma_f32_16x16x32_bf16 v[116:119], v[184:187], v[204:207], v[116:119]
	v_mfma_f32_16x16x32_bf16 v[112:115], v[192:195], v[204:207], v[112:115]
	v_mfma_f32_16x16x32_bf16 v[108:111], v[184:187], v[212:215], v[108:111]
	v_mfma_f32_16x16x32_bf16 v[104:107], v[192:195], v[212:215], v[104:107]
	v_mfma_f32_16x16x32_bf16 v[100:103], v[184:187], v[220:223], v[100:103]
	v_mfma_f32_16x16x32_bf16 v[96:99], v[192:195], v[220:223], v[96:99]
	s_barrier
	v_lshl_add_u64 v[248:249], s[20:21], 0, v[142:143]
	v_readfirstlane_b32 s1, v153
	v_add_u32_e32 v173, 0x2000, v153
	v_lshl_add_u64 v[240:241], v[248:249], 0, s[50:51]
	s_mov_b32 m0, s1
	v_lshl_add_u64 v[250:251], s[20:21], 0, v[144:145]
	v_readfirstlane_b32 s1, v173
	ds_read_b128 v[224:227], v169
	ds_read_b128 v[228:231], v169 offset:1024
	ds_read_b128 v[232:235], v169 offset:2048
	ds_read_b128 v[236:239], v169 offset:3072
	global_load_lds_dwordx4 v[240:241], off
	v_lshl_add_u64 v[240:241], v[250:251], 0, s[50:51]
	s_mov_b32 m0, s1
	s_nop 0
	global_load_lds_dwordx4 v[240:241], off
	s_barrier
	s_waitcnt lgkmcnt(0)
	v_mfma_f32_16x16x32_bf16 v[92:95], v[224:227], v[174:177], v[92:95]
	v_mfma_f32_16x16x32_bf16 v[88:91], v[232:235], v[174:177], v[88:91]
	v_mfma_f32_16x16x32_bf16 v[84:87], v[224:227], v[200:203], v[84:87]
	v_mfma_f32_16x16x32_bf16 v[80:83], v[232:235], v[200:203], v[80:83]
	v_mfma_f32_16x16x32_bf16 v[76:79], v[224:227], v[208:211], v[76:79]
	v_mfma_f32_16x16x32_bf16 v[72:75], v[232:235], v[208:211], v[72:75]
	v_mfma_f32_16x16x32_bf16 v[68:71], v[224:227], v[216:219], v[68:71]
	v_mfma_f32_16x16x32_bf16 v[64:67], v[232:235], v[216:219], v[64:67]
	v_mfma_f32_16x16x32_bf16 v[92:95], v[228:231], v[196:199], v[92:95]
	v_mfma_f32_16x16x32_bf16 v[88:91], v[236:239], v[196:199], v[88:91]
	v_mfma_f32_16x16x32_bf16 v[84:87], v[228:231], v[204:207], v[84:87]
	v_mfma_f32_16x16x32_bf16 v[80:83], v[236:239], v[204:207], v[80:83]
	v_mfma_f32_16x16x32_bf16 v[76:79], v[228:231], v[212:215], v[76:79]
	v_mfma_f32_16x16x32_bf16 v[72:75], v[236:239], v[212:215], v[72:75]
	v_mfma_f32_16x16x32_bf16 v[68:71], v[228:231], v[220:223], v[68:71]
	v_mfma_f32_16x16x32_bf16 v[64:67], v[236:239], v[220:223], v[64:67]
	v_readfirstlane_b32 s1, v152
	v_lshl_add_u64 v[174:175], v[244:245], 0, s[52:53]
	s_mov_b32 m0, s1
	s_barrier
	ds_read_b128 v[196:199], v161 offset:16384
	ds_read_b128 v[200:203], v161 offset:17408
	ds_read_b128 v[204:207], v160 offset:16384
	ds_read_b128 v[208:211], v160 offset:17408
	ds_read_b128 v[212:215], v159 offset:16384
	ds_read_b128 v[216:219], v159 offset:17408
	ds_read_b128 v[220:223], v158 offset:16384
	ds_read_b128 v[240:243], v158 offset:17408
	global_load_lds_dwordx4 v[174:175], off
	v_add_u32_e32 v174, 0x2000, v152
	v_lshl_add_u64 v[176:177], v[246:247], 0, s[52:53]
	v_readfirstlane_b32 s1, v174
	s_mov_b32 m0, s1
	s_nop 0
	global_load_lds_dwordx4 v[176:177], off
	s_barrier
	s_waitcnt lgkmcnt(0)
	v_mfma_f32_16x16x32_bf16 v[60:63], v[180:183], v[196:199], v[60:63]
	v_mfma_f32_16x16x32_bf16 v[56:59], v[188:191], v[196:199], v[56:59]
	v_mfma_f32_16x16x32_bf16 v[52:55], v[180:183], v[204:207], v[52:55]
	v_mfma_f32_16x16x32_bf16 v[48:51], v[188:191], v[204:207], v[48:51]
	v_mfma_f32_16x16x32_bf16 v[44:47], v[180:183], v[212:215], v[44:47]
	v_mfma_f32_16x16x32_bf16 v[40:43], v[188:191], v[212:215], v[40:43]
	v_mfma_f32_16x16x32_bf16 v[36:39], v[180:183], v[220:223], v[36:39]
	v_mfma_f32_16x16x32_bf16 v[32:35], v[188:191], v[220:223], v[32:35]
	v_mfma_f32_16x16x32_bf16 v[60:63], v[184:187], v[200:203], v[60:63]
	v_mfma_f32_16x16x32_bf16 v[56:59], v[192:195], v[200:203], v[56:59]
	v_mfma_f32_16x16x32_bf16 v[52:55], v[184:187], v[208:211], v[52:55]
	v_mfma_f32_16x16x32_bf16 v[48:51], v[192:195], v[208:211], v[48:51]
	v_mfma_f32_16x16x32_bf16 v[44:47], v[184:187], v[216:219], v[44:47]
	v_mfma_f32_16x16x32_bf16 v[40:43], v[192:195], v[216:219], v[40:43]
	v_mfma_f32_16x16x32_bf16 v[36:39], v[184:187], v[240:243], v[36:39]
	v_mfma_f32_16x16x32_bf16 v[32:35], v[192:195], v[240:243], v[32:35]
	s_barrier
	v_readfirstlane_b32 s1, v151
	v_add_u32_e32 v175, 0x2000, v151
	v_lshl_add_u64 v[176:177], v[248:249], 0, s[54:55]
	s_mov_b32 m0, s1
	v_readfirstlane_b32 s1, v175
	global_load_lds_dwordx4 v[176:177], off
	v_lshl_add_u64 v[176:177], v[250:251], 0, s[54:55]
	s_mov_b32 m0, s1
	s_nop 0
	global_load_lds_dwordx4 v[176:177], off
	s_waitcnt vmcnt(6)
	s_barrier
	v_mfma_f32_16x16x32_bf16 v[28:31], v[224:227], v[196:199], v[28:31]
	v_mfma_f32_16x16x32_bf16 v[24:27], v[232:235], v[196:199], v[24:27]
	v_mfma_f32_16x16x32_bf16 v[20:23], v[224:227], v[204:207], v[20:23]
	v_mfma_f32_16x16x32_bf16 v[16:19], v[232:235], v[204:207], v[16:19]
	v_mfma_f32_16x16x32_bf16 v[12:15], v[224:227], v[212:215], v[12:15]
	v_mfma_f32_16x16x32_bf16 v[8:11], v[232:235], v[212:215], v[8:11]
	v_mfma_f32_16x16x32_bf16 v[4:7], v[224:227], v[220:223], v[4:7]
	v_mfma_f32_16x16x32_bf16 v[0:3], v[232:235], v[220:223], v[0:3]
	v_mfma_f32_16x16x32_bf16 v[28:31], v[228:231], v[200:203], v[28:31]
	v_mfma_f32_16x16x32_bf16 v[24:27], v[236:239], v[200:203], v[24:27]
	v_mfma_f32_16x16x32_bf16 v[20:23], v[228:231], v[208:211], v[20:23]
	v_mfma_f32_16x16x32_bf16 v[16:19], v[236:239], v[208:211], v[16:19]
	v_mfma_f32_16x16x32_bf16 v[12:15], v[228:231], v[216:219], v[12:15]
	v_mfma_f32_16x16x32_bf16 v[8:11], v[236:239], v[216:219], v[8:11]
	v_mfma_f32_16x16x32_bf16 v[4:7], v[228:231], v[240:243], v[4:7]
	v_mfma_f32_16x16x32_bf16 v[0:3], v[236:239], v[240:243], v[0:3]
	s_barrier
	ds_read_b128 v[180:183], v163
	ds_read_b128 v[184:187], v163 offset:1024
	ds_read_b128 v[188:191], v163 offset:2048
	ds_read_b128 v[192:195], v163 offset:3072
	v_add_u32_e32 v176, 0x4000, v152
	v_add_u32_e32 v177, 0x6000, v152
	v_readfirstlane_b32 s1, v176
	v_lshl_add_u64 v[228:229], v[244:245], 0, s[56:57]
	s_mov_b32 m0, s1
	v_readfirstlane_b32 s1, v177
	ds_read_b128 v[196:199], v161 offset:32768
	ds_read_b128 v[200:203], v161 offset:33792
	ds_read_b128 v[204:207], v160 offset:32768
	ds_read_b128 v[208:211], v160 offset:33792
	ds_read_b128 v[212:215], v159 offset:32768
	ds_read_b128 v[216:219], v159 offset:33792
	ds_read_b128 v[220:223], v158 offset:32768
	ds_read_b128 v[224:227], v158 offset:33792
	global_load_lds_dwordx4 v[228:229], off
	v_lshl_add_u64 v[228:229], v[246:247], 0, s[56:57]
	s_mov_b32 m0, s1
	s_nop 0
	global_load_lds_dwordx4 v[228:229], off
	s_barrier
	s_waitcnt lgkmcnt(0)
	v_mfma_f32_16x16x32_bf16 v[124:127], v[180:183], v[196:199], v[124:127]
	v_mfma_f32_16x16x32_bf16 v[120:123], v[188:191], v[196:199], v[120:123]
	v_mfma_f32_16x16x32_bf16 v[116:119], v[180:183], v[204:207], v[116:119]
	v_mfma_f32_16x16x32_bf16 v[112:115], v[188:191], v[204:207], v[112:115]
	v_mfma_f32_16x16x32_bf16 v[108:111], v[180:183], v[212:215], v[108:111]
	v_mfma_f32_16x16x32_bf16 v[104:107], v[188:191], v[212:215], v[104:107]
	v_mfma_f32_16x16x32_bf16 v[100:103], v[180:183], v[220:223], v[100:103]
	v_mfma_f32_16x16x32_bf16 v[96:99], v[188:191], v[220:223], v[96:99]
	v_mfma_f32_16x16x32_bf16 v[124:127], v[184:187], v[200:203], v[124:127]
	v_mfma_f32_16x16x32_bf16 v[120:123], v[192:195], v[200:203], v[120:123]
	v_mfma_f32_16x16x32_bf16 v[116:119], v[184:187], v[208:211], v[116:119]
	v_mfma_f32_16x16x32_bf16 v[112:115], v[192:195], v[208:211], v[112:115]
	v_mfma_f32_16x16x32_bf16 v[108:111], v[184:187], v[216:219], v[108:111]
	v_mfma_f32_16x16x32_bf16 v[104:107], v[192:195], v[216:219], v[104:107]
	v_mfma_f32_16x16x32_bf16 v[100:103], v[184:187], v[224:227], v[100:103]
	v_mfma_f32_16x16x32_bf16 v[96:99], v[192:195], v[224:227], v[96:99]
	s_barrier
	v_readfirstlane_b32 s1, v167
	v_add_u32_e32 v254, 0x2000, v167
	v_lshl_add_u64 v[252:253], v[248:249], 0, s[58:59]
	s_mov_b32 m0, s1
	v_readfirstlane_b32 s1, v254
	ds_read_b128 v[228:231], v162
	ds_read_b128 v[232:235], v162 offset:1024
	ds_read_b128 v[236:239], v162 offset:2048
	ds_read_b128 v[240:243], v162 offset:3072
	global_load_lds_dwordx4 v[252:253], off
	v_lshl_add_u64 v[252:253], v[250:251], 0, s[58:59]
	s_mov_b32 m0, s1
	s_nop 0
	global_load_lds_dwordx4 v[252:253], off
	s_barrier
	s_waitcnt lgkmcnt(0)
	v_mfma_f32_16x16x32_bf16 v[92:95], v[228:231], v[196:199], v[92:95]
	v_mfma_f32_16x16x32_bf16 v[88:91], v[236:239], v[196:199], v[88:91]
	v_mfma_f32_16x16x32_bf16 v[84:87], v[228:231], v[204:207], v[84:87]
	v_mfma_f32_16x16x32_bf16 v[80:83], v[236:239], v[204:207], v[80:83]
	v_mfma_f32_16x16x32_bf16 v[76:79], v[228:231], v[212:215], v[76:79]
	v_mfma_f32_16x16x32_bf16 v[72:75], v[236:239], v[212:215], v[72:75]
	v_mfma_f32_16x16x32_bf16 v[68:71], v[228:231], v[220:223], v[68:71]
	v_mfma_f32_16x16x32_bf16 v[64:67], v[236:239], v[220:223], v[64:67]
	v_mfma_f32_16x16x32_bf16 v[92:95], v[232:235], v[200:203], v[92:95]
	v_mfma_f32_16x16x32_bf16 v[88:91], v[240:243], v[200:203], v[88:91]
	v_mfma_f32_16x16x32_bf16 v[84:87], v[232:235], v[208:211], v[84:87]
	v_mfma_f32_16x16x32_bf16 v[80:83], v[240:243], v[208:211], v[80:83]
	v_mfma_f32_16x16x32_bf16 v[76:79], v[232:235], v[216:219], v[76:79]
	v_mfma_f32_16x16x32_bf16 v[72:75], v[240:243], v[216:219], v[72:75]
	v_mfma_f32_16x16x32_bf16 v[68:71], v[232:235], v[224:227], v[68:71]
	v_mfma_f32_16x16x32_bf16 v[64:67], v[240:243], v[224:227], v[64:67]
	v_readfirstlane_b32 s1, v168
	v_lshl_add_u64 v[244:245], v[244:245], 0, s[60:61]
	s_mov_b32 m0, s1
	v_readfirstlane_b32 s1, v170
	s_barrier
	ds_read_b128 v[196:199], v161 offset:49152
	ds_read_b128 v[200:203], v161 offset:50176
	ds_read_b128 v[204:207], v160 offset:49152
	ds_read_b128 v[208:211], v160 offset:50176
	ds_read_b128 v[212:215], v159 offset:49152
	ds_read_b128 v[216:219], v159 offset:50176
	ds_read_b128 v[220:223], v158 offset:49152
	ds_read_b128 v[224:227], v158 offset:50176
	global_load_lds_dwordx4 v[244:245], off
	v_lshl_add_u64 v[244:245], v[246:247], 0, s[60:61]
	s_mov_b32 m0, s1
	s_nop 0
	global_load_lds_dwordx4 v[244:245], off
	s_barrier
	s_waitcnt lgkmcnt(0)
	v_mfma_f32_16x16x32_bf16 v[60:63], v[180:183], v[196:199], v[60:63]
	v_mfma_f32_16x16x32_bf16 v[56:59], v[188:191], v[196:199], v[56:59]
	v_mfma_f32_16x16x32_bf16 v[52:55], v[180:183], v[204:207], v[52:55]
	v_mfma_f32_16x16x32_bf16 v[48:51], v[188:191], v[204:207], v[48:51]
	v_mfma_f32_16x16x32_bf16 v[44:47], v[180:183], v[212:215], v[44:47]
	v_mfma_f32_16x16x32_bf16 v[40:43], v[188:191], v[212:215], v[40:43]
	v_mfma_f32_16x16x32_bf16 v[36:39], v[180:183], v[220:223], v[36:39]
	v_mfma_f32_16x16x32_bf16 v[32:35], v[188:191], v[220:223], v[32:35]
	v_mfma_f32_16x16x32_bf16 v[60:63], v[184:187], v[200:203], v[60:63]
	v_mfma_f32_16x16x32_bf16 v[56:59], v[192:195], v[200:203], v[56:59]
	v_mfma_f32_16x16x32_bf16 v[52:55], v[184:187], v[208:211], v[52:55]
	v_mfma_f32_16x16x32_bf16 v[48:51], v[192:195], v[208:211], v[48:51]
	v_mfma_f32_16x16x32_bf16 v[44:47], v[184:187], v[216:219], v[44:47]
	v_mfma_f32_16x16x32_bf16 v[40:43], v[192:195], v[216:219], v[40:43]
	v_mfma_f32_16x16x32_bf16 v[36:39], v[184:187], v[224:227], v[36:39]
	v_mfma_f32_16x16x32_bf16 v[32:35], v[192:195], v[224:227], v[32:35]
	s_barrier
	v_readfirstlane_b32 s1, v171
	v_add_u32_e32 v182, 0x2000, v171
	v_lshl_add_u64 v[180:181], v[248:249], 0, s[62:63]
	s_mov_b32 m0, s1
	v_readfirstlane_b32 s1, v182
	global_load_lds_dwordx4 v[180:181], off
	v_lshl_add_u64 v[180:181], v[250:251], 0, s[62:63]
	s_mov_b32 m0, s1
	s_nop 0
	global_load_lds_dwordx4 v[180:181], off
	s_waitcnt vmcnt(6)
	s_barrier
	v_mfma_f32_16x16x32_bf16 v[28:31], v[228:231], v[196:199], v[28:31]
	v_mfma_f32_16x16x32_bf16 v[24:27], v[236:239], v[196:199], v[24:27]
	v_mfma_f32_16x16x32_bf16 v[20:23], v[228:231], v[204:207], v[20:23]
	v_mfma_f32_16x16x32_bf16 v[16:19], v[236:239], v[204:207], v[16:19]
	v_mfma_f32_16x16x32_bf16 v[12:15], v[228:231], v[212:215], v[12:15]
	v_mfma_f32_16x16x32_bf16 v[8:11], v[236:239], v[212:215], v[8:11]
	v_mfma_f32_16x16x32_bf16 v[4:7], v[228:231], v[220:223], v[4:7]
	v_mfma_f32_16x16x32_bf16 v[0:3], v[236:239], v[220:223], v[0:3]
	v_mfma_f32_16x16x32_bf16 v[28:31], v[232:235], v[200:203], v[28:31]
	v_mfma_f32_16x16x32_bf16 v[24:27], v[240:243], v[200:203], v[24:27]
	v_mfma_f32_16x16x32_bf16 v[20:23], v[232:235], v[208:211], v[20:23]
	v_mfma_f32_16x16x32_bf16 v[16:19], v[240:243], v[208:211], v[16:19]
	v_mfma_f32_16x16x32_bf16 v[12:15], v[232:235], v[216:219], v[12:15]
	v_mfma_f32_16x16x32_bf16 v[8:11], v[240:243], v[216:219], v[8:11]
	v_mfma_f32_16x16x32_bf16 v[4:7], v[232:235], v[224:227], v[4:7]
	v_mfma_f32_16x16x32_bf16 v[0:3], v[240:243], v[224:227], v[0:3]
	s_add_i32 s0, s0, 2
	v_lshl_add_u64 v[142:143], v[142:143], 0, s[50:51]
	v_lshl_add_u64 v[144:145], v[144:145], 0, s[50:51]
	v_lshl_add_u64 v[146:147], v[146:147], 0, s[50:51]
	s_cmp_lt_u32 s0, 12
	v_lshl_add_u64 v[148:149], v[148:149], 0, s[50:51]
	s_barrier
	s_cbranch_scc1 .LBB0_190
	s_or_b32 s0, s6, 0x80
	s_ashr_i32 s1, s0, 31
	s_lshl_b64 s[0:1], s[0:1], 11
	s_add_u32 s0, s45, s0
	s_addc_u32 s1, s46, s1
	v_lshl_add_u64 v[170:171], s[0:1], 0, v[130:131]
	v_lshl_add_u64 v[138:139], v[138:139], 1, v[170:171]
	v_readfirstlane_b32 s2, v178
	v_lshl_add_u64 v[138:139], v[138:139], 0, s[64:65]
	s_mov_b32 m0, s2
	ds_read_b128 v[142:145], v172
	ds_read_b128 v[146:149], v172 offset:1024
	ds_read_b128 v[180:183], v172 offset:2048
	ds_read_b128 v[184:187], v172 offset:3072
	ds_read_b128 v[188:191], v161
	ds_read_b128 v[192:195], v161 offset:1024
	ds_read_b128 v[196:199], v160
	ds_read_b128 v[200:203], v160 offset:1024
	ds_read_b128 v[204:207], v159
	ds_read_b128 v[208:211], v159 offset:1024
	ds_read_b128 v[212:215], v158
	ds_read_b128 v[216:219], v158 offset:1024
	global_load_lds_dwordx4 v[138:139], off
	v_lshl_add_u64 v[138:139], s[0:1], 0, v[134:135]
	v_lshl_add_u64 v[138:139], v[140:141], 1, v[138:139]
	v_readfirstlane_b32 s0, v179
	v_lshl_add_u64 v[138:139], v[138:139], 0, s[64:65]
	s_mov_b32 m0, s0
	v_readlane_b32 s0, v255, 11
	global_load_lds_dwordx4 v[138:139], off
	s_add_i32 s82, s82, s0
	s_barrier
	s_waitcnt lgkmcnt(0)
	s_cmpk_gt_i32 s82, 0x54
	s_cselect_b64 s[66:67], -1, 0
	s_waitcnt lgkmcnt(0)
	v_mfma_f32_16x16x32_bf16 v[124:127], v[142:145], v[188:191], v[124:127]
	v_mfma_f32_16x16x32_bf16 v[116:119], v[142:145], v[196:199], v[116:119]
	v_mfma_f32_16x16x32_bf16 v[108:111], v[142:145], v[204:207], v[108:111]
	v_mfma_f32_16x16x32_bf16 v[100:103], v[142:145], v[212:215], v[100:103]
	v_mfma_f32_16x16x32_bf16 v[124:127], v[146:149], v[192:195], v[124:127]
	v_mfma_f32_16x16x32_bf16 v[120:123], v[180:183], v[188:191], v[120:123]
	v_mfma_f32_16x16x32_bf16 v[116:119], v[146:149], v[200:203], v[116:119]
	v_mfma_f32_16x16x32_bf16 v[112:115], v[180:183], v[196:199], v[112:115]
	v_mfma_f32_16x16x32_bf16 v[108:111], v[146:149], v[208:211], v[108:111]
	v_mfma_f32_16x16x32_bf16 v[104:107], v[180:183], v[204:207], v[104:107]
	v_mfma_f32_16x16x32_bf16 v[100:103], v[146:149], v[216:219], v[100:103]
	v_mfma_f32_16x16x32_bf16 v[96:99], v[180:183], v[212:215], v[96:99]
	v_mfma_f32_16x16x32_bf16 v[138:141], v[184:187], v[192:195], v[120:123]
	v_mfma_f32_16x16x32_bf16 v[220:223], v[184:187], v[200:203], v[112:115]
	v_mfma_f32_16x16x32_bf16 v[224:227], v[184:187], v[208:211], v[104:107]
	v_mfma_f32_16x16x32_bf16 v[228:231], v[184:187], v[216:219], v[96:99]
	s_barrier
	s_nop 1
	ds_read_b128 v[96:99], v169
	ds_read_b128 v[104:107], v169 offset:1024
	ds_read_b128 v[112:115], v169 offset:2048
	ds_read_b128 v[120:123], v169 offset:3072
	s_barrier
	s_waitcnt lgkmcnt(0)
	v_mfma_f32_16x16x32_bf16 v[92:95], v[96:99], v[188:191], v[92:95]
	v_mfma_f32_16x16x32_bf16 v[88:91], v[112:115], v[188:191], v[88:91]
	v_mfma_f32_16x16x32_bf16 v[84:87], v[96:99], v[196:199], v[84:87]
	v_mfma_f32_16x16x32_bf16 v[80:83], v[112:115], v[196:199], v[80:83]
	v_mfma_f32_16x16x32_bf16 v[76:79], v[96:99], v[204:207], v[76:79]
	v_mfma_f32_16x16x32_bf16 v[72:75], v[112:115], v[204:207], v[72:75]
	v_mfma_f32_16x16x32_bf16 v[68:71], v[96:99], v[212:215], v[68:71]
	v_mfma_f32_16x16x32_bf16 v[64:67], v[112:115], v[212:215], v[64:67]
	v_mfma_f32_16x16x32_bf16 v[92:95], v[104:107], v[192:195], v[92:95]
	v_mfma_f32_16x16x32_bf16 v[88:91], v[120:123], v[192:195], v[88:91]
	v_mfma_f32_16x16x32_bf16 v[84:87], v[104:107], v[200:203], v[84:87]
	v_mfma_f32_16x16x32_bf16 v[80:83], v[120:123], v[200:203], v[80:83]
	v_mfma_f32_16x16x32_bf16 v[76:79], v[104:107], v[208:211], v[76:79]
	v_mfma_f32_16x16x32_bf16 v[72:75], v[120:123], v[208:211], v[72:75]
	v_mfma_f32_16x16x32_bf16 v[68:71], v[104:107], v[216:219], v[68:71]
	v_mfma_f32_16x16x32_bf16 v[64:67], v[120:123], v[216:219], v[64:67]
	s_barrier
	ds_read_b128 v[168:171], v161 offset:16384
	ds_read_b128 v[188:191], v161 offset:17408
	ds_read_b128 v[192:195], v160 offset:16384
	ds_read_b128 v[196:199], v160 offset:17408
	ds_read_b128 v[200:203], v159 offset:16384
	ds_read_b128 v[204:207], v159 offset:17408
	ds_read_b128 v[208:211], v158 offset:16384
	ds_read_b128 v[212:215], v158 offset:17408
	s_waitcnt vmcnt(4)
	s_barrier
	s_waitcnt lgkmcnt(0)
	v_mfma_f32_16x16x32_bf16 v[60:63], v[142:145], v[168:171], v[60:63]
	v_mfma_f32_16x16x32_bf16 v[52:55], v[142:145], v[192:195], v[52:55]
	v_mfma_f32_16x16x32_bf16 v[44:47], v[142:145], v[200:203], v[44:47]
	v_mfma_f32_16x16x32_bf16 v[36:39], v[142:145], v[208:211], v[36:39]
	v_mfma_f32_16x16x32_bf16 v[60:63], v[146:149], v[188:191], v[60:63]
	v_mfma_f32_16x16x32_bf16 v[56:59], v[180:183], v[168:171], v[56:59]
	v_mfma_f32_16x16x32_bf16 v[52:55], v[146:149], v[196:199], v[52:55]
	v_mfma_f32_16x16x32_bf16 v[48:51], v[180:183], v[192:195], v[48:51]
	v_mfma_f32_16x16x32_bf16 v[44:47], v[146:149], v[204:207], v[44:47]
	v_mfma_f32_16x16x32_bf16 v[40:43], v[180:183], v[200:203], v[40:43]
	v_mfma_f32_16x16x32_bf16 v[36:39], v[146:149], v[212:215], v[36:39]
	v_mfma_f32_16x16x32_bf16 v[32:35], v[180:183], v[208:211], v[32:35]
	v_mfma_f32_16x16x32_bf16 v[216:219], v[184:187], v[188:191], v[56:59]
	v_mfma_f32_16x16x32_bf16 v[232:235], v[184:187], v[196:199], v[48:51]
	v_mfma_f32_16x16x32_bf16 v[236:239], v[184:187], v[204:207], v[40:43]
	v_mfma_f32_16x16x32_bf16 v[142:145], v[184:187], v[212:215], v[32:35]
	v_mfma_f32_16x16x32_bf16 v[28:31], v[96:99], v[168:171], v[28:31]
	v_mfma_f32_16x16x32_bf16 v[24:27], v[112:115], v[168:171], v[24:27]
	v_mfma_f32_16x16x32_bf16 v[20:23], v[96:99], v[192:195], v[20:23]
	v_mfma_f32_16x16x32_bf16 v[16:19], v[112:115], v[192:195], v[16:19]
	v_mfma_f32_16x16x32_bf16 v[12:15], v[96:99], v[200:203], v[12:15]
	v_mfma_f32_16x16x32_bf16 v[8:11], v[112:115], v[200:203], v[8:11]
	v_mfma_f32_16x16x32_bf16 v[4:7], v[96:99], v[208:211], v[4:7]
	v_mfma_f32_16x16x32_bf16 v[0:3], v[112:115], v[208:211], v[0:3]
	v_mfma_f32_16x16x32_bf16 v[28:31], v[104:107], v[188:191], v[28:31]
	v_mfma_f32_16x16x32_bf16 v[24:27], v[120:123], v[188:191], v[24:27]
	v_mfma_f32_16x16x32_bf16 v[20:23], v[104:107], v[196:199], v[20:23]
	v_mfma_f32_16x16x32_bf16 v[16:19], v[120:123], v[196:199], v[16:19]
	v_mfma_f32_16x16x32_bf16 v[12:15], v[104:107], v[204:207], v[12:15]
	v_mfma_f32_16x16x32_bf16 v[8:11], v[120:123], v[204:207], v[8:11]
	v_mfma_f32_16x16x32_bf16 v[4:7], v[104:107], v[212:215], v[4:7]
	v_mfma_f32_16x16x32_bf16 v[0:3], v[120:123], v[212:215], v[0:3]
	s_barrier
	ds_read_b128 v[32:35], v163
	ds_read_b128 v[146:149], v163 offset:1024
	ds_read_b128 v[168:171], v163 offset:2048
	ds_read_b128 v[178:181], v163 offset:3072
	ds_read_b128 v[40:43], v161 offset:32768
	ds_read_b128 v[48:51], v161 offset:33792
	ds_read_b128 v[56:59], v160 offset:32768
	ds_read_b128 v[182:185], v160 offset:33792
	ds_read_b128 v[186:189], v159 offset:32768
	ds_read_b128 v[190:193], v159 offset:33792
	ds_read_b128 v[194:197], v158 offset:32768
	ds_read_b128 v[198:201], v158 offset:33792
	s_waitcnt vmcnt(2)
	s_barrier
	s_waitcnt lgkmcnt(0)
	v_mfma_f32_16x16x32_bf16 v[96:99], v[32:35], v[40:43], v[124:127]
	v_mfma_f32_16x16x32_bf16 v[120:123], v[146:149], v[48:51], v[96:99]
	v_mfma_f32_16x16x32_bf16 v[96:99], v[168:171], v[40:43], v[138:141]
	v_mfma_f32_16x16x32_bf16 v[124:127], v[178:181], v[48:51], v[96:99]
	v_mfma_f32_16x16x32_bf16 v[96:99], v[32:35], v[56:59], v[116:119]
	v_mfma_f32_16x16x32_bf16 v[112:115], v[146:149], v[182:185], v[96:99]
	v_mfma_f32_16x16x32_bf16 v[96:99], v[168:171], v[56:59], v[220:223]
	v_mfma_f32_16x16x32_bf16 v[116:119], v[178:181], v[182:185], v[96:99]
	v_mfma_f32_16x16x32_bf16 v[96:99], v[32:35], v[186:189], v[108:111]
	v_mfma_f32_16x16x32_bf16 v[104:107], v[146:149], v[190:193], v[96:99]
	v_mfma_f32_16x16x32_bf16 v[96:99], v[168:171], v[186:189], v[224:227]
	v_mfma_f32_16x16x32_bf16 v[108:111], v[178:181], v[190:193], v[96:99]
	v_mfma_f32_16x16x32_bf16 v[96:99], v[32:35], v[194:197], v[100:103]
	v_mfma_f32_16x16x32_bf16 v[100:103], v[168:171], v[194:197], v[228:231]
	v_mfma_f32_16x16x32_bf16 v[96:99], v[146:149], v[198:201], v[96:99]
	v_mfma_f32_16x16x32_bf16 v[100:103], v[178:181], v[198:201], v[100:103]
	s_barrier
	ds_read_b128 v[138:141], v162
	ds_read_b128 v[202:205], v162 offset:1024
	ds_read_b128 v[206:209], v162 offset:2048
	ds_read_b128 v[210:213], v162 offset:3072
	s_waitcnt vmcnt(0)
	s_barrier
	s_waitcnt lgkmcnt(0)
	v_mfma_f32_16x16x32_bf16 v[92:95], v[138:141], v[40:43], v[92:95]
	v_mfma_f32_16x16x32_bf16 v[40:43], v[206:209], v[40:43], v[88:91]
	v_mfma_f32_16x16x32_bf16 v[88:91], v[210:213], v[48:51], v[40:43]
	v_mfma_f32_16x16x32_bf16 v[40:43], v[138:141], v[56:59], v[84:87]
	v_mfma_f32_16x16x32_bf16 v[84:87], v[202:205], v[182:185], v[40:43]
	v_mfma_f32_16x16x32_bf16 v[40:43], v[206:209], v[56:59], v[80:83]
	v_mfma_f32_16x16x32_bf16 v[80:83], v[210:213], v[182:185], v[40:43]
	v_mfma_f32_16x16x32_bf16 v[40:43], v[138:141], v[186:189], v[76:79]
	v_mfma_f32_16x16x32_bf16 v[76:79], v[202:205], v[190:193], v[40:43]
	v_mfma_f32_16x16x32_bf16 v[40:43], v[206:209], v[186:189], v[72:75]
	v_mfma_f32_16x16x32_bf16 v[72:75], v[210:213], v[190:193], v[40:43]
	v_mfma_f32_16x16x32_bf16 v[40:43], v[138:141], v[194:197], v[68:71]
	v_mfma_f32_16x16x32_bf16 v[68:71], v[202:205], v[198:201], v[40:43]
	v_mfma_f32_16x16x32_bf16 v[40:43], v[206:209], v[194:197], v[64:67]
	v_mfma_f32_16x16x32_bf16 v[92:95], v[202:205], v[48:51], v[92:95]
	v_mfma_f32_16x16x32_bf16 v[64:67], v[210:213], v[198:201], v[40:43]
	s_barrier
	ds_read_b128 v[182:185], v161 offset:49152
	ds_read_b128 v[186:189], v161 offset:50176
	ds_read_b128 v[190:193], v160 offset:49152
	ds_read_b128 v[160:163], v160 offset:50176
	ds_read_b128 v[194:197], v159 offset:49152
	ds_read_b128 v[198:201], v159 offset:50176
	ds_read_b128 v[220:223], v158 offset:49152
	ds_read_b128 v[224:227], v158 offset:50176
	s_barrier
	s_waitcnt lgkmcnt(0)
	v_mfma_f32_16x16x32_bf16 v[40:43], v[32:35], v[182:185], v[60:63]
	v_mfma_f32_16x16x32_bf16 v[56:59], v[146:149], v[186:189], v[40:43]
	v_mfma_f32_16x16x32_bf16 v[40:43], v[168:171], v[182:185], v[216:219]
	v_mfma_f32_16x16x32_bf16 v[60:63], v[178:181], v[186:189], v[40:43]
	v_mfma_f32_16x16x32_bf16 v[40:43], v[32:35], v[190:193], v[52:55]
	v_mfma_f32_16x16x32_bf16 v[48:51], v[146:149], v[160:163], v[40:43]
	v_mfma_f32_16x16x32_bf16 v[40:43], v[168:171], v[190:193], v[232:235]
	v_mfma_f32_16x16x32_bf16 v[52:55], v[178:181], v[160:163], v[40:43]
	v_mfma_f32_16x16x32_bf16 v[40:43], v[32:35], v[194:197], v[44:47]
	v_mfma_f32_16x16x32_bf16 v[44:47], v[168:171], v[194:197], v[236:239]
	v_mfma_f32_16x16x32_bf16 v[32:35], v[32:35], v[220:223], v[36:39]
	v_mfma_f32_16x16x32_bf16 v[36:39], v[168:171], v[220:223], v[142:145]
	v_mfma_f32_16x16x32_bf16 v[40:43], v[146:149], v[198:201], v[40:43]
	v_mfma_f32_16x16x32_bf16 v[44:47], v[178:181], v[198:201], v[44:47]
	v_mfma_f32_16x16x32_bf16 v[32:35], v[146:149], v[224:227], v[32:35]
	v_mfma_f32_16x16x32_bf16 v[36:39], v[178:181], v[224:227], v[36:39]
	v_mfma_f32_16x16x32_bf16 v[28:31], v[138:141], v[182:185], v[28:31]
	v_mfma_f32_16x16x32_bf16 v[24:27], v[206:209], v[182:185], v[24:27]
	v_mfma_f32_16x16x32_bf16 v[20:23], v[138:141], v[190:193], v[20:23]
	v_mfma_f32_16x16x32_bf16 v[16:19], v[206:209], v[190:193], v[16:19]
	v_mfma_f32_16x16x32_bf16 v[12:15], v[138:141], v[194:197], v[12:15]
	v_mfma_f32_16x16x32_bf16 v[8:11], v[206:209], v[194:197], v[8:11]
	v_mfma_f32_16x16x32_bf16 v[4:7], v[138:141], v[220:223], v[4:7]
	v_mfma_f32_16x16x32_bf16 v[0:3], v[206:209], v[220:223], v[0:3]
	v_mfma_f32_16x16x32_bf16 v[28:31], v[202:205], v[186:189], v[28:31]
	v_mfma_f32_16x16x32_bf16 v[24:27], v[210:213], v[186:189], v[24:27]
	v_mfma_f32_16x16x32_bf16 v[20:23], v[202:205], v[160:163], v[20:23]
	v_mfma_f32_16x16x32_bf16 v[16:19], v[210:213], v[160:163], v[16:19]
	v_mfma_f32_16x16x32_bf16 v[12:15], v[202:205], v[198:201], v[12:15]
	v_mfma_f32_16x16x32_bf16 v[8:11], v[210:213], v[198:201], v[8:11]
	v_mfma_f32_16x16x32_bf16 v[4:7], v[202:205], v[224:227], v[4:7]
	v_mfma_f32_16x16x32_bf16 v[0:3], v[210:213], v[224:227], v[0:3]
	s_and_b64 vcc, exec, s[66:67]
	s_barrier
	s_cbranch_vccnz .LBB0_193
	s_mul_hi_i32 s0, s82, 0x66666667
	s_lshr_b32 s1, s0, 31
	s_ashr_i32 s0, s0, 1
	s_add_i32 s0, s0, s1
	v_readlane_b32 s1, v255, 15
	s_add_i32 s1, s0, s1
	s_mul_i32 s0, s0, 5
	s_sub_i32 s0, s82, s0
	v_readlane_b32 s2, v255, 14
	s_add_i32 s2, s0, s2
	s_lshl_b32 s8, s2, 8
	s_ashr_i32 s9, s8, 31
	s_lshl_b32 s0, s1, 8
	s_lshl_b64 s[40:41], s[8:9], 11
	s_add_u32 s40, s20, s40
	s_addc_u32 s41, s21, s41
	v_lshl_add_u64 v[138:139], s[40:41], 0, v[130:131]
	v_readfirstlane_b32 s1, v153
	v_lshl_add_u64 v[138:139], v[138:139], 0, v[132:133]
	s_mov_b32 m0, s1
	v_readfirstlane_b32 s1, v173
	global_load_lds_dwordx4 v[138:139], off
	s_mov_b32 m0, s1
	s_ashr_i32 s1, s0, 31
	v_lshl_add_u64 v[138:139], s[40:41], 0, v[134:135]
	s_lshl_b64 s[40:41], s[0:1], 11
	s_add_u32 s40, s45, s40
	v_lshl_add_u64 v[138:139], v[138:139], 0, v[136:137]
	s_addc_u32 s41, s46, s41
	s_bitset1_b32 s8, 7
	global_load_lds_dwordx4 v[138:139], off
	v_lshl_add_u64 v[138:139], s[40:41], 0, v[130:131]
	v_readfirstlane_b32 s1, v152
	s_ashr_i32 s9, s8, 31
	v_lshl_add_u64 v[138:139], v[138:139], 0, v[132:133]
	s_mov_b32 m0, s1
	s_lshl_b64 s[8:9], s[8:9], 11
	global_load_lds_dwordx4 v[138:139], off
	v_lshl_add_u64 v[138:139], s[40:41], 0, v[134:135]
	v_readfirstlane_b32 s1, v174
	s_add_u32 s8, s20, s8
	v_lshl_add_u64 v[138:139], v[138:139], 0, v[136:137]
	s_mov_b32 m0, s1
	s_addc_u32 s9, s21, s9
	global_load_lds_dwordx4 v[138:139], off
	v_lshl_add_u64 v[138:139], s[8:9], 0, v[130:131]
	v_readfirstlane_b32 s1, v151
	v_lshl_add_u64 v[138:139], v[138:139], 0, v[132:133]
	s_mov_b32 m0, s1
	v_readfirstlane_b32 s1, v175
	s_bitset1_b32 s0, 7
	global_load_lds_dwordx4 v[138:139], off
	s_mov_b32 m0, s1
	s_ashr_i32 s1, s0, 31
	s_lshl_b64 s[0:1], s[0:1], 11
	s_add_u32 s0, s45, s0
	v_lshl_add_u64 v[138:139], s[8:9], 0, v[134:135]
	s_addc_u32 s1, s46, s1
	v_lshl_add_u64 v[138:139], v[138:139], 0, v[136:137]
	v_lshl_add_u64 v[130:131], s[0:1], 0, v[130:131]
	v_readfirstlane_b32 s2, v176
	global_load_lds_dwordx4 v[138:139], off
	v_lshl_add_u64 v[130:131], v[130:131], 0, v[132:133]
	s_mov_b32 m0, s2
	s_nop 0
	global_load_lds_dwordx4 v[130:131], off
	v_lshl_add_u64 v[130:131], s[0:1], 0, v[134:135]
	v_readfirstlane_b32 s0, v177
	v_lshl_add_u64 v[130:131], v[130:131], 0, v[136:137]
	s_mov_b32 m0, s0
	s_nop 0
	global_load_lds_dwordx4 v[130:131], off

.LBB0_1529:
	ds_read_b128 v[182:185], v180
	ds_read_b128 v[186:189], v180 offset:1024
	ds_read_b128 v[190:193], v180 offset:2048
	ds_read_b128 v[194:197], v180 offset:3072
	v_add_u32_e32 v0, 0xc000, v162
	v_lshl_add_u64 v[246:247], v[142:143], 0, s[60:61]
	v_readfirstlane_b32 s1, v0
	v_lshl_add_u64 v[2:3], v[246:247], 0, s[18:19]
	s_mov_b32 m0, s1
	ds_read_b128 v[198:201], v161
	ds_read_b128 v[202:205], v161 offset:1024
	ds_read_b128 v[206:209], v160
	ds_read_b128 v[210:213], v160 offset:1024
	ds_read_b128 v[214:217], v159
	ds_read_b128 v[218:221], v159 offset:1024
	ds_read_b128 v[222:225], v158
	ds_read_b128 v[226:229], v158 offset:1024
	global_load_lds_dwordx4 v[2:3], off
	v_add_u32_e32 v2, 0xe000, v162
	v_lshl_add_u64 v[248:249], v[144:145], 0, s[60:61]
	v_readfirstlane_b32 s1, v2
	v_lshl_add_u64 v[230:231], v[248:249], 0, s[18:19]
	s_mov_b32 m0, s1
	s_nop 0
	global_load_lds_dwordx4 v[230:231], off
	s_barrier
	s_waitcnt lgkmcnt(0)
	v_mfma_f32_16x16x32_bf16 v[128:131], v[182:185], v[198:201], v[128:131]
	v_mfma_f32_16x16x32_bf16 v[124:127], v[190:193], v[198:201], v[124:127]
	v_mfma_f32_16x16x32_bf16 v[120:123], v[182:185], v[206:209], v[120:123]
	v_mfma_f32_16x16x32_bf16 v[116:119], v[190:193], v[206:209], v[116:119]
	v_mfma_f32_16x16x32_bf16 v[112:115], v[182:185], v[214:217], v[112:115]
	v_mfma_f32_16x16x32_bf16 v[108:111], v[190:193], v[214:217], v[108:111]
	v_mfma_f32_16x16x32_bf16 v[104:107], v[182:185], v[222:225], v[104:107]
	v_mfma_f32_16x16x32_bf16 v[100:103], v[190:193], v[222:225], v[100:103]
	v_mfma_f32_16x16x32_bf16 v[128:131], v[186:189], v[202:205], v[128:131]
	v_mfma_f32_16x16x32_bf16 v[124:127], v[194:197], v[202:205], v[124:127]
	v_mfma_f32_16x16x32_bf16 v[120:123], v[186:189], v[210:213], v[120:123]
	v_mfma_f32_16x16x32_bf16 v[116:119], v[194:197], v[210:213], v[116:119]
	v_mfma_f32_16x16x32_bf16 v[112:115], v[186:189], v[218:221], v[112:115]
	v_mfma_f32_16x16x32_bf16 v[108:111], v[194:197], v[218:221], v[108:111]
	v_mfma_f32_16x16x32_bf16 v[104:107], v[186:189], v[226:229], v[104:107]
	v_mfma_f32_16x16x32_bf16 v[100:103], v[194:197], v[226:229], v[100:103]
	s_barrier
	v_lshl_add_u64 v[250:251], v[138:139], 0, s[60:61]
	v_readfirstlane_b32 s1, v147
	v_lshl_add_u64 v[252:253], v[250:251], 0, s[20:21]
	s_mov_b32 m0, s1
	v_add_u32_e32 v3, 0x2000, v147
	ds_read_b128 v[230:233], v178
	ds_read_b128 v[234:237], v178 offset:1024
	ds_read_b128 v[238:241], v178 offset:2048
	ds_read_b128 v[242:245], v178 offset:3072
	global_load_lds_dwordx4 v[252:253], off
	v_lshl_add_u64 v[252:253], v[140:141], 0, s[60:61]
	v_readfirstlane_b32 s1, v3
	v_lshl_add_u64 v[132:133], v[252:253], 0, s[20:21]
	s_mov_b32 m0, s1
	s_add_i32 s1, s0, 2
	global_load_lds_dwordx4 v[132:133], off
	s_barrier
	s_waitcnt lgkmcnt(0)
	v_mfma_f32_16x16x32_bf16 v[96:99], v[230:233], v[198:201], v[96:99]
	v_mfma_f32_16x16x32_bf16 v[92:95], v[238:241], v[198:201], v[92:95]
	v_mfma_f32_16x16x32_bf16 v[88:91], v[230:233], v[206:209], v[88:91]
	v_mfma_f32_16x16x32_bf16 v[84:87], v[238:241], v[206:209], v[84:87]
	v_mfma_f32_16x16x32_bf16 v[80:83], v[230:233], v[214:217], v[80:83]
	v_mfma_f32_16x16x32_bf16 v[76:79], v[238:241], v[214:217], v[76:79]
	v_mfma_f32_16x16x32_bf16 v[72:75], v[230:233], v[222:225], v[72:75]
	v_mfma_f32_16x16x32_bf16 v[68:71], v[238:241], v[222:225], v[68:71]
	v_mfma_f32_16x16x32_bf16 v[96:99], v[234:237], v[202:205], v[96:99]
	v_mfma_f32_16x16x32_bf16 v[92:95], v[242:245], v[202:205], v[92:95]
	v_mfma_f32_16x16x32_bf16 v[88:91], v[234:237], v[210:213], v[88:91]
	v_mfma_f32_16x16x32_bf16 v[84:87], v[242:245], v[210:213], v[84:87]
	v_mfma_f32_16x16x32_bf16 v[80:83], v[234:237], v[218:221], v[80:83]
	v_mfma_f32_16x16x32_bf16 v[76:79], v[242:245], v[218:221], v[76:79]
	v_mfma_f32_16x16x32_bf16 v[72:75], v[234:237], v[226:229], v[72:75]
	v_mfma_f32_16x16x32_bf16 v[68:71], v[242:245], v[226:229], v[68:71]
	v_readfirstlane_b32 s2, v162
	v_lshl_add_u64 v[132:133], v[246:247], 0, s[24:25]
	s_mov_b32 m0, s2
	v_readfirstlane_b32 s2, v163
	s_barrier
	ds_read_b128 v[198:201], v161 offset:16384
	ds_read_b128 v[202:205], v161 offset:17408
	ds_read_b128 v[206:209], v160 offset:16384
	ds_read_b128 v[210:213], v160 offset:17408
	ds_read_b128 v[214:217], v159 offset:16384
	ds_read_b128 v[218:221], v159 offset:17408
	ds_read_b128 v[222:225], v158 offset:16384
	ds_read_b128 v[226:229], v158 offset:17408
	global_load_lds_dwordx4 v[132:133], off
	v_lshl_add_u64 v[132:133], v[248:249], 0, s[24:25]
	s_mov_b32 m0, s2
	s_nop 0
	global_load_lds_dwordx4 v[132:133], off
	s_barrier
	s_waitcnt lgkmcnt(0)
	v_mfma_f32_16x16x32_bf16 v[64:67], v[182:185], v[198:201], v[64:67]
	v_mfma_f32_16x16x32_bf16 v[60:63], v[190:193], v[198:201], v[60:63]
	v_mfma_f32_16x16x32_bf16 v[56:59], v[182:185], v[206:209], v[56:59]
	v_mfma_f32_16x16x32_bf16 v[52:55], v[190:193], v[206:209], v[52:55]
	v_mfma_f32_16x16x32_bf16 v[48:51], v[182:185], v[214:217], v[48:51]
	v_mfma_f32_16x16x32_bf16 v[44:47], v[190:193], v[214:217], v[44:47]
	v_mfma_f32_16x16x32_bf16 v[40:43], v[182:185], v[222:225], v[40:43]
	v_mfma_f32_16x16x32_bf16 v[36:39], v[190:193], v[222:225], v[36:39]
	v_mfma_f32_16x16x32_bf16 v[64:67], v[186:189], v[202:205], v[64:67]
	v_mfma_f32_16x16x32_bf16 v[60:63], v[194:197], v[202:205], v[60:63]
	v_mfma_f32_16x16x32_bf16 v[56:59], v[186:189], v[210:213], v[56:59]
	v_mfma_f32_16x16x32_bf16 v[52:55], v[194:197], v[210:213], v[52:55]
	v_mfma_f32_16x16x32_bf16 v[48:51], v[186:189], v[218:221], v[48:51]
	v_mfma_f32_16x16x32_bf16 v[44:47], v[194:197], v[218:221], v[44:47]
	v_mfma_f32_16x16x32_bf16 v[40:43], v[186:189], v[226:229], v[40:43]
	v_mfma_f32_16x16x32_bf16 v[36:39], v[194:197], v[226:229], v[36:39]
	s_barrier
	v_readfirstlane_b32 s2, v168
	v_add_u32_e32 v3, 0x2000, v168
	v_lshl_add_u64 v[132:133], v[250:251], 0, s[26:27]
	s_mov_b32 m0, s2
	v_readfirstlane_b32 s2, v3
	global_load_lds_dwordx4 v[132:133], off
	v_lshl_add_u64 v[132:133], v[252:253], 0, s[26:27]
	s_mov_b32 m0, s2
	s_nop 0
	global_load_lds_dwordx4 v[132:133], off
	s_waitcnt vmcnt(6)
	s_barrier
	v_mfma_f32_16x16x32_bf16 v[32:35], v[230:233], v[198:201], v[32:35]
	v_mfma_f32_16x16x32_bf16 v[28:31], v[238:241], v[198:201], v[28:31]
	v_mfma_f32_16x16x32_bf16 v[24:27], v[230:233], v[206:209], v[24:27]
	v_mfma_f32_16x16x32_bf16 v[20:23], v[238:241], v[206:209], v[20:23]
	v_mfma_f32_16x16x32_bf16 v[16:19], v[230:233], v[214:217], v[16:19]
	v_mfma_f32_16x16x32_bf16 v[12:15], v[238:241], v[214:217], v[12:15]
	v_mfma_f32_16x16x32_bf16 v[8:11], v[230:233], v[222:225], v[8:11]
	v_mfma_f32_16x16x32_bf16 v[4:7], v[238:241], v[222:225], v[4:7]
	v_mfma_f32_16x16x32_bf16 v[32:35], v[234:237], v[202:205], v[32:35]
	v_mfma_f32_16x16x32_bf16 v[28:31], v[242:245], v[202:205], v[28:31]
	v_mfma_f32_16x16x32_bf16 v[24:27], v[234:237], v[210:213], v[24:27]
	v_mfma_f32_16x16x32_bf16 v[20:23], v[242:245], v[210:213], v[20:23]
	v_mfma_f32_16x16x32_bf16 v[16:19], v[234:237], v[218:221], v[16:19]
	v_mfma_f32_16x16x32_bf16 v[12:15], v[242:245], v[218:221], v[12:15]
	v_mfma_f32_16x16x32_bf16 v[8:11], v[234:237], v[226:229], v[8:11]
	v_mfma_f32_16x16x32_bf16 v[4:7], v[242:245], v[226:229], v[4:7]
	s_barrier
	ds_read_b128 v[182:185], v170
	ds_read_b128 v[186:189], v170 offset:1024
	ds_read_b128 v[190:193], v170 offset:2048
	ds_read_b128 v[194:197], v170 offset:3072
	v_readfirstlane_b32 s2, v169
	v_lshl_add_u64 v[132:133], v[246:247], 0, s[28:29]
	s_mov_b32 m0, s2
	v_readfirstlane_b32 s2, v171
	ds_read_b128 v[198:201], v161 offset:32768
	ds_read_b128 v[202:205], v161 offset:33792
	ds_read_b128 v[206:209], v160 offset:32768
	ds_read_b128 v[210:213], v160 offset:33792
	ds_read_b128 v[214:217], v159 offset:32768
	ds_read_b128 v[218:221], v159 offset:33792
	ds_read_b128 v[222:225], v158 offset:32768
	ds_read_b128 v[226:229], v158 offset:33792
	global_load_lds_dwordx4 v[132:133], off
	v_lshl_add_u64 v[132:133], v[248:249], 0, s[28:29]
	s_mov_b32 m0, s2
	s_nop 0
	global_load_lds_dwordx4 v[132:133], off
	s_barrier
	s_waitcnt lgkmcnt(0)
	v_mfma_f32_16x16x32_bf16 v[128:131], v[182:185], v[198:201], v[128:131]
	v_mfma_f32_16x16x32_bf16 v[124:127], v[190:193], v[198:201], v[124:127]
	v_mfma_f32_16x16x32_bf16 v[120:123], v[182:185], v[206:209], v[120:123]
	v_mfma_f32_16x16x32_bf16 v[116:119], v[190:193], v[206:209], v[116:119]
	v_mfma_f32_16x16x32_bf16 v[112:115], v[182:185], v[214:217], v[112:115]
	v_mfma_f32_16x16x32_bf16 v[108:111], v[190:193], v[214:217], v[108:111]
	v_mfma_f32_16x16x32_bf16 v[104:107], v[182:185], v[222:225], v[104:107]
	v_mfma_f32_16x16x32_bf16 v[100:103], v[190:193], v[222:225], v[100:103]
	v_mfma_f32_16x16x32_bf16 v[128:131], v[186:189], v[202:205], v[128:131]
	v_mfma_f32_16x16x32_bf16 v[124:127], v[194:197], v[202:205], v[124:127]
	v_mfma_f32_16x16x32_bf16 v[120:123], v[186:189], v[210:213], v[120:123]
	v_mfma_f32_16x16x32_bf16 v[116:119], v[194:197], v[210:213], v[116:119]
	v_mfma_f32_16x16x32_bf16 v[112:115], v[186:189], v[218:221], v[112:115]
	v_mfma_f32_16x16x32_bf16 v[108:111], v[194:197], v[218:221], v[108:111]
	v_mfma_f32_16x16x32_bf16 v[104:107], v[186:189], v[226:229], v[104:107]
	v_mfma_f32_16x16x32_bf16 v[100:103], v[194:197], v[226:229], v[100:103]
	s_barrier
	v_readfirstlane_b32 s2, v172
	v_lshl_add_u64 v[132:133], v[250:251], 0, s[30:31]
	s_mov_b32 m0, s2
	v_readfirstlane_b32 s2, v173
	ds_read_b128 v[230:233], v167
	ds_read_b128 v[234:237], v167 offset:1024
	ds_read_b128 v[238:241], v167 offset:2048
	ds_read_b128 v[242:245], v167 offset:3072
	global_load_lds_dwordx4 v[132:133], off
	v_lshl_add_u64 v[132:133], v[252:253], 0, s[30:31]
	s_mov_b32 m0, s2
	s_nop 0
	global_load_lds_dwordx4 v[132:133], off
	s_barrier
	s_waitcnt lgkmcnt(0)
	v_mfma_f32_16x16x32_bf16 v[96:99], v[230:233], v[198:201], v[96:99]
	v_mfma_f32_16x16x32_bf16 v[92:95], v[238:241], v[198:201], v[92:95]
	v_mfma_f32_16x16x32_bf16 v[88:91], v[230:233], v[206:209], v[88:91]
	v_mfma_f32_16x16x32_bf16 v[84:87], v[238:241], v[206:209], v[84:87]
	v_mfma_f32_16x16x32_bf16 v[80:83], v[230:233], v[214:217], v[80:83]
	v_mfma_f32_16x16x32_bf16 v[76:79], v[238:241], v[214:217], v[76:79]
	v_mfma_f32_16x16x32_bf16 v[72:75], v[230:233], v[222:225], v[72:75]
	v_mfma_f32_16x16x32_bf16 v[68:71], v[238:241], v[222:225], v[68:71]
	v_mfma_f32_16x16x32_bf16 v[96:99], v[234:237], v[202:205], v[96:99]
	v_mfma_f32_16x16x32_bf16 v[92:95], v[242:245], v[202:205], v[92:95]
	v_mfma_f32_16x16x32_bf16 v[88:91], v[234:237], v[210:213], v[88:91]
	v_mfma_f32_16x16x32_bf16 v[84:87], v[242:245], v[210:213], v[84:87]
	v_mfma_f32_16x16x32_bf16 v[80:83], v[234:237], v[218:221], v[80:83]
	v_mfma_f32_16x16x32_bf16 v[76:79], v[242:245], v[218:221], v[76:79]
	v_mfma_f32_16x16x32_bf16 v[72:75], v[234:237], v[226:229], v[72:75]
	v_mfma_f32_16x16x32_bf16 v[68:71], v[242:245], v[226:229], v[68:71]
	v_readfirstlane_b32 s2, v174
	v_lshl_add_u64 v[132:133], v[246:247], 0, s[34:35]
	s_mov_b32 m0, s2
	v_readfirstlane_b32 s2, v175
	s_barrier
	ds_read_b128 v[198:201], v161 offset:49152
	ds_read_b128 v[202:205], v161 offset:50176
	ds_read_b128 v[206:209], v160 offset:49152
	ds_read_b128 v[210:213], v160 offset:50176
	ds_read_b128 v[214:217], v159 offset:49152
	ds_read_b128 v[218:221], v159 offset:50176
	ds_read_b128 v[222:225], v158 offset:49152
	ds_read_b128 v[226:229], v158 offset:50176
	global_load_lds_dwordx4 v[132:133], off
	v_lshl_add_u64 v[132:133], v[248:249], 0, s[34:35]
	s_mov_b32 m0, s2
	s_nop 0
	global_load_lds_dwordx4 v[132:133], off
	s_barrier
	s_waitcnt lgkmcnt(0)
	v_mfma_f32_16x16x32_bf16 v[64:67], v[182:185], v[198:201], v[64:67]
	v_mfma_f32_16x16x32_bf16 v[60:63], v[190:193], v[198:201], v[60:63]
	v_mfma_f32_16x16x32_bf16 v[56:59], v[182:185], v[206:209], v[56:59]
	v_mfma_f32_16x16x32_bf16 v[52:55], v[190:193], v[206:209], v[52:55]
	v_mfma_f32_16x16x32_bf16 v[48:51], v[182:185], v[214:217], v[48:51]
	v_mfma_f32_16x16x32_bf16 v[44:47], v[190:193], v[214:217], v[44:47]
	v_mfma_f32_16x16x32_bf16 v[40:43], v[182:185], v[222:225], v[40:43]
	v_mfma_f32_16x16x32_bf16 v[36:39], v[190:193], v[222:225], v[36:39]
	v_mfma_f32_16x16x32_bf16 v[64:67], v[186:189], v[202:205], v[64:67]
	v_mfma_f32_16x16x32_bf16 v[60:63], v[194:197], v[202:205], v[60:63]
	v_mfma_f32_16x16x32_bf16 v[56:59], v[186:189], v[210:213], v[56:59]
	v_mfma_f32_16x16x32_bf16 v[52:55], v[194:197], v[210:213], v[52:55]
	v_mfma_f32_16x16x32_bf16 v[48:51], v[186:189], v[218:221], v[48:51]
	v_mfma_f32_16x16x32_bf16 v[44:47], v[194:197], v[218:221], v[44:47]
	v_mfma_f32_16x16x32_bf16 v[40:43], v[186:189], v[226:229], v[40:43]
	v_mfma_f32_16x16x32_bf16 v[36:39], v[194:197], v[226:229], v[36:39]
	s_barrier
	v_readfirstlane_b32 s2, v176
	v_lshl_add_u64 v[132:133], v[250:251], 0, s[36:37]
	s_mov_b32 m0, s2
	v_readfirstlane_b32 s2, v177
	global_load_lds_dwordx4 v[132:133], off
	v_lshl_add_u64 v[132:133], v[252:253], 0, s[36:37]
	s_mov_b32 m0, s2
	s_nop 0
	global_load_lds_dwordx4 v[132:133], off
	s_waitcnt vmcnt(6)
	s_barrier
	v_mfma_f32_16x16x32_bf16 v[32:35], v[230:233], v[198:201], v[32:35]
	v_mfma_f32_16x16x32_bf16 v[28:31], v[238:241], v[198:201], v[28:31]
	v_mfma_f32_16x16x32_bf16 v[24:27], v[230:233], v[206:209], v[24:27]
	v_mfma_f32_16x16x32_bf16 v[20:23], v[238:241], v[206:209], v[20:23]
	v_mfma_f32_16x16x32_bf16 v[16:19], v[230:233], v[214:217], v[16:19]
	v_mfma_f32_16x16x32_bf16 v[12:15], v[238:241], v[214:217], v[12:15]
	v_mfma_f32_16x16x32_bf16 v[8:11], v[230:233], v[222:225], v[8:11]
	v_mfma_f32_16x16x32_bf16 v[4:7], v[238:241], v[222:225], v[4:7]
	v_mfma_f32_16x16x32_bf16 v[32:35], v[234:237], v[202:205], v[32:35]
	v_mfma_f32_16x16x32_bf16 v[28:31], v[242:245], v[202:205], v[28:31]
	v_mfma_f32_16x16x32_bf16 v[24:27], v[234:237], v[210:213], v[24:27]
	v_mfma_f32_16x16x32_bf16 v[20:23], v[242:245], v[210:213], v[20:23]
	v_mfma_f32_16x16x32_bf16 v[16:19], v[234:237], v[218:221], v[16:19]
	v_mfma_f32_16x16x32_bf16 v[12:15], v[242:245], v[218:221], v[12:15]
	v_mfma_f32_16x16x32_bf16 v[8:11], v[234:237], v[226:229], v[8:11]
	v_mfma_f32_16x16x32_bf16 v[4:7], v[242:245], v[226:229], v[4:7]
	s_add_u32 s60, s60, 0x100
	s_addc_u32 s61, s61, 0
	s_cmp_gt_u32 s0, 11
	s_barrier
	s_cbranch_scc1 .LBB0_1532
	s_mov_b32 s0, s1
	s_cmp_lt_i32 s0, 12
	s_cbranch_scc1 .LBB0_1493

.LBB0_1661:
	ds_read_b128 v[180:183], v172
	ds_read_b128 v[184:187], v172 offset:1024
	ds_read_b128 v[188:191], v172 offset:2048
	ds_read_b128 v[192:195], v172 offset:3072
	v_add_u32_e32 v178, 0xc000, v152
	v_lshl_add_u64 v[244:245], s[8:9], 0, v[146:147]
	v_readfirstlane_b32 s1, v178
	v_add_u32_e32 v179, 0xe000, v152
	v_lshl_add_u64 v[224:225], v[244:245], 0, s[12:13]
	s_mov_b32 m0, s1
	v_lshl_add_u64 v[246:247], s[8:9], 0, v[148:149]
	v_readfirstlane_b32 s1, v179
	ds_read_b128 v[174:177], v161
	ds_read_b128 v[196:199], v161 offset:1024
	ds_read_b128 v[200:203], v160
	ds_read_b128 v[204:207], v160 offset:1024
	ds_read_b128 v[208:211], v159
	ds_read_b128 v[212:215], v159 offset:1024
	ds_read_b128 v[216:219], v158
	ds_read_b128 v[220:223], v158 offset:1024
	global_load_lds_dwordx4 v[224:225], off
	v_lshl_add_u64 v[224:225], v[246:247], 0, s[12:13]
	s_mov_b32 m0, s1
	s_nop 0
	global_load_lds_dwordx4 v[224:225], off
	s_barrier
	s_waitcnt lgkmcnt(0)
	v_mfma_f32_16x16x32_bf16 v[124:127], v[180:183], v[174:177], v[124:127]
	v_mfma_f32_16x16x32_bf16 v[120:123], v[188:191], v[174:177], v[120:123]
	v_mfma_f32_16x16x32_bf16 v[116:119], v[180:183], v[200:203], v[116:119]
	v_mfma_f32_16x16x32_bf16 v[112:115], v[188:191], v[200:203], v[112:115]
	v_mfma_f32_16x16x32_bf16 v[108:111], v[180:183], v[208:211], v[108:111]
	v_mfma_f32_16x16x32_bf16 v[104:107], v[188:191], v[208:211], v[104:107]
	v_mfma_f32_16x16x32_bf16 v[100:103], v[180:183], v[216:219], v[100:103]
	v_mfma_f32_16x16x32_bf16 v[96:99], v[188:191], v[216:219], v[96:99]
	v_mfma_f32_16x16x32_bf16 v[124:127], v[184:187], v[196:199], v[124:127]
	v_mfma_f32_16x16x32_bf16 v[120:123], v[192:195], v[196:199], v[120:123]
	v_mfma_f32_16x16x32_bf16 v[116:119], v[184:187], v[204:207], v[116:119]
	v_mfma_f32_16x16x32_bf16 v[112:115], v[192:195], v[204:207], v[112:115]
	v_mfma_f32_16x16x32_bf16 v[108:111], v[184:187], v[212:215], v[108:111]
	v_mfma_f32_16x16x32_bf16 v[104:107], v[192:195], v[212:215], v[104:107]
	v_mfma_f32_16x16x32_bf16 v[100:103], v[184:187], v[220:223], v[100:103]
	v_mfma_f32_16x16x32_bf16 v[96:99], v[192:195], v[220:223], v[96:99]
	s_barrier
	v_lshl_add_u64 v[248:249], s[8:9], 0, v[142:143]
	v_readfirstlane_b32 s1, v153
	v_add_u32_e32 v173, 0x2000, v153
	v_lshl_add_u64 v[240:241], v[248:249], 0, s[14:15]
	s_mov_b32 m0, s1
	v_lshl_add_u64 v[250:251], s[8:9], 0, v[144:145]
	v_readfirstlane_b32 s1, v173
	ds_read_b128 v[224:227], v168
	ds_read_b128 v[228:231], v168 offset:1024
	ds_read_b128 v[232:235], v168 offset:2048
	ds_read_b128 v[236:239], v168 offset:3072
	global_load_lds_dwordx4 v[240:241], off
	v_lshl_add_u64 v[240:241], v[250:251], 0, s[14:15]
	s_mov_b32 m0, s1
	s_nop 0
	global_load_lds_dwordx4 v[240:241], off
	s_barrier
	s_waitcnt lgkmcnt(0)
	v_mfma_f32_16x16x32_bf16 v[92:95], v[224:227], v[174:177], v[92:95]
	v_mfma_f32_16x16x32_bf16 v[88:91], v[232:235], v[174:177], v[88:91]
	v_mfma_f32_16x16x32_bf16 v[84:87], v[224:227], v[200:203], v[84:87]
	v_mfma_f32_16x16x32_bf16 v[80:83], v[232:235], v[200:203], v[80:83]
	v_mfma_f32_16x16x32_bf16 v[76:79], v[224:227], v[208:211], v[76:79]
	v_mfma_f32_16x16x32_bf16 v[72:75], v[232:235], v[208:211], v[72:75]
	v_mfma_f32_16x16x32_bf16 v[68:71], v[224:227], v[216:219], v[68:71]
	v_mfma_f32_16x16x32_bf16 v[64:67], v[232:235], v[216:219], v[64:67]
	v_mfma_f32_16x16x32_bf16 v[92:95], v[228:231], v[196:199], v[92:95]
	v_mfma_f32_16x16x32_bf16 v[88:91], v[236:239], v[196:199], v[88:91]
	v_mfma_f32_16x16x32_bf16 v[84:87], v[228:231], v[204:207], v[84:87]
	v_mfma_f32_16x16x32_bf16 v[80:83], v[236:239], v[204:207], v[80:83]
	v_mfma_f32_16x16x32_bf16 v[76:79], v[228:231], v[212:215], v[76:79]
	v_mfma_f32_16x16x32_bf16 v[72:75], v[236:239], v[212:215], v[72:75]
	v_mfma_f32_16x16x32_bf16 v[68:71], v[228:231], v[220:223], v[68:71]
	v_mfma_f32_16x16x32_bf16 v[64:67], v[236:239], v[220:223], v[64:67]
	v_readfirstlane_b32 s1, v152
	v_lshl_add_u64 v[174:175], v[244:245], 0, s[16:17]
	s_mov_b32 m0, s1
	s_barrier
	ds_read_b128 v[196:199], v161 offset:16384
	ds_read_b128 v[200:203], v161 offset:17408
	ds_read_b128 v[204:207], v160 offset:16384
	ds_read_b128 v[208:211], v160 offset:17408
	ds_read_b128 v[212:215], v159 offset:16384
	ds_read_b128 v[216:219], v159 offset:17408
	ds_read_b128 v[220:223], v158 offset:16384
	ds_read_b128 v[240:243], v158 offset:17408
	global_load_lds_dwordx4 v[174:175], off
	v_add_u32_e32 v174, 0x2000, v152
	v_lshl_add_u64 v[176:177], v[246:247], 0, s[16:17]
	v_readfirstlane_b32 s1, v174
	s_mov_b32 m0, s1
	s_nop 0
	global_load_lds_dwordx4 v[176:177], off
	s_barrier
	s_waitcnt lgkmcnt(0)
	v_mfma_f32_16x16x32_bf16 v[60:63], v[180:183], v[196:199], v[60:63]
	v_mfma_f32_16x16x32_bf16 v[56:59], v[188:191], v[196:199], v[56:59]
	v_mfma_f32_16x16x32_bf16 v[52:55], v[180:183], v[204:207], v[52:55]
	v_mfma_f32_16x16x32_bf16 v[48:51], v[188:191], v[204:207], v[48:51]
	v_mfma_f32_16x16x32_bf16 v[44:47], v[180:183], v[212:215], v[44:47]
	v_mfma_f32_16x16x32_bf16 v[40:43], v[188:191], v[212:215], v[40:43]
	v_mfma_f32_16x16x32_bf16 v[36:39], v[180:183], v[220:223], v[36:39]
	v_mfma_f32_16x16x32_bf16 v[32:35], v[188:191], v[220:223], v[32:35]
	v_mfma_f32_16x16x32_bf16 v[60:63], v[184:187], v[200:203], v[60:63]
	v_mfma_f32_16x16x32_bf16 v[56:59], v[192:195], v[200:203], v[56:59]
	v_mfma_f32_16x16x32_bf16 v[52:55], v[184:187], v[208:211], v[52:55]
	v_mfma_f32_16x16x32_bf16 v[48:51], v[192:195], v[208:211], v[48:51]
	v_mfma_f32_16x16x32_bf16 v[44:47], v[184:187], v[216:219], v[44:47]
	v_mfma_f32_16x16x32_bf16 v[40:43], v[192:195], v[216:219], v[40:43]
	v_mfma_f32_16x16x32_bf16 v[36:39], v[184:187], v[240:243], v[36:39]
	v_mfma_f32_16x16x32_bf16 v[32:35], v[192:195], v[240:243], v[32:35]
	s_barrier
	v_readfirstlane_b32 s1, v151
	v_add_u32_e32 v175, 0x2000, v151
	v_lshl_add_u64 v[176:177], v[248:249], 0, s[18:19]
	s_mov_b32 m0, s1
	v_readfirstlane_b32 s1, v175
	global_load_lds_dwordx4 v[176:177], off
	v_lshl_add_u64 v[176:177], v[250:251], 0, s[18:19]
	s_mov_b32 m0, s1
	s_nop 0
	global_load_lds_dwordx4 v[176:177], off
	s_waitcnt vmcnt(6)
	s_barrier
	v_mfma_f32_16x16x32_bf16 v[28:31], v[224:227], v[196:199], v[28:31]
	v_mfma_f32_16x16x32_bf16 v[24:27], v[232:235], v[196:199], v[24:27]
	v_mfma_f32_16x16x32_bf16 v[20:23], v[224:227], v[204:207], v[20:23]
	v_mfma_f32_16x16x32_bf16 v[16:19], v[232:235], v[204:207], v[16:19]
	v_mfma_f32_16x16x32_bf16 v[12:15], v[224:227], v[212:215], v[12:15]
	v_mfma_f32_16x16x32_bf16 v[8:11], v[232:235], v[212:215], v[8:11]
	v_mfma_f32_16x16x32_bf16 v[4:7], v[224:227], v[220:223], v[4:7]
	v_mfma_f32_16x16x32_bf16 v[0:3], v[232:235], v[220:223], v[0:3]
	v_mfma_f32_16x16x32_bf16 v[28:31], v[228:231], v[200:203], v[28:31]
	v_mfma_f32_16x16x32_bf16 v[24:27], v[236:239], v[200:203], v[24:27]
	v_mfma_f32_16x16x32_bf16 v[20:23], v[228:231], v[208:211], v[20:23]
	v_mfma_f32_16x16x32_bf16 v[16:19], v[236:239], v[208:211], v[16:19]
	v_mfma_f32_16x16x32_bf16 v[12:15], v[228:231], v[216:219], v[12:15]
	v_mfma_f32_16x16x32_bf16 v[8:11], v[236:239], v[216:219], v[8:11]
	v_mfma_f32_16x16x32_bf16 v[4:7], v[228:231], v[240:243], v[4:7]
	v_mfma_f32_16x16x32_bf16 v[0:3], v[236:239], v[240:243], v[0:3]
	s_barrier
	ds_read_b128 v[180:183], v163
	ds_read_b128 v[184:187], v163 offset:1024
	ds_read_b128 v[188:191], v163 offset:2048
	ds_read_b128 v[192:195], v163 offset:3072
	v_add_u32_e32 v176, 0x4000, v152
	v_add_u32_e32 v177, 0x6000, v152
	v_readfirstlane_b32 s1, v176
	v_lshl_add_u64 v[228:229], v[244:245], 0, s[20:21]
	s_mov_b32 m0, s1
	v_readfirstlane_b32 s1, v177
	ds_read_b128 v[196:199], v161 offset:32768
	ds_read_b128 v[200:203], v161 offset:33792
	ds_read_b128 v[204:207], v160 offset:32768
	ds_read_b128 v[208:211], v160 offset:33792
	ds_read_b128 v[212:215], v159 offset:32768
	ds_read_b128 v[216:219], v159 offset:33792
	ds_read_b128 v[220:223], v158 offset:32768
	ds_read_b128 v[224:227], v158 offset:33792
	global_load_lds_dwordx4 v[228:229], off
	v_lshl_add_u64 v[228:229], v[246:247], 0, s[20:21]
	s_mov_b32 m0, s1
	s_nop 0
	global_load_lds_dwordx4 v[228:229], off
	s_barrier
	s_waitcnt lgkmcnt(0)
	v_mfma_f32_16x16x32_bf16 v[124:127], v[180:183], v[196:199], v[124:127]
	v_mfma_f32_16x16x32_bf16 v[120:123], v[188:191], v[196:199], v[120:123]
	v_mfma_f32_16x16x32_bf16 v[116:119], v[180:183], v[204:207], v[116:119]
	v_mfma_f32_16x16x32_bf16 v[112:115], v[188:191], v[204:207], v[112:115]
	v_mfma_f32_16x16x32_bf16 v[108:111], v[180:183], v[212:215], v[108:111]
	v_mfma_f32_16x16x32_bf16 v[104:107], v[188:191], v[212:215], v[104:107]
	v_mfma_f32_16x16x32_bf16 v[100:103], v[180:183], v[220:223], v[100:103]
	v_mfma_f32_16x16x32_bf16 v[96:99], v[188:191], v[220:223], v[96:99]
	v_mfma_f32_16x16x32_bf16 v[124:127], v[184:187], v[200:203], v[124:127]
	v_mfma_f32_16x16x32_bf16 v[120:123], v[192:195], v[200:203], v[120:123]
	v_mfma_f32_16x16x32_bf16 v[116:119], v[184:187], v[208:211], v[116:119]
	v_mfma_f32_16x16x32_bf16 v[112:115], v[192:195], v[208:211], v[112:115]
	v_mfma_f32_16x16x32_bf16 v[108:111], v[184:187], v[216:219], v[108:111]
	v_mfma_f32_16x16x32_bf16 v[104:107], v[192:195], v[216:219], v[104:107]
	v_mfma_f32_16x16x32_bf16 v[100:103], v[184:187], v[224:227], v[100:103]
	v_mfma_f32_16x16x32_bf16 v[96:99], v[192:195], v[224:227], v[96:99]
	s_barrier
	v_readfirstlane_b32 s1, v167
	v_add_u32_e32 v254, 0x2000, v167
	v_lshl_add_u64 v[252:253], v[248:249], 0, s[24:25]
	s_mov_b32 m0, s1
	v_readfirstlane_b32 s1, v254
	ds_read_b128 v[228:231], v162
	ds_read_b128 v[232:235], v162 offset:1024
	ds_read_b128 v[236:239], v162 offset:2048
	ds_read_b128 v[240:243], v162 offset:3072
	global_load_lds_dwordx4 v[252:253], off
	v_lshl_add_u64 v[252:253], v[250:251], 0, s[24:25]
	s_mov_b32 m0, s1
	s_nop 0
	global_load_lds_dwordx4 v[252:253], off
	s_barrier
	s_waitcnt lgkmcnt(0)
	v_mfma_f32_16x16x32_bf16 v[92:95], v[228:231], v[196:199], v[92:95]
	v_mfma_f32_16x16x32_bf16 v[88:91], v[236:239], v[196:199], v[88:91]
	v_mfma_f32_16x16x32_bf16 v[84:87], v[228:231], v[204:207], v[84:87]
	v_mfma_f32_16x16x32_bf16 v[80:83], v[236:239], v[204:207], v[80:83]
	v_mfma_f32_16x16x32_bf16 v[76:79], v[228:231], v[212:215], v[76:79]
	v_mfma_f32_16x16x32_bf16 v[72:75], v[236:239], v[212:215], v[72:75]
	v_mfma_f32_16x16x32_bf16 v[68:71], v[228:231], v[220:223], v[68:71]
	v_mfma_f32_16x16x32_bf16 v[64:67], v[236:239], v[220:223], v[64:67]
	v_mfma_f32_16x16x32_bf16 v[92:95], v[232:235], v[200:203], v[92:95]
	v_mfma_f32_16x16x32_bf16 v[88:91], v[240:243], v[200:203], v[88:91]
	v_mfma_f32_16x16x32_bf16 v[84:87], v[232:235], v[208:211], v[84:87]
	v_mfma_f32_16x16x32_bf16 v[80:83], v[240:243], v[208:211], v[80:83]
	v_mfma_f32_16x16x32_bf16 v[76:79], v[232:235], v[216:219], v[76:79]
	v_mfma_f32_16x16x32_bf16 v[72:75], v[240:243], v[216:219], v[72:75]
	v_mfma_f32_16x16x32_bf16 v[68:71], v[232:235], v[224:227], v[68:71]
	v_mfma_f32_16x16x32_bf16 v[64:67], v[240:243], v[224:227], v[64:67]
	v_readfirstlane_b32 s1, v169
	v_lshl_add_u64 v[244:245], v[244:245], 0, s[26:27]
	s_mov_b32 m0, s1
	v_readfirstlane_b32 s1, v170
	s_barrier
	ds_read_b128 v[196:199], v161 offset:49152
	ds_read_b128 v[200:203], v161 offset:50176
	ds_read_b128 v[204:207], v160 offset:49152
	ds_read_b128 v[208:211], v160 offset:50176
	ds_read_b128 v[212:215], v159 offset:49152
	ds_read_b128 v[216:219], v159 offset:50176
	ds_read_b128 v[220:223], v158 offset:49152
	ds_read_b128 v[224:227], v158 offset:50176
	global_load_lds_dwordx4 v[244:245], off
	v_lshl_add_u64 v[244:245], v[246:247], 0, s[26:27]
	s_mov_b32 m0, s1
	s_nop 0
	global_load_lds_dwordx4 v[244:245], off
	s_barrier
	s_waitcnt lgkmcnt(0)
	v_mfma_f32_16x16x32_bf16 v[60:63], v[180:183], v[196:199], v[60:63]
	v_mfma_f32_16x16x32_bf16 v[56:59], v[188:191], v[196:199], v[56:59]
	v_mfma_f32_16x16x32_bf16 v[52:55], v[180:183], v[204:207], v[52:55]
	v_mfma_f32_16x16x32_bf16 v[48:51], v[188:191], v[204:207], v[48:51]
	v_mfma_f32_16x16x32_bf16 v[44:47], v[180:183], v[212:215], v[44:47]
	v_mfma_f32_16x16x32_bf16 v[40:43], v[188:191], v[212:215], v[40:43]
	v_mfma_f32_16x16x32_bf16 v[36:39], v[180:183], v[220:223], v[36:39]
	v_mfma_f32_16x16x32_bf16 v[32:35], v[188:191], v[220:223], v[32:35]
	v_mfma_f32_16x16x32_bf16 v[60:63], v[184:187], v[200:203], v[60:63]
	v_mfma_f32_16x16x32_bf16 v[56:59], v[192:195], v[200:203], v[56:59]
	v_mfma_f32_16x16x32_bf16 v[52:55], v[184:187], v[208:211], v[52:55]
	v_mfma_f32_16x16x32_bf16 v[48:51], v[192:195], v[208:211], v[48:51]
	v_mfma_f32_16x16x32_bf16 v[44:47], v[184:187], v[216:219], v[44:47]
	v_mfma_f32_16x16x32_bf16 v[40:43], v[192:195], v[216:219], v[40:43]
	v_mfma_f32_16x16x32_bf16 v[36:39], v[184:187], v[224:227], v[36:39]
	v_mfma_f32_16x16x32_bf16 v[32:35], v[192:195], v[224:227], v[32:35]
	s_barrier
	v_readfirstlane_b32 s1, v171
	v_add_u32_e32 v182, 0x2000, v171
	v_lshl_add_u64 v[180:181], v[248:249], 0, s[28:29]
	s_mov_b32 m0, s1
	v_readfirstlane_b32 s1, v182
	global_load_lds_dwordx4 v[180:181], off
	v_lshl_add_u64 v[180:181], v[250:251], 0, s[28:29]
	s_mov_b32 m0, s1
	s_nop 0
	global_load_lds_dwordx4 v[180:181], off
	s_waitcnt vmcnt(6)
	s_barrier
	v_mfma_f32_16x16x32_bf16 v[28:31], v[228:231], v[196:199], v[28:31]
	v_mfma_f32_16x16x32_bf16 v[24:27], v[236:239], v[196:199], v[24:27]
	v_mfma_f32_16x16x32_bf16 v[20:23], v[228:231], v[204:207], v[20:23]
	v_mfma_f32_16x16x32_bf16 v[16:19], v[236:239], v[204:207], v[16:19]
	v_mfma_f32_16x16x32_bf16 v[12:15], v[228:231], v[212:215], v[12:15]
	v_mfma_f32_16x16x32_bf16 v[8:11], v[236:239], v[212:215], v[8:11]
	v_mfma_f32_16x16x32_bf16 v[4:7], v[228:231], v[220:223], v[4:7]
	v_mfma_f32_16x16x32_bf16 v[0:3], v[236:239], v[220:223], v[0:3]
	v_mfma_f32_16x16x32_bf16 v[28:31], v[232:235], v[200:203], v[28:31]
	v_mfma_f32_16x16x32_bf16 v[24:27], v[240:243], v[200:203], v[24:27]
	v_mfma_f32_16x16x32_bf16 v[20:23], v[232:235], v[208:211], v[20:23]
	v_mfma_f32_16x16x32_bf16 v[16:19], v[240:243], v[208:211], v[16:19]
	v_mfma_f32_16x16x32_bf16 v[12:15], v[232:235], v[216:219], v[12:15]
	v_mfma_f32_16x16x32_bf16 v[8:11], v[240:243], v[216:219], v[8:11]
	v_mfma_f32_16x16x32_bf16 v[4:7], v[232:235], v[224:227], v[4:7]
	v_mfma_f32_16x16x32_bf16 v[0:3], v[240:243], v[224:227], v[0:3]
	s_add_i32 s0, s0, 2
	v_lshl_add_u64 v[142:143], v[142:143], 0, s[30:31]
	v_lshl_add_u64 v[144:145], v[144:145], 0, s[30:31]
	v_lshl_add_u64 v[146:147], v[146:147], 0, s[30:31]
	s_cmp_lt_u32 s0, 12
	v_lshl_add_u64 v[148:149], v[148:149], 0, s[30:31]
	s_barrier
	s_cbranch_scc1 .LBB0_1661
	s_or_b32 s0, s36, 0x80
	s_ashr_i32 s1, s0, 31
	s_lshl_b64 s[0:1], s[0:1], 11
	s_add_u32 s0, s39, s0
	s_addc_u32 s1, s46, s1
	v_lshl_add_u64 v[170:171], s[0:1], 0, v[130:131]
	v_lshl_add_u64 v[138:139], v[138:139], 1, v[170:171]
	v_readfirstlane_b32 s2, v178
	v_lshl_add_u64 v[138:139], v[138:139], 0, s[34:35]
	s_mov_b32 m0, s2
	ds_read_b128 v[142:145], v172
	ds_read_b128 v[146:149], v172 offset:1024
	ds_read_b128 v[180:183], v172 offset:2048
	ds_read_b128 v[184:187], v172 offset:3072
	ds_read_b128 v[188:191], v161
	ds_read_b128 v[192:195], v161 offset:1024
	ds_read_b128 v[196:199], v160
	ds_read_b128 v[200:203], v160 offset:1024
	ds_read_b128 v[204:207], v159
	ds_read_b128 v[208:211], v159 offset:1024
	ds_read_b128 v[212:215], v158
	ds_read_b128 v[216:219], v158 offset:1024
	global_load_lds_dwordx4 v[138:139], off
	v_lshl_add_u64 v[138:139], s[0:1], 0, v[134:135]
	v_lshl_add_u64 v[138:139], v[140:141], 1, v[138:139]
	v_readfirstlane_b32 s0, v179
	v_lshl_add_u64 v[138:139], v[138:139], 0, s[34:35]
	s_mov_b32 m0, s0
	v_readlane_b32 s0, v255, 11
	global_load_lds_dwordx4 v[138:139], off
	s_add_i32 s70, s70, s0
	s_barrier
	s_waitcnt lgkmcnt(0)
	s_cmpk_gt_i32 s70, 0x7f
	s_cselect_b64 s[58:59], -1, 0
	s_waitcnt lgkmcnt(0)
	v_mfma_f32_16x16x32_bf16 v[124:127], v[142:145], v[188:191], v[124:127]
	v_mfma_f32_16x16x32_bf16 v[120:123], v[180:183], v[188:191], v[120:123]
	v_mfma_f32_16x16x32_bf16 v[116:119], v[142:145], v[196:199], v[116:119]
	v_mfma_f32_16x16x32_bf16 v[112:115], v[180:183], v[196:199], v[112:115]
	v_mfma_f32_16x16x32_bf16 v[108:111], v[142:145], v[204:207], v[108:111]
	v_mfma_f32_16x16x32_bf16 v[104:107], v[180:183], v[204:207], v[104:107]
	v_mfma_f32_16x16x32_bf16 v[100:103], v[142:145], v[212:215], v[100:103]
	v_mfma_f32_16x16x32_bf16 v[96:99], v[180:183], v[212:215], v[96:99]
	v_mfma_f32_16x16x32_bf16 v[124:127], v[146:149], v[192:195], v[124:127]
	v_mfma_f32_16x16x32_bf16 v[120:123], v[184:187], v[192:195], v[120:123]
	v_mfma_f32_16x16x32_bf16 v[116:119], v[146:149], v[200:203], v[116:119]
	v_mfma_f32_16x16x32_bf16 v[112:115], v[184:187], v[200:203], v[112:115]
	v_mfma_f32_16x16x32_bf16 v[108:111], v[146:149], v[208:211], v[108:111]
	v_mfma_f32_16x16x32_bf16 v[104:107], v[184:187], v[208:211], v[104:107]
	v_mfma_f32_16x16x32_bf16 v[100:103], v[146:149], v[216:219], v[100:103]
	v_mfma_f32_16x16x32_bf16 v[96:99], v[184:187], v[216:219], v[96:99]
	s_barrier
	ds_read_b128 v[138:141], v168
	ds_read_b128 v[220:223], v168 offset:1024
	ds_read_b128 v[224:227], v168 offset:2048
	ds_read_b128 v[168:171], v168 offset:3072
	s_barrier
	s_waitcnt lgkmcnt(0)
	v_mfma_f32_16x16x32_bf16 v[92:95], v[138:141], v[188:191], v[92:95]
	v_mfma_f32_16x16x32_bf16 v[88:91], v[224:227], v[188:191], v[88:91]
	v_mfma_f32_16x16x32_bf16 v[84:87], v[138:141], v[196:199], v[84:87]
	v_mfma_f32_16x16x32_bf16 v[80:83], v[224:227], v[196:199], v[80:83]
	v_mfma_f32_16x16x32_bf16 v[76:79], v[138:141], v[204:207], v[76:79]
	v_mfma_f32_16x16x32_bf16 v[72:75], v[224:227], v[204:207], v[72:75]
	v_mfma_f32_16x16x32_bf16 v[68:71], v[138:141], v[212:215], v[68:71]
	v_mfma_f32_16x16x32_bf16 v[64:67], v[224:227], v[212:215], v[64:67]
	v_mfma_f32_16x16x32_bf16 v[92:95], v[220:223], v[192:195], v[92:95]
	v_mfma_f32_16x16x32_bf16 v[88:91], v[168:171], v[192:195], v[88:91]
	v_mfma_f32_16x16x32_bf16 v[84:87], v[220:223], v[200:203], v[84:87]
	v_mfma_f32_16x16x32_bf16 v[80:83], v[168:171], v[200:203], v[80:83]
	v_mfma_f32_16x16x32_bf16 v[76:79], v[220:223], v[208:211], v[76:79]
	v_mfma_f32_16x16x32_bf16 v[72:75], v[168:171], v[208:211], v[72:75]
	v_mfma_f32_16x16x32_bf16 v[68:71], v[220:223], v[216:219], v[68:71]
	v_mfma_f32_16x16x32_bf16 v[64:67], v[168:171], v[216:219], v[64:67]
	s_barrier
	ds_read_b128 v[188:191], v161 offset:16384
	ds_read_b128 v[192:195], v161 offset:17408
	ds_read_b128 v[196:199], v160 offset:16384
	ds_read_b128 v[200:203], v160 offset:17408
	ds_read_b128 v[204:207], v159 offset:16384
	ds_read_b128 v[208:211], v159 offset:17408
	ds_read_b128 v[212:215], v158 offset:16384
	ds_read_b128 v[216:219], v158 offset:17408
	s_waitcnt vmcnt(4)
	s_barrier
	s_waitcnt lgkmcnt(0)
	v_mfma_f32_16x16x32_bf16 v[60:63], v[142:145], v[188:191], v[60:63]
	v_mfma_f32_16x16x32_bf16 v[56:59], v[180:183], v[188:191], v[56:59]
	v_mfma_f32_16x16x32_bf16 v[52:55], v[142:145], v[196:199], v[52:55]
	v_mfma_f32_16x16x32_bf16 v[48:51], v[180:183], v[196:199], v[48:51]
	v_mfma_f32_16x16x32_bf16 v[44:47], v[142:145], v[204:207], v[44:47]
	v_mfma_f32_16x16x32_bf16 v[40:43], v[180:183], v[204:207], v[40:43]
	v_mfma_f32_16x16x32_bf16 v[36:39], v[142:145], v[212:215], v[36:39]
	v_mfma_f32_16x16x32_bf16 v[32:35], v[180:183], v[212:215], v[32:35]
	v_mfma_f32_16x16x32_bf16 v[60:63], v[146:149], v[192:195], v[60:63]
	v_mfma_f32_16x16x32_bf16 v[56:59], v[184:187], v[192:195], v[56:59]
	v_mfma_f32_16x16x32_bf16 v[52:55], v[146:149], v[200:203], v[52:55]
	v_mfma_f32_16x16x32_bf16 v[48:51], v[184:187], v[200:203], v[48:51]
	v_mfma_f32_16x16x32_bf16 v[44:47], v[146:149], v[208:211], v[44:47]
	v_mfma_f32_16x16x32_bf16 v[40:43], v[184:187], v[208:211], v[40:43]
	v_mfma_f32_16x16x32_bf16 v[36:39], v[146:149], v[216:219], v[36:39]
	v_mfma_f32_16x16x32_bf16 v[32:35], v[184:187], v[216:219], v[32:35]
	v_mfma_f32_16x16x32_bf16 v[28:31], v[138:141], v[188:191], v[28:31]
	v_mfma_f32_16x16x32_bf16 v[24:27], v[224:227], v[188:191], v[24:27]
	v_mfma_f32_16x16x32_bf16 v[20:23], v[138:141], v[196:199], v[20:23]
	v_mfma_f32_16x16x32_bf16 v[16:19], v[224:227], v[196:199], v[16:19]
	v_mfma_f32_16x16x32_bf16 v[12:15], v[138:141], v[204:207], v[12:15]
	v_mfma_f32_16x16x32_bf16 v[8:11], v[224:227], v[204:207], v[8:11]
	v_mfma_f32_16x16x32_bf16 v[4:7], v[138:141], v[212:215], v[4:7]
	v_mfma_f32_16x16x32_bf16 v[0:3], v[224:227], v[212:215], v[0:3]
	v_mfma_f32_16x16x32_bf16 v[28:31], v[220:223], v[192:195], v[28:31]
	v_mfma_f32_16x16x32_bf16 v[24:27], v[168:171], v[192:195], v[24:27]
	v_mfma_f32_16x16x32_bf16 v[20:23], v[220:223], v[200:203], v[20:23]
	v_mfma_f32_16x16x32_bf16 v[16:19], v[168:171], v[200:203], v[16:19]
	v_mfma_f32_16x16x32_bf16 v[12:15], v[220:223], v[208:211], v[12:15]
	v_mfma_f32_16x16x32_bf16 v[8:11], v[168:171], v[208:211], v[8:11]
	v_mfma_f32_16x16x32_bf16 v[4:7], v[220:223], v[216:219], v[4:7]
	v_mfma_f32_16x16x32_bf16 v[0:3], v[168:171], v[216:219], v[0:3]
	s_barrier
	ds_read_b128 v[138:141], v163
	ds_read_b128 v[142:145], v163 offset:1024
	ds_read_b128 v[146:149], v163 offset:2048
	ds_read_b128 v[168:171], v163 offset:3072
	ds_read_b128 v[178:181], v161 offset:32768
	ds_read_b128 v[182:185], v161 offset:33792
	ds_read_b128 v[186:189], v160 offset:32768
	ds_read_b128 v[190:193], v160 offset:33792
	ds_read_b128 v[194:197], v159 offset:32768
	ds_read_b128 v[198:201], v159 offset:33792
	ds_read_b128 v[202:205], v158 offset:32768
	ds_read_b128 v[206:209], v158 offset:33792
	s_waitcnt vmcnt(2)
	s_barrier
	s_waitcnt lgkmcnt(0)
	v_mfma_f32_16x16x32_bf16 v[124:127], v[138:141], v[178:181], v[124:127]
	v_mfma_f32_16x16x32_bf16 v[120:123], v[146:149], v[178:181], v[120:123]
	v_mfma_f32_16x16x32_bf16 v[116:119], v[138:141], v[186:189], v[116:119]
	v_mfma_f32_16x16x32_bf16 v[112:115], v[146:149], v[186:189], v[112:115]
	v_mfma_f32_16x16x32_bf16 v[108:111], v[138:141], v[194:197], v[108:111]
	v_mfma_f32_16x16x32_bf16 v[104:107], v[146:149], v[194:197], v[104:107]
	v_mfma_f32_16x16x32_bf16 v[100:103], v[138:141], v[202:205], v[100:103]
	v_mfma_f32_16x16x32_bf16 v[96:99], v[146:149], v[202:205], v[96:99]
	v_mfma_f32_16x16x32_bf16 v[124:127], v[142:145], v[182:185], v[124:127]
	v_mfma_f32_16x16x32_bf16 v[120:123], v[168:171], v[182:185], v[120:123]
	v_mfma_f32_16x16x32_bf16 v[116:119], v[142:145], v[190:193], v[116:119]
	v_mfma_f32_16x16x32_bf16 v[112:115], v[168:171], v[190:193], v[112:115]
	v_mfma_f32_16x16x32_bf16 v[108:111], v[142:145], v[198:201], v[108:111]
	v_mfma_f32_16x16x32_bf16 v[104:107], v[168:171], v[198:201], v[104:107]
	v_mfma_f32_16x16x32_bf16 v[100:103], v[142:145], v[206:209], v[100:103]
	v_mfma_f32_16x16x32_bf16 v[96:99], v[168:171], v[206:209], v[96:99]
	s_barrier
	ds_read_b128 v[210:213], v162
	ds_read_b128 v[214:217], v162 offset:1024
	ds_read_b128 v[218:221], v162 offset:2048
	ds_read_b128 v[222:225], v162 offset:3072
	s_waitcnt vmcnt(0)
	s_barrier
	s_waitcnt lgkmcnt(0)
	v_mfma_f32_16x16x32_bf16 v[92:95], v[210:213], v[178:181], v[92:95]
	v_mfma_f32_16x16x32_bf16 v[88:91], v[218:221], v[178:181], v[88:91]
	v_mfma_f32_16x16x32_bf16 v[84:87], v[210:213], v[186:189], v[84:87]
	v_mfma_f32_16x16x32_bf16 v[80:83], v[218:221], v[186:189], v[80:83]
	v_mfma_f32_16x16x32_bf16 v[76:79], v[210:213], v[194:197], v[76:79]
	v_mfma_f32_16x16x32_bf16 v[72:75], v[218:221], v[194:197], v[72:75]
	v_mfma_f32_16x16x32_bf16 v[68:71], v[210:213], v[202:205], v[68:71]
	v_mfma_f32_16x16x32_bf16 v[64:67], v[218:221], v[202:205], v[64:67]
	v_mfma_f32_16x16x32_bf16 v[92:95], v[214:217], v[182:185], v[92:95]
	v_mfma_f32_16x16x32_bf16 v[88:91], v[222:225], v[182:185], v[88:91]
	v_mfma_f32_16x16x32_bf16 v[84:87], v[214:217], v[190:193], v[84:87]
	v_mfma_f32_16x16x32_bf16 v[80:83], v[222:225], v[190:193], v[80:83]
	v_mfma_f32_16x16x32_bf16 v[76:79], v[214:217], v[198:201], v[76:79]
	v_mfma_f32_16x16x32_bf16 v[72:75], v[222:225], v[198:201], v[72:75]
	v_mfma_f32_16x16x32_bf16 v[68:71], v[214:217], v[206:209], v[68:71]
	v_mfma_f32_16x16x32_bf16 v[64:67], v[222:225], v[206:209], v[64:67]
	s_barrier
	ds_read_b128 v[178:181], v161 offset:49152
	ds_read_b128 v[182:185], v161 offset:50176
	ds_read_b128 v[186:189], v160 offset:49152
	ds_read_b128 v[160:163], v160 offset:50176
	ds_read_b128 v[190:193], v159 offset:49152
	ds_read_b128 v[194:197], v159 offset:50176
	ds_read_b128 v[198:201], v158 offset:49152
	ds_read_b128 v[202:205], v158 offset:50176
	s_barrier
	s_waitcnt lgkmcnt(0)
	v_mfma_f32_16x16x32_bf16 v[60:63], v[138:141], v[178:181], v[60:63]
	v_mfma_f32_16x16x32_bf16 v[56:59], v[146:149], v[178:181], v[56:59]
	v_mfma_f32_16x16x32_bf16 v[52:55], v[138:141], v[186:189], v[52:55]
	v_mfma_f32_16x16x32_bf16 v[48:51], v[146:149], v[186:189], v[48:51]
	v_mfma_f32_16x16x32_bf16 v[44:47], v[138:141], v[190:193], v[44:47]
	v_mfma_f32_16x16x32_bf16 v[40:43], v[146:149], v[190:193], v[40:43]
	v_mfma_f32_16x16x32_bf16 v[36:39], v[138:141], v[198:201], v[36:39]
	v_mfma_f32_16x16x32_bf16 v[32:35], v[146:149], v[198:201], v[32:35]
	v_mfma_f32_16x16x32_bf16 v[60:63], v[142:145], v[182:185], v[60:63]
	v_mfma_f32_16x16x32_bf16 v[56:59], v[168:171], v[182:185], v[56:59]
	v_mfma_f32_16x16x32_bf16 v[52:55], v[142:145], v[160:163], v[52:55]
	v_mfma_f32_16x16x32_bf16 v[48:51], v[168:171], v[160:163], v[48:51]
	v_mfma_f32_16x16x32_bf16 v[44:47], v[142:145], v[194:197], v[44:47]
	v_mfma_f32_16x16x32_bf16 v[40:43], v[168:171], v[194:197], v[40:43]
	v_mfma_f32_16x16x32_bf16 v[36:39], v[142:145], v[202:205], v[36:39]
	v_mfma_f32_16x16x32_bf16 v[32:35], v[168:171], v[202:205], v[32:35]
	v_mfma_f32_16x16x32_bf16 v[28:31], v[210:213], v[178:181], v[28:31]
	v_mfma_f32_16x16x32_bf16 v[24:27], v[218:221], v[178:181], v[24:27]
	v_mfma_f32_16x16x32_bf16 v[20:23], v[210:213], v[186:189], v[20:23]
	v_mfma_f32_16x16x32_bf16 v[16:19], v[218:221], v[186:189], v[16:19]
	v_mfma_f32_16x16x32_bf16 v[12:15], v[210:213], v[190:193], v[12:15]
	v_mfma_f32_16x16x32_bf16 v[8:11], v[218:221], v[190:193], v[8:11]
	v_mfma_f32_16x16x32_bf16 v[4:7], v[210:213], v[198:201], v[4:7]
	v_mfma_f32_16x16x32_bf16 v[0:3], v[218:221], v[198:201], v[0:3]
	v_mfma_f32_16x16x32_bf16 v[28:31], v[214:217], v[182:185], v[28:31]
	v_mfma_f32_16x16x32_bf16 v[24:27], v[222:225], v[182:185], v[24:27]
	v_mfma_f32_16x16x32_bf16 v[20:23], v[214:217], v[160:163], v[20:23]
	v_mfma_f32_16x16x32_bf16 v[16:19], v[222:225], v[160:163], v[16:19]
	v_mfma_f32_16x16x32_bf16 v[12:15], v[214:217], v[194:197], v[12:15]
	v_mfma_f32_16x16x32_bf16 v[8:11], v[222:225], v[194:197], v[8:11]
	v_mfma_f32_16x16x32_bf16 v[4:7], v[214:217], v[202:205], v[4:7]
	v_mfma_f32_16x16x32_bf16 v[0:3], v[222:225], v[202:205], v[0:3]
	s_and_b64 vcc, exec, s[58:59]
	s_barrier
	s_cbranch_vccnz .LBB0_1664
	s_lshr_b32 s0, s70, 2
	s_and_b32 s1, s70, 3
	s_add_i32 s0, s0, s56
	s_or_b32 s1, s1, s53
	s_lshl_b32 s0, s0, 8
	s_lshl_b32 s1, s1, 19
	s_add_u32 s40, s57, s1
	s_addc_u32 s41, s62, 0
	v_lshl_add_u64 v[138:139], s[40:41], 0, v[130:131]
	v_readfirstlane_b32 s1, v153
	v_lshl_add_u64 v[138:139], v[138:139], 0, v[132:133]
	s_mov_b32 m0, s1
	v_readfirstlane_b32 s1, v173
	global_load_lds_dwordx4 v[138:139], off
	s_mov_b32 m0, s1
	s_ashr_i32 s1, s0, 31
	s_lshl_b64 s[42:43], s[0:1], 11
	v_lshl_add_u64 v[138:139], s[40:41], 0, v[134:135]
	s_add_u32 s42, s39, s42
	v_lshl_add_u64 v[138:139], v[138:139], 0, v[136:137]
	s_addc_u32 s43, s46, s43
	global_load_lds_dwordx4 v[138:139], off
	v_lshl_add_u64 v[138:139], s[42:43], 0, v[130:131]
	v_readfirstlane_b32 s1, v152
	v_lshl_add_u64 v[138:139], v[138:139], 0, v[132:133]
	s_mov_b32 m0, s1
	v_readfirstlane_b32 s1, v174
	global_load_lds_dwordx4 v[138:139], off
	v_lshl_add_u64 v[138:139], s[42:43], 0, v[134:135]
	s_add_u32 s40, s40, 0x40000
	v_lshl_add_u64 v[138:139], v[138:139], 0, v[136:137]
	s_mov_b32 m0, s1
	s_addc_u32 s41, s41, 0
	global_load_lds_dwordx4 v[138:139], off
	v_lshl_add_u64 v[138:139], s[40:41], 0, v[130:131]
	v_readfirstlane_b32 s1, v151
	v_lshl_add_u64 v[138:139], v[138:139], 0, v[132:133]
	s_mov_b32 m0, s1
	v_readfirstlane_b32 s1, v175
	s_bitset1_b32 s0, 7
	global_load_lds_dwordx4 v[138:139], off
	s_mov_b32 m0, s1
	s_ashr_i32 s1, s0, 31
	s_lshl_b64 s[0:1], s[0:1], 11
	s_add_u32 s0, s39, s0
	v_lshl_add_u64 v[138:139], s[40:41], 0, v[134:135]
	s_addc_u32 s1, s46, s1
	v_lshl_add_u64 v[138:139], v[138:139], 0, v[136:137]
	v_lshl_add_u64 v[130:131], s[0:1], 0, v[130:131]
	v_readfirstlane_b32 s2, v176
	global_load_lds_dwordx4 v[138:139], off
	v_lshl_add_u64 v[130:131], v[130:131], 0, v[132:133]
	s_mov_b32 m0, s2
	s_nop 0
	global_load_lds_dwordx4 v[130:131], off
	v_lshl_add_u64 v[130:131], s[0:1], 0, v[134:135]
	v_readfirstlane_b32 s0, v177
	v_lshl_add_u64 v[130:131], v[130:131], 0, v[136:137]
	s_mov_b32 m0, s0
	s_nop 0
	global_load_lds_dwordx4 v[130:131], off

.LBB0_1720:
	ds_read_b128 v[176:179], v173
	ds_read_b128 v[180:183], v173 offset:1024
	ds_read_b128 v[184:187], v173 offset:2048
	ds_read_b128 v[188:191], v173 offset:3072
	v_add_u32_e32 v174, 0xc000, v157
	v_lshl_add_u64 v[240:241], s[6:7], 0, v[142:143]
	v_readfirstlane_b32 s2, v174
	v_add_u32_e32 v175, 0xe000, v157
	v_lshl_add_u64 v[224:225], v[240:241], 0, s[14:15]
	s_mov_b32 m0, s2
	v_lshl_add_u64 v[242:243], s[6:7], 0, v[144:145]
	v_readfirstlane_b32 s2, v175
	ds_read_b128 v[192:195], v155
	ds_read_b128 v[196:199], v155 offset:1024
	ds_read_b128 v[200:203], v154
	ds_read_b128 v[204:207], v154 offset:1024
	ds_read_b128 v[208:211], v153
	ds_read_b128 v[212:215], v153 offset:1024
	ds_read_b128 v[216:219], v152
	ds_read_b128 v[220:223], v152 offset:1024
	global_load_lds_dwordx4 v[224:225], off
	v_lshl_add_u64 v[224:225], v[242:243], 0, s[14:15]
	s_mov_b32 m0, s2
	s_nop 0
	global_load_lds_dwordx4 v[224:225], off
	s_barrier
	s_waitcnt lgkmcnt(0)
	v_mfma_f32_16x16x32_bf16 v[124:127], v[176:179], v[192:195], v[124:127]
	v_mfma_f32_16x16x32_bf16 v[120:123], v[184:187], v[192:195], v[120:123]
	v_mfma_f32_16x16x32_bf16 v[116:119], v[176:179], v[200:203], v[116:119]
	v_mfma_f32_16x16x32_bf16 v[112:115], v[184:187], v[200:203], v[112:115]
	v_mfma_f32_16x16x32_bf16 v[108:111], v[176:179], v[208:211], v[108:111]
	v_mfma_f32_16x16x32_bf16 v[104:107], v[184:187], v[208:211], v[104:107]
	v_mfma_f32_16x16x32_bf16 v[100:103], v[176:179], v[216:219], v[100:103]
	v_mfma_f32_16x16x32_bf16 v[96:99], v[184:187], v[216:219], v[96:99]
	v_mfma_f32_16x16x32_bf16 v[124:127], v[180:183], v[196:199], v[124:127]
	v_mfma_f32_16x16x32_bf16 v[120:123], v[188:191], v[196:199], v[120:123]
	v_mfma_f32_16x16x32_bf16 v[116:119], v[180:183], v[204:207], v[116:119]
	v_mfma_f32_16x16x32_bf16 v[112:115], v[188:191], v[204:207], v[112:115]
	v_mfma_f32_16x16x32_bf16 v[108:111], v[180:183], v[212:215], v[108:111]
	v_mfma_f32_16x16x32_bf16 v[104:107], v[188:191], v[212:215], v[104:107]
	v_mfma_f32_16x16x32_bf16 v[100:103], v[180:183], v[220:223], v[100:103]
	v_mfma_f32_16x16x32_bf16 v[96:99], v[188:191], v[220:223], v[96:99]
	s_barrier
	v_lshl_add_u64 v[244:245], s[6:7], 0, v[138:139]
	v_readfirstlane_b32 s2, v151
	v_lshl_add_u64 v[246:247], v[244:245], 0, s[16:17]
	s_mov_b32 m0, s2
	v_add_u32_e32 v250, 0x2000, v151
	ds_read_b128 v[224:227], v170
	ds_read_b128 v[228:231], v170 offset:1024
	ds_read_b128 v[232:235], v170 offset:2048
	ds_read_b128 v[236:239], v170 offset:3072
	global_load_lds_dwordx4 v[246:247], off
	v_lshl_add_u64 v[246:247], s[6:7], 0, v[140:141]
	v_readfirstlane_b32 s2, v250
	v_lshl_add_u64 v[248:249], v[246:247], 0, s[16:17]
	s_mov_b32 m0, s2
	s_nop 0
	global_load_lds_dwordx4 v[248:249], off
	s_barrier
	s_waitcnt lgkmcnt(0)
	v_mfma_f32_16x16x32_bf16 v[92:95], v[224:227], v[192:195], v[92:95]
	v_mfma_f32_16x16x32_bf16 v[88:91], v[232:235], v[192:195], v[88:91]
	v_mfma_f32_16x16x32_bf16 v[84:87], v[224:227], v[200:203], v[84:87]
	v_mfma_f32_16x16x32_bf16 v[80:83], v[232:235], v[200:203], v[80:83]
	v_mfma_f32_16x16x32_bf16 v[76:79], v[224:227], v[208:211], v[76:79]
	v_mfma_f32_16x16x32_bf16 v[72:75], v[232:235], v[208:211], v[72:75]
	v_mfma_f32_16x16x32_bf16 v[68:71], v[224:227], v[216:219], v[68:71]
	v_mfma_f32_16x16x32_bf16 v[64:67], v[232:235], v[216:219], v[64:67]
	v_mfma_f32_16x16x32_bf16 v[92:95], v[228:231], v[196:199], v[92:95]
	v_mfma_f32_16x16x32_bf16 v[88:91], v[236:239], v[196:199], v[88:91]
	v_mfma_f32_16x16x32_bf16 v[84:87], v[228:231], v[204:207], v[84:87]
	v_mfma_f32_16x16x32_bf16 v[80:83], v[236:239], v[204:207], v[80:83]
	v_mfma_f32_16x16x32_bf16 v[76:79], v[228:231], v[212:215], v[76:79]
	v_mfma_f32_16x16x32_bf16 v[72:75], v[236:239], v[212:215], v[72:75]
	v_mfma_f32_16x16x32_bf16 v[68:71], v[228:231], v[220:223], v[68:71]
	v_mfma_f32_16x16x32_bf16 v[64:67], v[236:239], v[220:223], v[64:67]
	v_readfirstlane_b32 s2, v157
	v_lshl_add_u64 v[248:249], v[240:241], 0, s[18:19]
	s_mov_b32 m0, s2
	v_readfirstlane_b32 s2, v158
	s_barrier
	ds_read_b128 v[192:195], v155 offset:16384
	ds_read_b128 v[196:199], v155 offset:17408
	ds_read_b128 v[200:203], v154 offset:16384
	ds_read_b128 v[204:207], v154 offset:17408
	ds_read_b128 v[208:211], v153 offset:16384
	ds_read_b128 v[212:215], v153 offset:17408
	ds_read_b128 v[216:219], v152 offset:16384
	ds_read_b128 v[220:223], v152 offset:17408
	global_load_lds_dwordx4 v[248:249], off
	v_lshl_add_u64 v[248:249], v[242:243], 0, s[18:19]
	s_mov_b32 m0, s2
	s_nop 0
	global_load_lds_dwordx4 v[248:249], off
	s_barrier
	s_waitcnt lgkmcnt(0)
	v_mfma_f32_16x16x32_bf16 v[60:63], v[176:179], v[192:195], v[60:63]
	v_mfma_f32_16x16x32_bf16 v[56:59], v[184:187], v[192:195], v[56:59]
	v_mfma_f32_16x16x32_bf16 v[52:55], v[176:179], v[200:203], v[52:55]
	v_mfma_f32_16x16x32_bf16 v[48:51], v[184:187], v[200:203], v[48:51]
	v_mfma_f32_16x16x32_bf16 v[44:47], v[176:179], v[208:211], v[44:47]
	v_mfma_f32_16x16x32_bf16 v[40:43], v[184:187], v[208:211], v[40:43]
	v_mfma_f32_16x16x32_bf16 v[36:39], v[176:179], v[216:219], v[36:39]
	v_mfma_f32_16x16x32_bf16 v[32:35], v[184:187], v[216:219], v[32:35]
	v_mfma_f32_16x16x32_bf16 v[60:63], v[180:183], v[196:199], v[60:63]
	v_mfma_f32_16x16x32_bf16 v[56:59], v[188:191], v[196:199], v[56:59]
	v_mfma_f32_16x16x32_bf16 v[52:55], v[180:183], v[204:207], v[52:55]
	v_mfma_f32_16x16x32_bf16 v[48:51], v[188:191], v[204:207], v[48:51]
	v_mfma_f32_16x16x32_bf16 v[44:47], v[180:183], v[212:215], v[44:47]
	v_mfma_f32_16x16x32_bf16 v[40:43], v[188:191], v[212:215], v[40:43]
	v_mfma_f32_16x16x32_bf16 v[36:39], v[180:183], v[220:223], v[36:39]
	v_mfma_f32_16x16x32_bf16 v[32:35], v[188:191], v[220:223], v[32:35]
	s_barrier
	v_readfirstlane_b32 s2, v159
	v_add_u32_e32 v178, 0x2000, v159
	v_lshl_add_u64 v[176:177], v[244:245], 0, s[20:21]
	s_mov_b32 m0, s2
	v_readfirstlane_b32 s2, v178
	global_load_lds_dwordx4 v[176:177], off
	v_lshl_add_u64 v[176:177], v[246:247], 0, s[20:21]
	s_mov_b32 m0, s2
	s_nop 0
	global_load_lds_dwordx4 v[176:177], off
	s_waitcnt vmcnt(6)
	s_barrier
	v_mfma_f32_16x16x32_bf16 v[28:31], v[224:227], v[192:195], v[28:31]
	v_mfma_f32_16x16x32_bf16 v[24:27], v[232:235], v[192:195], v[24:27]
	v_mfma_f32_16x16x32_bf16 v[20:23], v[224:227], v[200:203], v[20:23]
	v_mfma_f32_16x16x32_bf16 v[16:19], v[232:235], v[200:203], v[16:19]
	v_mfma_f32_16x16x32_bf16 v[12:15], v[224:227], v[208:211], v[12:15]
	v_mfma_f32_16x16x32_bf16 v[8:11], v[232:235], v[208:211], v[8:11]
	v_mfma_f32_16x16x32_bf16 v[4:7], v[224:227], v[216:219], v[4:7]
	v_mfma_f32_16x16x32_bf16 v[0:3], v[232:235], v[216:219], v[0:3]
	v_mfma_f32_16x16x32_bf16 v[28:31], v[228:231], v[196:199], v[28:31]
	v_mfma_f32_16x16x32_bf16 v[24:27], v[236:239], v[196:199], v[24:27]
	v_mfma_f32_16x16x32_bf16 v[20:23], v[228:231], v[204:207], v[20:23]
	v_mfma_f32_16x16x32_bf16 v[16:19], v[236:239], v[204:207], v[16:19]
	v_mfma_f32_16x16x32_bf16 v[12:15], v[228:231], v[212:215], v[12:15]
	v_mfma_f32_16x16x32_bf16 v[8:11], v[236:239], v[212:215], v[8:11]
	v_mfma_f32_16x16x32_bf16 v[4:7], v[228:231], v[220:223], v[4:7]
	v_mfma_f32_16x16x32_bf16 v[0:3], v[236:239], v[220:223], v[0:3]
	s_barrier
	ds_read_b128 v[176:179], v160
	ds_read_b128 v[180:183], v160 offset:1024
	ds_read_b128 v[184:187], v160 offset:2048
	ds_read_b128 v[188:191], v160 offset:3072
	v_readfirstlane_b32 s2, v161
	v_lshl_add_u64 v[224:225], v[240:241], 0, s[24:25]
	s_mov_b32 m0, s2
	v_readfirstlane_b32 s2, v162
	ds_read_b128 v[192:195], v155 offset:32768
	ds_read_b128 v[196:199], v155 offset:33792
	ds_read_b128 v[200:203], v154 offset:32768
	ds_read_b128 v[204:207], v154 offset:33792
	ds_read_b128 v[208:211], v153 offset:32768
	ds_read_b128 v[212:215], v153 offset:33792
	ds_read_b128 v[216:219], v152 offset:32768
	ds_read_b128 v[220:223], v152 offset:33792
	global_load_lds_dwordx4 v[224:225], off
	v_lshl_add_u64 v[224:225], v[242:243], 0, s[24:25]
	s_mov_b32 m0, s2
	s_nop 0
	global_load_lds_dwordx4 v[224:225], off
	s_barrier
	s_waitcnt lgkmcnt(0)
	v_mfma_f32_16x16x32_bf16 v[124:127], v[176:179], v[192:195], v[124:127]
	v_mfma_f32_16x16x32_bf16 v[120:123], v[184:187], v[192:195], v[120:123]
	v_mfma_f32_16x16x32_bf16 v[116:119], v[176:179], v[200:203], v[116:119]
	v_mfma_f32_16x16x32_bf16 v[112:115], v[184:187], v[200:203], v[112:115]
	v_mfma_f32_16x16x32_bf16 v[108:111], v[176:179], v[208:211], v[108:111]
	v_mfma_f32_16x16x32_bf16 v[104:107], v[184:187], v[208:211], v[104:107]
	v_mfma_f32_16x16x32_bf16 v[100:103], v[176:179], v[216:219], v[100:103]
	v_mfma_f32_16x16x32_bf16 v[96:99], v[184:187], v[216:219], v[96:99]
	v_mfma_f32_16x16x32_bf16 v[124:127], v[180:183], v[196:199], v[124:127]
	v_mfma_f32_16x16x32_bf16 v[120:123], v[188:191], v[196:199], v[120:123]
	v_mfma_f32_16x16x32_bf16 v[116:119], v[180:183], v[204:207], v[116:119]
	v_mfma_f32_16x16x32_bf16 v[112:115], v[188:191], v[204:207], v[112:115]
	v_mfma_f32_16x16x32_bf16 v[108:111], v[180:183], v[212:215], v[108:111]
	v_mfma_f32_16x16x32_bf16 v[104:107], v[188:191], v[212:215], v[104:107]
	v_mfma_f32_16x16x32_bf16 v[100:103], v[180:183], v[220:223], v[100:103]
	v_mfma_f32_16x16x32_bf16 v[96:99], v[188:191], v[220:223], v[96:99]
	s_barrier
	v_readfirstlane_b32 s2, v163
	v_lshl_add_u64 v[248:249], v[244:245], 0, s[26:27]
	s_mov_b32 m0, s2
	v_readfirstlane_b32 s2, v167
	ds_read_b128 v[224:227], v156
	ds_read_b128 v[228:231], v156 offset:1024
	ds_read_b128 v[232:235], v156 offset:2048
	ds_read_b128 v[236:239], v156 offset:3072
	global_load_lds_dwordx4 v[248:249], off
	v_lshl_add_u64 v[248:249], v[246:247], 0, s[26:27]
	s_mov_b32 m0, s2
	s_nop 0
	global_load_lds_dwordx4 v[248:249], off
	s_barrier
	s_waitcnt lgkmcnt(0)
	v_mfma_f32_16x16x32_bf16 v[92:95], v[224:227], v[192:195], v[92:95]
	v_mfma_f32_16x16x32_bf16 v[88:91], v[232:235], v[192:195], v[88:91]
	v_mfma_f32_16x16x32_bf16 v[84:87], v[224:227], v[200:203], v[84:87]
	v_mfma_f32_16x16x32_bf16 v[80:83], v[232:235], v[200:203], v[80:83]
	v_mfma_f32_16x16x32_bf16 v[76:79], v[224:227], v[208:211], v[76:79]
	v_mfma_f32_16x16x32_bf16 v[72:75], v[232:235], v[208:211], v[72:75]
	v_mfma_f32_16x16x32_bf16 v[68:71], v[224:227], v[216:219], v[68:71]
	v_mfma_f32_16x16x32_bf16 v[64:67], v[232:235], v[216:219], v[64:67]
	v_mfma_f32_16x16x32_bf16 v[92:95], v[228:231], v[196:199], v[92:95]
	v_mfma_f32_16x16x32_bf16 v[88:91], v[236:239], v[196:199], v[88:91]
	v_mfma_f32_16x16x32_bf16 v[84:87], v[228:231], v[204:207], v[84:87]
	v_mfma_f32_16x16x32_bf16 v[80:83], v[236:239], v[204:207], v[80:83]
	v_mfma_f32_16x16x32_bf16 v[76:79], v[228:231], v[212:215], v[76:79]
	v_mfma_f32_16x16x32_bf16 v[72:75], v[236:239], v[212:215], v[72:75]
	v_mfma_f32_16x16x32_bf16 v[68:71], v[228:231], v[220:223], v[68:71]
	v_mfma_f32_16x16x32_bf16 v[64:67], v[236:239], v[220:223], v[64:67]
	v_readfirstlane_b32 s2, v168
	v_lshl_add_u64 v[240:241], v[240:241], 0, s[28:29]
	s_mov_b32 m0, s2
	v_readfirstlane_b32 s2, v169
	s_barrier
	ds_read_b128 v[192:195], v155 offset:49152
	ds_read_b128 v[196:199], v155 offset:50176
	ds_read_b128 v[200:203], v154 offset:49152
	ds_read_b128 v[204:207], v154 offset:50176
	ds_read_b128 v[208:211], v153 offset:49152
	ds_read_b128 v[212:215], v153 offset:50176
	ds_read_b128 v[216:219], v152 offset:49152
	ds_read_b128 v[220:223], v152 offset:50176
	global_load_lds_dwordx4 v[240:241], off
	v_lshl_add_u64 v[240:241], v[242:243], 0, s[28:29]
	s_mov_b32 m0, s2
	s_nop 0
	global_load_lds_dwordx4 v[240:241], off
	s_barrier
	s_waitcnt lgkmcnt(0)
	v_mfma_f32_16x16x32_bf16 v[60:63], v[176:179], v[192:195], v[60:63]
	v_mfma_f32_16x16x32_bf16 v[56:59], v[184:187], v[192:195], v[56:59]
	v_mfma_f32_16x16x32_bf16 v[52:55], v[176:179], v[200:203], v[52:55]
	v_mfma_f32_16x16x32_bf16 v[48:51], v[184:187], v[200:203], v[48:51]
	v_mfma_f32_16x16x32_bf16 v[44:47], v[176:179], v[208:211], v[44:47]
	v_mfma_f32_16x16x32_bf16 v[40:43], v[184:187], v[208:211], v[40:43]
	v_mfma_f32_16x16x32_bf16 v[36:39], v[176:179], v[216:219], v[36:39]
	v_mfma_f32_16x16x32_bf16 v[32:35], v[184:187], v[216:219], v[32:35]
	v_mfma_f32_16x16x32_bf16 v[60:63], v[180:183], v[196:199], v[60:63]
	v_mfma_f32_16x16x32_bf16 v[56:59], v[188:191], v[196:199], v[56:59]
	v_mfma_f32_16x16x32_bf16 v[52:55], v[180:183], v[204:207], v[52:55]
	v_mfma_f32_16x16x32_bf16 v[48:51], v[188:191], v[204:207], v[48:51]
	v_mfma_f32_16x16x32_bf16 v[44:47], v[180:183], v[212:215], v[44:47]
	v_mfma_f32_16x16x32_bf16 v[40:43], v[188:191], v[212:215], v[40:43]
	v_mfma_f32_16x16x32_bf16 v[36:39], v[180:183], v[220:223], v[36:39]
	v_mfma_f32_16x16x32_bf16 v[32:35], v[188:191], v[220:223], v[32:35]
	s_barrier
	v_readfirstlane_b32 s2, v171
	v_lshl_add_u64 v[176:177], v[244:245], 0, s[30:31]
	s_mov_b32 m0, s2
	v_readfirstlane_b32 s2, v172
	global_load_lds_dwordx4 v[176:177], off
	v_lshl_add_u64 v[176:177], v[246:247], 0, s[30:31]
	s_mov_b32 m0, s2
	s_nop 0
	global_load_lds_dwordx4 v[176:177], off
	s_waitcnt vmcnt(6)
	s_barrier
	v_mfma_f32_16x16x32_bf16 v[28:31], v[224:227], v[192:195], v[28:31]
	v_mfma_f32_16x16x32_bf16 v[24:27], v[232:235], v[192:195], v[24:27]
	v_mfma_f32_16x16x32_bf16 v[20:23], v[224:227], v[200:203], v[20:23]
	v_mfma_f32_16x16x32_bf16 v[16:19], v[232:235], v[200:203], v[16:19]
	v_mfma_f32_16x16x32_bf16 v[12:15], v[224:227], v[208:211], v[12:15]
	v_mfma_f32_16x16x32_bf16 v[8:11], v[232:235], v[208:211], v[8:11]
	v_mfma_f32_16x16x32_bf16 v[4:7], v[224:227], v[216:219], v[4:7]
	v_mfma_f32_16x16x32_bf16 v[0:3], v[232:235], v[216:219], v[0:3]
	v_mfma_f32_16x16x32_bf16 v[28:31], v[228:231], v[196:199], v[28:31]
	v_mfma_f32_16x16x32_bf16 v[24:27], v[236:239], v[196:199], v[24:27]
	v_mfma_f32_16x16x32_bf16 v[20:23], v[228:231], v[204:207], v[20:23]
	v_mfma_f32_16x16x32_bf16 v[16:19], v[236:239], v[204:207], v[16:19]
	v_mfma_f32_16x16x32_bf16 v[12:15], v[228:231], v[212:215], v[12:15]
	v_mfma_f32_16x16x32_bf16 v[8:11], v[236:239], v[212:215], v[8:11]
	v_mfma_f32_16x16x32_bf16 v[4:7], v[228:231], v[220:223], v[4:7]
	v_mfma_f32_16x16x32_bf16 v[0:3], v[236:239], v[220:223], v[0:3]
	s_add_i32 s1, s1, 2
	v_lshl_add_u64 v[138:139], v[138:139], 0, s[34:35]
	v_lshl_add_u64 v[140:141], v[140:141], 0, s[34:35]
	v_lshl_add_u64 v[142:143], v[142:143], 0, s[34:35]
	s_cmp_lt_u32 s1, 60
	v_lshl_add_u64 v[144:145], v[144:145], 0, s[34:35]
	s_barrier
	s_cbranch_scc1 .LBB0_1720
	s_add_u32 s4, s38, 0x1f80
	s_addc_u32 s5, s39, 0
	v_lshl_add_u64 v[132:133], s[4:5], 0, v[132:133]
	v_readfirstlane_b32 s1, v174
	v_lshl_add_u64 v[130:131], v[130:131], 1, v[132:133]
	s_mov_b32 m0, s1
	ds_read_b128 v[138:141], v173
	ds_read_b128 v[142:145], v173 offset:1024
	ds_read_b128 v[176:179], v173 offset:2048
	ds_read_b128 v[180:183], v173 offset:3072
	ds_read_b128 v[184:187], v155
	ds_read_b128 v[188:191], v155 offset:1024
	ds_read_b128 v[192:195], v154
	ds_read_b128 v[196:199], v154 offset:1024
	ds_read_b128 v[200:203], v153
	ds_read_b128 v[204:207], v153 offset:1024
	ds_read_b128 v[208:211], v152
	ds_read_b128 v[212:215], v152 offset:1024
	global_load_lds_dwordx4 v[130:131], off
	v_lshl_add_u64 v[130:131], s[4:5], 0, v[136:137]
	v_readfirstlane_b32 s1, v175
	v_lshl_add_u64 v[130:131], v[134:135], 1, v[130:131]
	s_mov_b32 m0, s1
	s_nop 0
	global_load_lds_dwordx4 v[130:131], off
	s_barrier
	s_waitcnt lgkmcnt(0)
	v_mfma_f32_16x16x32_bf16 v[124:127], v[138:141], v[184:187], v[124:127]
	v_mfma_f32_16x16x32_bf16 v[116:119], v[138:141], v[192:195], v[116:119]
	v_mfma_f32_16x16x32_bf16 v[108:111], v[138:141], v[200:203], v[108:111]
	v_mfma_f32_16x16x32_bf16 v[100:103], v[138:141], v[208:211], v[100:103]
	v_mfma_f32_16x16x32_bf16 v[124:127], v[142:145], v[188:191], v[124:127]
	v_mfma_f32_16x16x32_bf16 v[120:123], v[176:179], v[184:187], v[120:123]
	v_mfma_f32_16x16x32_bf16 v[116:119], v[142:145], v[196:199], v[116:119]
	v_mfma_f32_16x16x32_bf16 v[112:115], v[176:179], v[192:195], v[112:115]
	v_mfma_f32_16x16x32_bf16 v[108:111], v[142:145], v[204:207], v[108:111]
	v_mfma_f32_16x16x32_bf16 v[104:107], v[176:179], v[200:203], v[104:107]
	v_mfma_f32_16x16x32_bf16 v[100:103], v[142:145], v[212:215], v[100:103]
	v_mfma_f32_16x16x32_bf16 v[96:99], v[176:179], v[208:211], v[96:99]
	v_mfma_f32_16x16x32_bf16 v[130:133], v[180:183], v[188:191], v[120:123]
	v_mfma_f32_16x16x32_bf16 v[134:137], v[180:183], v[196:199], v[112:115]
	v_mfma_f32_16x16x32_bf16 v[172:175], v[180:183], v[204:207], v[104:107]
	v_mfma_f32_16x16x32_bf16 v[216:219], v[180:183], v[212:215], v[96:99]
	s_barrier
	s_nop 1
	ds_read_b128 v[96:99], v170
	ds_read_b128 v[104:107], v170 offset:1024
	ds_read_b128 v[112:115], v170 offset:2048
	ds_read_b128 v[120:123], v170 offset:3072
	s_barrier
	s_waitcnt lgkmcnt(0)
	v_mfma_f32_16x16x32_bf16 v[92:95], v[96:99], v[184:187], v[92:95]
	v_mfma_f32_16x16x32_bf16 v[84:87], v[96:99], v[192:195], v[84:87]
	v_mfma_f32_16x16x32_bf16 v[76:79], v[96:99], v[200:203], v[76:79]
	v_mfma_f32_16x16x32_bf16 v[68:71], v[96:99], v[208:211], v[68:71]
	v_mfma_f32_16x16x32_bf16 v[92:95], v[104:107], v[188:191], v[92:95]
	v_mfma_f32_16x16x32_bf16 v[88:91], v[112:115], v[184:187], v[88:91]
	v_mfma_f32_16x16x32_bf16 v[84:87], v[104:107], v[196:199], v[84:87]
	v_mfma_f32_16x16x32_bf16 v[80:83], v[112:115], v[192:195], v[80:83]
	v_mfma_f32_16x16x32_bf16 v[76:79], v[104:107], v[204:207], v[76:79]
	v_mfma_f32_16x16x32_bf16 v[72:75], v[112:115], v[200:203], v[72:75]
	v_mfma_f32_16x16x32_bf16 v[68:71], v[104:107], v[212:215], v[68:71]
	v_mfma_f32_16x16x32_bf16 v[64:67], v[112:115], v[208:211], v[64:67]
	v_mfma_f32_16x16x32_bf16 v[168:171], v[120:123], v[188:191], v[88:91]
	v_mfma_f32_16x16x32_bf16 v[184:187], v[120:123], v[196:199], v[80:83]
	v_mfma_f32_16x16x32_bf16 v[188:191], v[120:123], v[204:207], v[72:75]
	v_mfma_f32_16x16x32_bf16 v[192:195], v[120:123], v[212:215], v[64:67]
	s_barrier
	s_nop 1
	ds_read_b128 v[64:67], v155 offset:16384
	ds_read_b128 v[72:75], v155 offset:17408
	ds_read_b128 v[80:83], v154 offset:16384
	ds_read_b128 v[88:91], v154 offset:17408
	ds_read_b128 v[196:199], v153 offset:16384
	ds_read_b128 v[200:203], v153 offset:17408
	ds_read_b128 v[204:207], v152 offset:16384
	ds_read_b128 v[208:211], v152 offset:17408
	s_waitcnt vmcnt(4)
	s_barrier
	s_waitcnt lgkmcnt(0)
	v_mfma_f32_16x16x32_bf16 v[60:63], v[138:141], v[64:67], v[60:63]
	v_mfma_f32_16x16x32_bf16 v[52:55], v[138:141], v[80:83], v[52:55]
	v_mfma_f32_16x16x32_bf16 v[44:47], v[138:141], v[196:199], v[44:47]
	v_mfma_f32_16x16x32_bf16 v[36:39], v[138:141], v[204:207], v[36:39]
	v_mfma_f32_16x16x32_bf16 v[60:63], v[142:145], v[72:75], v[60:63]
	v_mfma_f32_16x16x32_bf16 v[56:59], v[176:179], v[64:67], v[56:59]
	v_mfma_f32_16x16x32_bf16 v[52:55], v[142:145], v[88:91], v[52:55]
	v_mfma_f32_16x16x32_bf16 v[48:51], v[176:179], v[80:83], v[48:51]
	v_mfma_f32_16x16x32_bf16 v[44:47], v[142:145], v[200:203], v[44:47]
	v_mfma_f32_16x16x32_bf16 v[40:43], v[176:179], v[196:199], v[40:43]
	v_mfma_f32_16x16x32_bf16 v[36:39], v[142:145], v[208:211], v[36:39]
	v_mfma_f32_16x16x32_bf16 v[32:35], v[176:179], v[204:207], v[32:35]
	v_mfma_f32_16x16x32_bf16 v[212:215], v[180:183], v[72:75], v[56:59]
	v_mfma_f32_16x16x32_bf16 v[220:223], v[180:183], v[88:91], v[48:51]
	v_mfma_f32_16x16x32_bf16 v[224:227], v[180:183], v[200:203], v[40:43]
	v_mfma_f32_16x16x32_bf16 v[138:141], v[180:183], v[208:211], v[32:35]
	v_mfma_f32_16x16x32_bf16 v[28:31], v[96:99], v[64:67], v[28:31]
	v_mfma_f32_16x16x32_bf16 v[20:23], v[96:99], v[80:83], v[20:23]
	v_mfma_f32_16x16x32_bf16 v[12:15], v[96:99], v[196:199], v[12:15]
	v_mfma_f32_16x16x32_bf16 v[4:7], v[96:99], v[204:207], v[4:7]
	v_mfma_f32_16x16x32_bf16 v[28:31], v[104:107], v[72:75], v[28:31]
	v_mfma_f32_16x16x32_bf16 v[24:27], v[112:115], v[64:67], v[24:27]
	v_mfma_f32_16x16x32_bf16 v[20:23], v[104:107], v[88:91], v[20:23]
	v_mfma_f32_16x16x32_bf16 v[16:19], v[112:115], v[80:83], v[16:19]
	v_mfma_f32_16x16x32_bf16 v[12:15], v[104:107], v[200:203], v[12:15]
	v_mfma_f32_16x16x32_bf16 v[8:11], v[112:115], v[196:199], v[8:11]
	v_mfma_f32_16x16x32_bf16 v[4:7], v[104:107], v[208:211], v[4:7]
	v_mfma_f32_16x16x32_bf16 v[0:3], v[112:115], v[204:207], v[0:3]
	v_mfma_f32_16x16x32_bf16 v[142:145], v[120:123], v[72:75], v[24:27]
	v_mfma_f32_16x16x32_bf16 v[176:179], v[120:123], v[88:91], v[16:19]
	v_mfma_f32_16x16x32_bf16 v[180:183], v[120:123], v[200:203], v[8:11]
	v_mfma_f32_16x16x32_bf16 v[196:199], v[120:123], v[208:211], v[0:3]
	s_barrier
	s_nop 1
	ds_read_b128 v[0:3], v160
	ds_read_b128 v[8:11], v160 offset:1024
	ds_read_b128 v[16:19], v160 offset:2048
	ds_read_b128 v[24:27], v160 offset:3072
	ds_read_b128 v[32:35], v155 offset:32768
	ds_read_b128 v[40:43], v155 offset:33792
	ds_read_b128 v[48:51], v154 offset:32768
	ds_read_b128 v[56:59], v154 offset:33792
	ds_read_b128 v[64:67], v153 offset:32768
	ds_read_b128 v[158:161], v153 offset:33792
	ds_read_b128 v[200:203], v152 offset:32768
	ds_read_b128 v[204:207], v152 offset:33792
	s_waitcnt vmcnt(2)
	s_barrier
	s_waitcnt lgkmcnt(0)
	v_mfma_f32_16x16x32_bf16 v[72:75], v[0:3], v[32:35], v[124:127]
	v_mfma_f32_16x16x32_bf16 v[120:123], v[8:11], v[40:43], v[72:75]
	v_mfma_f32_16x16x32_bf16 v[72:75], v[16:19], v[32:35], v[130:133]
	v_mfma_f32_16x16x32_bf16 v[124:127], v[24:27], v[40:43], v[72:75]
	v_mfma_f32_16x16x32_bf16 v[72:75], v[0:3], v[48:51], v[116:119]
	v_mfma_f32_16x16x32_bf16 v[112:115], v[8:11], v[56:59], v[72:75]
	v_mfma_f32_16x16x32_bf16 v[72:75], v[16:19], v[48:51], v[134:137]
	v_mfma_f32_16x16x32_bf16 v[116:119], v[24:27], v[56:59], v[72:75]
	v_mfma_f32_16x16x32_bf16 v[72:75], v[0:3], v[64:67], v[108:111]
	v_mfma_f32_16x16x32_bf16 v[104:107], v[8:11], v[158:161], v[72:75]
	v_mfma_f32_16x16x32_bf16 v[72:75], v[16:19], v[64:67], v[172:175]
	v_mfma_f32_16x16x32_bf16 v[108:111], v[24:27], v[158:161], v[72:75]
	v_mfma_f32_16x16x32_bf16 v[72:75], v[0:3], v[200:203], v[100:103]
	v_mfma_f32_16x16x32_bf16 v[96:99], v[8:11], v[204:207], v[72:75]
	v_mfma_f32_16x16x32_bf16 v[72:75], v[16:19], v[200:203], v[216:219]
	v_mfma_f32_16x16x32_bf16 v[100:103], v[24:27], v[204:207], v[72:75]
	s_barrier
	ds_read_b128 v[130:133], v156
	ds_read_b128 v[134:137], v156 offset:1024
	ds_read_b128 v[172:175], v156 offset:2048
	ds_read_b128 v[208:211], v156 offset:3072
	s_waitcnt vmcnt(0)
	s_barrier
	s_waitcnt lgkmcnt(0)
	v_mfma_f32_16x16x32_bf16 v[72:75], v[130:133], v[32:35], v[92:95]
	v_mfma_f32_16x16x32_bf16 v[32:35], v[172:175], v[32:35], v[168:171]
	v_mfma_f32_16x16x32_bf16 v[92:95], v[208:211], v[40:43], v[32:35]
	v_mfma_f32_16x16x32_bf16 v[32:35], v[130:133], v[48:51], v[84:87]
	v_mfma_f32_16x16x32_bf16 v[80:83], v[134:137], v[56:59], v[32:35]
	v_mfma_f32_16x16x32_bf16 v[32:35], v[172:175], v[48:51], v[184:187]
	v_mfma_f32_16x16x32_bf16 v[84:87], v[208:211], v[56:59], v[32:35]
	v_mfma_f32_16x16x32_bf16 v[32:35], v[130:133], v[64:67], v[76:79]
	v_mfma_f32_16x16x32_bf16 v[88:91], v[134:137], v[40:43], v[72:75]
	v_mfma_f32_16x16x32_bf16 v[72:75], v[134:137], v[158:161], v[32:35]
	v_mfma_f32_16x16x32_bf16 v[32:35], v[172:175], v[64:67], v[188:191]
	v_mfma_f32_16x16x32_bf16 v[76:79], v[208:211], v[158:161], v[32:35]
	v_mfma_f32_16x16x32_bf16 v[32:35], v[130:133], v[200:203], v[68:71]
	v_mfma_f32_16x16x32_bf16 v[64:67], v[134:137], v[204:207], v[32:35]
	v_mfma_f32_16x16x32_bf16 v[32:35], v[172:175], v[200:203], v[192:195]
	v_mfma_f32_16x16x32_bf16 v[68:71], v[208:211], v[204:207], v[32:35]
	s_barrier
	ds_read_b128 v[156:159], v155 offset:49152
	ds_read_b128 v[160:163], v155 offset:50176
	ds_read_b128 v[168:171], v154 offset:49152
	ds_read_b128 v[184:187], v154 offset:50176
	ds_read_b128 v[188:191], v153 offset:49152
	ds_read_b128 v[192:195], v153 offset:50176
	ds_read_b128 v[200:203], v152 offset:49152
	ds_read_b128 v[152:155], v152 offset:50176
	s_barrier
	s_waitcnt lgkmcnt(0)
	v_mfma_f32_16x16x32_bf16 v[32:35], v[0:3], v[156:159], v[60:63]
	v_mfma_f32_16x16x32_bf16 v[56:59], v[8:11], v[160:163], v[32:35]
	v_mfma_f32_16x16x32_bf16 v[32:35], v[16:19], v[156:159], v[212:215]
	v_mfma_f32_16x16x32_bf16 v[60:63], v[24:27], v[160:163], v[32:35]
	v_mfma_f32_16x16x32_bf16 v[32:35], v[0:3], v[168:171], v[52:55]
	v_mfma_f32_16x16x32_bf16 v[48:51], v[8:11], v[184:187], v[32:35]
	v_mfma_f32_16x16x32_bf16 v[32:35], v[16:19], v[168:171], v[220:223]
	v_mfma_f32_16x16x32_bf16 v[52:55], v[24:27], v[184:187], v[32:35]
	v_mfma_f32_16x16x32_bf16 v[32:35], v[0:3], v[188:191], v[44:47]
	v_mfma_f32_16x16x32_bf16 v[40:43], v[8:11], v[192:195], v[32:35]
	v_mfma_f32_16x16x32_bf16 v[32:35], v[16:19], v[188:191], v[224:227]
	v_mfma_f32_16x16x32_bf16 v[0:3], v[0:3], v[200:203], v[36:39]
	v_mfma_f32_16x16x32_bf16 v[44:47], v[24:27], v[192:195], v[32:35]
	v_mfma_f32_16x16x32_bf16 v[32:35], v[8:11], v[152:155], v[0:3]
	v_mfma_f32_16x16x32_bf16 v[0:3], v[16:19], v[200:203], v[138:141]
	v_mfma_f32_16x16x32_bf16 v[36:39], v[24:27], v[152:155], v[0:3]
	v_mfma_f32_16x16x32_bf16 v[0:3], v[130:133], v[156:159], v[28:31]
	v_mfma_f32_16x16x32_bf16 v[24:27], v[134:137], v[160:163], v[0:3]
	v_mfma_f32_16x16x32_bf16 v[0:3], v[172:175], v[156:159], v[142:145]
	v_mfma_f32_16x16x32_bf16 v[28:31], v[208:211], v[160:163], v[0:3]
	v_mfma_f32_16x16x32_bf16 v[0:3], v[130:133], v[168:171], v[20:23]
	v_mfma_f32_16x16x32_bf16 v[16:19], v[134:137], v[184:187], v[0:3]
	v_mfma_f32_16x16x32_bf16 v[0:3], v[172:175], v[168:171], v[176:179]
	v_mfma_f32_16x16x32_bf16 v[20:23], v[208:211], v[184:187], v[0:3]
	v_mfma_f32_16x16x32_bf16 v[0:3], v[130:133], v[188:191], v[12:15]
	v_mfma_f32_16x16x32_bf16 v[8:11], v[134:137], v[192:195], v[0:3]
	v_mfma_f32_16x16x32_bf16 v[0:3], v[172:175], v[188:191], v[180:183]
	v_mfma_f32_16x16x32_bf16 v[12:15], v[208:211], v[192:195], v[0:3]
	v_mfma_f32_16x16x32_bf16 v[0:3], v[130:133], v[200:203], v[4:7]
	v_mfma_f32_16x16x32_bf16 v[4:7], v[172:175], v[200:203], v[196:199]
	v_mfma_f32_16x16x32_bf16 v[0:3], v[134:137], v[152:155], v[0:3]
	v_mfma_f32_16x16x32_bf16 v[4:7], v[208:211], v[152:155], v[4:7]
	v_cmp_gt_u32_e32 vcc, s75, v128
	s_barrier
	s_and_saveexec_b64 s[38:39], vcc
	s_cbranch_execz .LBB0_1716
	s_barrier
	s_branch .LBB0_1716

.LBB0_1842:
	ds_read_b128 v[180:183], v172
	ds_read_b128 v[184:187], v172 offset:1024
	ds_read_b128 v[188:191], v172 offset:2048
	ds_read_b128 v[192:195], v172 offset:3072
	v_add_u32_e32 v178, 0xc000, v152
	v_lshl_add_u64 v[244:245], s[12:13], 0, v[146:147]
	v_readfirstlane_b32 s1, v178
	v_add_u32_e32 v179, 0xe000, v152
	v_lshl_add_u64 v[224:225], v[244:245], 0, s[20:21]
	s_mov_b32 m0, s1
	v_lshl_add_u64 v[246:247], s[12:13], 0, v[148:149]
	v_readfirstlane_b32 s1, v179
	ds_read_b128 v[174:177], v161
	ds_read_b128 v[196:199], v161 offset:1024
	ds_read_b128 v[200:203], v160
	ds_read_b128 v[204:207], v160 offset:1024
	ds_read_b128 v[208:211], v159
	ds_read_b128 v[212:215], v159 offset:1024
	ds_read_b128 v[216:219], v158
	ds_read_b128 v[220:223], v158 offset:1024
	global_load_lds_dwordx4 v[224:225], off
	v_lshl_add_u64 v[224:225], v[246:247], 0, s[20:21]
	s_mov_b32 m0, s1
	s_nop 0
	global_load_lds_dwordx4 v[224:225], off
	s_barrier
	s_waitcnt lgkmcnt(0)
	v_mfma_f32_16x16x32_bf16 v[124:127], v[180:183], v[174:177], v[124:127]
	v_mfma_f32_16x16x32_bf16 v[120:123], v[188:191], v[174:177], v[120:123]
	v_mfma_f32_16x16x32_bf16 v[116:119], v[180:183], v[200:203], v[116:119]
	v_mfma_f32_16x16x32_bf16 v[112:115], v[188:191], v[200:203], v[112:115]
	v_mfma_f32_16x16x32_bf16 v[108:111], v[180:183], v[208:211], v[108:111]
	v_mfma_f32_16x16x32_bf16 v[104:107], v[188:191], v[208:211], v[104:107]
	v_mfma_f32_16x16x32_bf16 v[100:103], v[180:183], v[216:219], v[100:103]
	v_mfma_f32_16x16x32_bf16 v[96:99], v[188:191], v[216:219], v[96:99]
	v_mfma_f32_16x16x32_bf16 v[124:127], v[184:187], v[196:199], v[124:127]
	v_mfma_f32_16x16x32_bf16 v[120:123], v[192:195], v[196:199], v[120:123]
	v_mfma_f32_16x16x32_bf16 v[116:119], v[184:187], v[204:207], v[116:119]
	v_mfma_f32_16x16x32_bf16 v[112:115], v[192:195], v[204:207], v[112:115]
	v_mfma_f32_16x16x32_bf16 v[108:111], v[184:187], v[212:215], v[108:111]
	v_mfma_f32_16x16x32_bf16 v[104:107], v[192:195], v[212:215], v[104:107]
	v_mfma_f32_16x16x32_bf16 v[100:103], v[184:187], v[220:223], v[100:103]
	v_mfma_f32_16x16x32_bf16 v[96:99], v[192:195], v[220:223], v[96:99]
	s_barrier
	v_lshl_add_u64 v[248:249], s[12:13], 0, v[142:143]
	v_readfirstlane_b32 s1, v153
	v_add_u32_e32 v173, 0x2000, v153
	v_lshl_add_u64 v[240:241], v[248:249], 0, s[24:25]
	s_mov_b32 m0, s1
	v_lshl_add_u64 v[250:251], s[12:13], 0, v[144:145]
	v_readfirstlane_b32 s1, v173
	ds_read_b128 v[224:227], v169
	ds_read_b128 v[228:231], v169 offset:1024
	ds_read_b128 v[232:235], v169 offset:2048
	ds_read_b128 v[236:239], v169 offset:3072
	global_load_lds_dwordx4 v[240:241], off
	v_lshl_add_u64 v[240:241], v[250:251], 0, s[24:25]
	s_mov_b32 m0, s1
	s_nop 0
	global_load_lds_dwordx4 v[240:241], off
	s_barrier
	s_waitcnt lgkmcnt(0)
	v_mfma_f32_16x16x32_bf16 v[92:95], v[224:227], v[174:177], v[92:95]
	v_mfma_f32_16x16x32_bf16 v[88:91], v[232:235], v[174:177], v[88:91]
	v_mfma_f32_16x16x32_bf16 v[84:87], v[224:227], v[200:203], v[84:87]
	v_mfma_f32_16x16x32_bf16 v[80:83], v[232:235], v[200:203], v[80:83]
	v_mfma_f32_16x16x32_bf16 v[76:79], v[224:227], v[208:211], v[76:79]
	v_mfma_f32_16x16x32_bf16 v[72:75], v[232:235], v[208:211], v[72:75]
	v_mfma_f32_16x16x32_bf16 v[68:71], v[224:227], v[216:219], v[68:71]
	v_mfma_f32_16x16x32_bf16 v[64:67], v[232:235], v[216:219], v[64:67]
	v_mfma_f32_16x16x32_bf16 v[92:95], v[228:231], v[196:199], v[92:95]
	v_mfma_f32_16x16x32_bf16 v[88:91], v[236:239], v[196:199], v[88:91]
	v_mfma_f32_16x16x32_bf16 v[84:87], v[228:231], v[204:207], v[84:87]
	v_mfma_f32_16x16x32_bf16 v[80:83], v[236:239], v[204:207], v[80:83]
	v_mfma_f32_16x16x32_bf16 v[76:79], v[228:231], v[212:215], v[76:79]
	v_mfma_f32_16x16x32_bf16 v[72:75], v[236:239], v[212:215], v[72:75]
	v_mfma_f32_16x16x32_bf16 v[68:71], v[228:231], v[220:223], v[68:71]
	v_mfma_f32_16x16x32_bf16 v[64:67], v[236:239], v[220:223], v[64:67]
	v_readfirstlane_b32 s1, v152
	v_lshl_add_u64 v[174:175], v[244:245], 0, s[26:27]
	s_mov_b32 m0, s1
	s_barrier
	ds_read_b128 v[196:199], v161 offset:16384
	ds_read_b128 v[200:203], v161 offset:17408
	ds_read_b128 v[204:207], v160 offset:16384
	ds_read_b128 v[208:211], v160 offset:17408
	ds_read_b128 v[212:215], v159 offset:16384
	ds_read_b128 v[216:219], v159 offset:17408
	ds_read_b128 v[220:223], v158 offset:16384
	ds_read_b128 v[240:243], v158 offset:17408
	global_load_lds_dwordx4 v[174:175], off
	v_add_u32_e32 v174, 0x2000, v152
	v_lshl_add_u64 v[176:177], v[246:247], 0, s[26:27]
	v_readfirstlane_b32 s1, v174
	s_mov_b32 m0, s1
	s_nop 0
	global_load_lds_dwordx4 v[176:177], off
	s_barrier
	s_waitcnt lgkmcnt(0)
	v_mfma_f32_16x16x32_bf16 v[60:63], v[180:183], v[196:199], v[60:63]
	v_mfma_f32_16x16x32_bf16 v[56:59], v[188:191], v[196:199], v[56:59]
	v_mfma_f32_16x16x32_bf16 v[52:55], v[180:183], v[204:207], v[52:55]
	v_mfma_f32_16x16x32_bf16 v[48:51], v[188:191], v[204:207], v[48:51]
	v_mfma_f32_16x16x32_bf16 v[44:47], v[180:183], v[212:215], v[44:47]
	v_mfma_f32_16x16x32_bf16 v[40:43], v[188:191], v[212:215], v[40:43]
	v_mfma_f32_16x16x32_bf16 v[36:39], v[180:183], v[220:223], v[36:39]
	v_mfma_f32_16x16x32_bf16 v[32:35], v[188:191], v[220:223], v[32:35]
	v_mfma_f32_16x16x32_bf16 v[60:63], v[184:187], v[200:203], v[60:63]
	v_mfma_f32_16x16x32_bf16 v[56:59], v[192:195], v[200:203], v[56:59]
	v_mfma_f32_16x16x32_bf16 v[52:55], v[184:187], v[208:211], v[52:55]
	v_mfma_f32_16x16x32_bf16 v[48:51], v[192:195], v[208:211], v[48:51]
	v_mfma_f32_16x16x32_bf16 v[44:47], v[184:187], v[216:219], v[44:47]
	v_mfma_f32_16x16x32_bf16 v[40:43], v[192:195], v[216:219], v[40:43]
	v_mfma_f32_16x16x32_bf16 v[36:39], v[184:187], v[240:243], v[36:39]
	v_mfma_f32_16x16x32_bf16 v[32:35], v[192:195], v[240:243], v[32:35]
	s_barrier
	v_readfirstlane_b32 s1, v151
	v_add_u32_e32 v175, 0x2000, v151
	v_lshl_add_u64 v[176:177], v[248:249], 0, s[28:29]
	s_mov_b32 m0, s1
	v_readfirstlane_b32 s1, v175
	global_load_lds_dwordx4 v[176:177], off
	v_lshl_add_u64 v[176:177], v[250:251], 0, s[28:29]
	s_mov_b32 m0, s1
	s_nop 0
	global_load_lds_dwordx4 v[176:177], off
	s_waitcnt vmcnt(6)
	s_barrier
	v_mfma_f32_16x16x32_bf16 v[28:31], v[224:227], v[196:199], v[28:31]
	v_mfma_f32_16x16x32_bf16 v[24:27], v[232:235], v[196:199], v[24:27]
	v_mfma_f32_16x16x32_bf16 v[20:23], v[224:227], v[204:207], v[20:23]
	v_mfma_f32_16x16x32_bf16 v[16:19], v[232:235], v[204:207], v[16:19]
	v_mfma_f32_16x16x32_bf16 v[12:15], v[224:227], v[212:215], v[12:15]
	v_mfma_f32_16x16x32_bf16 v[8:11], v[232:235], v[212:215], v[8:11]
	v_mfma_f32_16x16x32_bf16 v[4:7], v[224:227], v[220:223], v[4:7]
	v_mfma_f32_16x16x32_bf16 v[0:3], v[232:235], v[220:223], v[0:3]
	v_mfma_f32_16x16x32_bf16 v[28:31], v[228:231], v[200:203], v[28:31]
	v_mfma_f32_16x16x32_bf16 v[24:27], v[236:239], v[200:203], v[24:27]
	v_mfma_f32_16x16x32_bf16 v[20:23], v[228:231], v[208:211], v[20:23]
	v_mfma_f32_16x16x32_bf16 v[16:19], v[236:239], v[208:211], v[16:19]
	v_mfma_f32_16x16x32_bf16 v[12:15], v[228:231], v[216:219], v[12:15]
	v_mfma_f32_16x16x32_bf16 v[8:11], v[236:239], v[216:219], v[8:11]
	v_mfma_f32_16x16x32_bf16 v[4:7], v[228:231], v[240:243], v[4:7]
	v_mfma_f32_16x16x32_bf16 v[0:3], v[236:239], v[240:243], v[0:3]
	s_barrier
	ds_read_b128 v[180:183], v163
	ds_read_b128 v[184:187], v163 offset:1024
	ds_read_b128 v[188:191], v163 offset:2048
	ds_read_b128 v[192:195], v163 offset:3072
	v_add_u32_e32 v176, 0x4000, v152
	v_add_u32_e32 v177, 0x6000, v152
	v_readfirstlane_b32 s1, v176
	v_lshl_add_u64 v[228:229], v[244:245], 0, s[30:31]
	s_mov_b32 m0, s1
	v_readfirstlane_b32 s1, v177
	ds_read_b128 v[196:199], v161 offset:32768
	ds_read_b128 v[200:203], v161 offset:33792
	ds_read_b128 v[204:207], v160 offset:32768
	ds_read_b128 v[208:211], v160 offset:33792
	ds_read_b128 v[212:215], v159 offset:32768
	ds_read_b128 v[216:219], v159 offset:33792
	ds_read_b128 v[220:223], v158 offset:32768
	ds_read_b128 v[224:227], v158 offset:33792
	global_load_lds_dwordx4 v[228:229], off
	v_lshl_add_u64 v[228:229], v[246:247], 0, s[30:31]
	s_mov_b32 m0, s1
	s_nop 0
	global_load_lds_dwordx4 v[228:229], off
	s_barrier
	s_waitcnt lgkmcnt(0)
	v_mfma_f32_16x16x32_bf16 v[124:127], v[180:183], v[196:199], v[124:127]
	v_mfma_f32_16x16x32_bf16 v[120:123], v[188:191], v[196:199], v[120:123]
	v_mfma_f32_16x16x32_bf16 v[116:119], v[180:183], v[204:207], v[116:119]
	v_mfma_f32_16x16x32_bf16 v[112:115], v[188:191], v[204:207], v[112:115]
	v_mfma_f32_16x16x32_bf16 v[108:111], v[180:183], v[212:215], v[108:111]
	v_mfma_f32_16x16x32_bf16 v[104:107], v[188:191], v[212:215], v[104:107]
	v_mfma_f32_16x16x32_bf16 v[100:103], v[180:183], v[220:223], v[100:103]
	v_mfma_f32_16x16x32_bf16 v[96:99], v[188:191], v[220:223], v[96:99]
	v_mfma_f32_16x16x32_bf16 v[124:127], v[184:187], v[200:203], v[124:127]
	v_mfma_f32_16x16x32_bf16 v[120:123], v[192:195], v[200:203], v[120:123]
	v_mfma_f32_16x16x32_bf16 v[116:119], v[184:187], v[208:211], v[116:119]
	v_mfma_f32_16x16x32_bf16 v[112:115], v[192:195], v[208:211], v[112:115]
	v_mfma_f32_16x16x32_bf16 v[108:111], v[184:187], v[216:219], v[108:111]
	v_mfma_f32_16x16x32_bf16 v[104:107], v[192:195], v[216:219], v[104:107]
	v_mfma_f32_16x16x32_bf16 v[100:103], v[184:187], v[224:227], v[100:103]
	v_mfma_f32_16x16x32_bf16 v[96:99], v[192:195], v[224:227], v[96:99]
	s_barrier
	v_readfirstlane_b32 s1, v167
	v_add_u32_e32 v254, 0x2000, v167
	v_lshl_add_u64 v[252:253], v[248:249], 0, s[34:35]
	s_mov_b32 m0, s1
	v_readfirstlane_b32 s1, v254
	ds_read_b128 v[228:231], v162
	ds_read_b128 v[232:235], v162 offset:1024
	ds_read_b128 v[236:239], v162 offset:2048
	ds_read_b128 v[240:243], v162 offset:3072
	global_load_lds_dwordx4 v[252:253], off
	v_lshl_add_u64 v[252:253], v[250:251], 0, s[34:35]
	s_mov_b32 m0, s1
	s_nop 0
	global_load_lds_dwordx4 v[252:253], off
	s_barrier
	s_waitcnt lgkmcnt(0)
	v_mfma_f32_16x16x32_bf16 v[92:95], v[228:231], v[196:199], v[92:95]
	v_mfma_f32_16x16x32_bf16 v[88:91], v[236:239], v[196:199], v[88:91]
	v_mfma_f32_16x16x32_bf16 v[84:87], v[228:231], v[204:207], v[84:87]
	v_mfma_f32_16x16x32_bf16 v[80:83], v[236:239], v[204:207], v[80:83]
	v_mfma_f32_16x16x32_bf16 v[76:79], v[228:231], v[212:215], v[76:79]
	v_mfma_f32_16x16x32_bf16 v[72:75], v[236:239], v[212:215], v[72:75]
	v_mfma_f32_16x16x32_bf16 v[68:71], v[228:231], v[220:223], v[68:71]
	v_mfma_f32_16x16x32_bf16 v[64:67], v[236:239], v[220:223], v[64:67]
	v_mfma_f32_16x16x32_bf16 v[92:95], v[232:235], v[200:203], v[92:95]
	v_mfma_f32_16x16x32_bf16 v[88:91], v[240:243], v[200:203], v[88:91]
	v_mfma_f32_16x16x32_bf16 v[84:87], v[232:235], v[208:211], v[84:87]
	v_mfma_f32_16x16x32_bf16 v[80:83], v[240:243], v[208:211], v[80:83]
	v_mfma_f32_16x16x32_bf16 v[76:79], v[232:235], v[216:219], v[76:79]
	v_mfma_f32_16x16x32_bf16 v[72:75], v[240:243], v[216:219], v[72:75]
	v_mfma_f32_16x16x32_bf16 v[68:71], v[232:235], v[224:227], v[68:71]
	v_mfma_f32_16x16x32_bf16 v[64:67], v[240:243], v[224:227], v[64:67]
	v_readfirstlane_b32 s1, v168
	v_lshl_add_u64 v[244:245], v[244:245], 0, s[36:37]
	s_mov_b32 m0, s1
	v_readfirstlane_b32 s1, v170
	s_barrier
	ds_read_b128 v[196:199], v161 offset:49152
	ds_read_b128 v[200:203], v161 offset:50176
	ds_read_b128 v[204:207], v160 offset:49152
	ds_read_b128 v[208:211], v160 offset:50176
	ds_read_b128 v[212:215], v159 offset:49152
	ds_read_b128 v[216:219], v159 offset:50176
	ds_read_b128 v[220:223], v158 offset:49152
	ds_read_b128 v[224:227], v158 offset:50176
	global_load_lds_dwordx4 v[244:245], off
	v_lshl_add_u64 v[244:245], v[246:247], 0, s[36:37]
	s_mov_b32 m0, s1
	s_nop 0
	global_load_lds_dwordx4 v[244:245], off
	s_barrier
	s_waitcnt lgkmcnt(0)
	v_mfma_f32_16x16x32_bf16 v[60:63], v[180:183], v[196:199], v[60:63]
	v_mfma_f32_16x16x32_bf16 v[56:59], v[188:191], v[196:199], v[56:59]
	v_mfma_f32_16x16x32_bf16 v[52:55], v[180:183], v[204:207], v[52:55]
	v_mfma_f32_16x16x32_bf16 v[48:51], v[188:191], v[204:207], v[48:51]
	v_mfma_f32_16x16x32_bf16 v[44:47], v[180:183], v[212:215], v[44:47]
	v_mfma_f32_16x16x32_bf16 v[40:43], v[188:191], v[212:215], v[40:43]
	v_mfma_f32_16x16x32_bf16 v[36:39], v[180:183], v[220:223], v[36:39]
	v_mfma_f32_16x16x32_bf16 v[32:35], v[188:191], v[220:223], v[32:35]
	v_mfma_f32_16x16x32_bf16 v[60:63], v[184:187], v[200:203], v[60:63]
	v_mfma_f32_16x16x32_bf16 v[56:59], v[192:195], v[200:203], v[56:59]
	v_mfma_f32_16x16x32_bf16 v[52:55], v[184:187], v[208:211], v[52:55]
	v_mfma_f32_16x16x32_bf16 v[48:51], v[192:195], v[208:211], v[48:51]
	v_mfma_f32_16x16x32_bf16 v[44:47], v[184:187], v[216:219], v[44:47]
	v_mfma_f32_16x16x32_bf16 v[40:43], v[192:195], v[216:219], v[40:43]
	v_mfma_f32_16x16x32_bf16 v[36:39], v[184:187], v[224:227], v[36:39]
	v_mfma_f32_16x16x32_bf16 v[32:35], v[192:195], v[224:227], v[32:35]
	s_barrier
	v_readfirstlane_b32 s1, v171
	v_add_u32_e32 v182, 0x2000, v171
	v_lshl_add_u64 v[180:181], v[248:249], 0, s[38:39]
	s_mov_b32 m0, s1
	v_readfirstlane_b32 s1, v182
	global_load_lds_dwordx4 v[180:181], off
	v_lshl_add_u64 v[180:181], v[250:251], 0, s[38:39]
	s_mov_b32 m0, s1
	s_nop 0
	global_load_lds_dwordx4 v[180:181], off
	s_waitcnt vmcnt(6)
	s_barrier
	v_mfma_f32_16x16x32_bf16 v[28:31], v[228:231], v[196:199], v[28:31]
	v_mfma_f32_16x16x32_bf16 v[24:27], v[236:239], v[196:199], v[24:27]
	v_mfma_f32_16x16x32_bf16 v[20:23], v[228:231], v[204:207], v[20:23]
	v_mfma_f32_16x16x32_bf16 v[16:19], v[236:239], v[204:207], v[16:19]
	v_mfma_f32_16x16x32_bf16 v[12:15], v[228:231], v[212:215], v[12:15]
	v_mfma_f32_16x16x32_bf16 v[8:11], v[236:239], v[212:215], v[8:11]
	v_mfma_f32_16x16x32_bf16 v[4:7], v[228:231], v[220:223], v[4:7]
	v_mfma_f32_16x16x32_bf16 v[0:3], v[236:239], v[220:223], v[0:3]
	v_mfma_f32_16x16x32_bf16 v[28:31], v[232:235], v[200:203], v[28:31]
	v_mfma_f32_16x16x32_bf16 v[24:27], v[240:243], v[200:203], v[24:27]
	v_mfma_f32_16x16x32_bf16 v[20:23], v[232:235], v[208:211], v[20:23]
	v_mfma_f32_16x16x32_bf16 v[16:19], v[240:243], v[208:211], v[16:19]
	v_mfma_f32_16x16x32_bf16 v[12:15], v[232:235], v[216:219], v[12:15]
	v_mfma_f32_16x16x32_bf16 v[8:11], v[240:243], v[216:219], v[8:11]
	v_mfma_f32_16x16x32_bf16 v[4:7], v[232:235], v[224:227], v[4:7]
	v_mfma_f32_16x16x32_bf16 v[0:3], v[240:243], v[224:227], v[0:3]
	s_add_i32 s0, s0, 2
	v_lshl_add_u64 v[142:143], v[142:143], 0, s[46:47]
	v_lshl_add_u64 v[144:145], v[144:145], 0, s[46:47]
	v_lshl_add_u64 v[146:147], v[146:147], 0, s[46:47]
	s_cmp_lt_u32 s0, 12
	v_lshl_add_u64 v[148:149], v[148:149], 0, s[46:47]
	s_barrier
	s_cbranch_scc1 .LBB0_1842
	s_or_b32 s0, s8, 0x80
	s_ashr_i32 s1, s0, 31
	s_lshl_b64 s[0:1], s[0:1], 11
	s_add_u32 s0, s45, s0
	s_addc_u32 s1, s64, s1
	v_lshl_add_u64 v[170:171], s[0:1], 0, v[130:131]
	v_lshl_add_u64 v[138:139], v[138:139], 1, v[170:171]
	v_readfirstlane_b32 s2, v178
	v_lshl_add_u64 v[138:139], v[138:139], 0, s[58:59]
	s_mov_b32 m0, s2
	ds_read_b128 v[142:145], v172
	ds_read_b128 v[146:149], v172 offset:1024
	ds_read_b128 v[180:183], v172 offset:2048
	ds_read_b128 v[184:187], v172 offset:3072
	ds_read_b128 v[188:191], v161
	ds_read_b128 v[192:195], v161 offset:1024
	ds_read_b128 v[196:199], v160
	ds_read_b128 v[200:203], v160 offset:1024
	ds_read_b128 v[204:207], v159
	ds_read_b128 v[208:211], v159 offset:1024
	ds_read_b128 v[212:215], v158
	ds_read_b128 v[216:219], v158 offset:1024
	global_load_lds_dwordx4 v[138:139], off
	v_lshl_add_u64 v[138:139], s[0:1], 0, v[134:135]
	v_lshl_add_u64 v[138:139], v[140:141], 1, v[138:139]
	v_readfirstlane_b32 s0, v179
	v_lshl_add_u64 v[138:139], v[138:139], 0, s[58:59]
	s_mov_b32 m0, s0
	v_readlane_b32 s0, v255, 11
	global_load_lds_dwordx4 v[138:139], off
	s_add_i32 s79, s79, s0
	s_barrier
	s_waitcnt lgkmcnt(0)
	s_cmpk_gt_i32 s79, 0x54
	s_cselect_b64 s[60:61], -1, 0
	s_waitcnt lgkmcnt(0)
	v_mfma_f32_16x16x32_bf16 v[124:127], v[142:145], v[188:191], v[124:127]
	v_mfma_f32_16x16x32_bf16 v[116:119], v[142:145], v[196:199], v[116:119]
	v_mfma_f32_16x16x32_bf16 v[108:111], v[142:145], v[204:207], v[108:111]
	v_mfma_f32_16x16x32_bf16 v[100:103], v[142:145], v[212:215], v[100:103]
	v_mfma_f32_16x16x32_bf16 v[124:127], v[146:149], v[192:195], v[124:127]
	v_mfma_f32_16x16x32_bf16 v[120:123], v[180:183], v[188:191], v[120:123]
	v_mfma_f32_16x16x32_bf16 v[116:119], v[146:149], v[200:203], v[116:119]
	v_mfma_f32_16x16x32_bf16 v[112:115], v[180:183], v[196:199], v[112:115]
	v_mfma_f32_16x16x32_bf16 v[108:111], v[146:149], v[208:211], v[108:111]
	v_mfma_f32_16x16x32_bf16 v[104:107], v[180:183], v[204:207], v[104:107]
	v_mfma_f32_16x16x32_bf16 v[100:103], v[146:149], v[216:219], v[100:103]
	v_mfma_f32_16x16x32_bf16 v[96:99], v[180:183], v[212:215], v[96:99]
	v_mfma_f32_16x16x32_bf16 v[138:141], v[184:187], v[192:195], v[120:123]
	v_mfma_f32_16x16x32_bf16 v[220:223], v[184:187], v[200:203], v[112:115]
	v_mfma_f32_16x16x32_bf16 v[224:227], v[184:187], v[208:211], v[104:107]
	v_mfma_f32_16x16x32_bf16 v[228:231], v[184:187], v[216:219], v[96:99]
	s_barrier
	s_nop 1
	ds_read_b128 v[96:99], v169
	ds_read_b128 v[104:107], v169 offset:1024
	ds_read_b128 v[112:115], v169 offset:2048
	ds_read_b128 v[120:123], v169 offset:3072
	s_barrier
	s_waitcnt lgkmcnt(0)
	v_mfma_f32_16x16x32_bf16 v[92:95], v[96:99], v[188:191], v[92:95]
	v_mfma_f32_16x16x32_bf16 v[88:91], v[112:115], v[188:191], v[88:91]
	v_mfma_f32_16x16x32_bf16 v[84:87], v[96:99], v[196:199], v[84:87]
	v_mfma_f32_16x16x32_bf16 v[80:83], v[112:115], v[196:199], v[80:83]
	v_mfma_f32_16x16x32_bf16 v[76:79], v[96:99], v[204:207], v[76:79]
	v_mfma_f32_16x16x32_bf16 v[72:75], v[112:115], v[204:207], v[72:75]
	v_mfma_f32_16x16x32_bf16 v[68:71], v[96:99], v[212:215], v[68:71]
	v_mfma_f32_16x16x32_bf16 v[64:67], v[112:115], v[212:215], v[64:67]
	v_mfma_f32_16x16x32_bf16 v[92:95], v[104:107], v[192:195], v[92:95]
	v_mfma_f32_16x16x32_bf16 v[88:91], v[120:123], v[192:195], v[88:91]
	v_mfma_f32_16x16x32_bf16 v[84:87], v[104:107], v[200:203], v[84:87]
	v_mfma_f32_16x16x32_bf16 v[80:83], v[120:123], v[200:203], v[80:83]
	v_mfma_f32_16x16x32_bf16 v[76:79], v[104:107], v[208:211], v[76:79]
	v_mfma_f32_16x16x32_bf16 v[72:75], v[120:123], v[208:211], v[72:75]
	v_mfma_f32_16x16x32_bf16 v[68:71], v[104:107], v[216:219], v[68:71]
	v_mfma_f32_16x16x32_bf16 v[64:67], v[120:123], v[216:219], v[64:67]
	s_barrier
	ds_read_b128 v[168:171], v161 offset:16384
	ds_read_b128 v[188:191], v161 offset:17408
	ds_read_b128 v[192:195], v160 offset:16384
	ds_read_b128 v[196:199], v160 offset:17408
	ds_read_b128 v[200:203], v159 offset:16384
	ds_read_b128 v[204:207], v159 offset:17408
	ds_read_b128 v[208:211], v158 offset:16384
	ds_read_b128 v[212:215], v158 offset:17408
	s_waitcnt vmcnt(4)
	s_barrier
	s_waitcnt lgkmcnt(0)
	v_mfma_f32_16x16x32_bf16 v[60:63], v[142:145], v[168:171], v[60:63]
	v_mfma_f32_16x16x32_bf16 v[52:55], v[142:145], v[192:195], v[52:55]
	v_mfma_f32_16x16x32_bf16 v[44:47], v[142:145], v[200:203], v[44:47]
	v_mfma_f32_16x16x32_bf16 v[36:39], v[142:145], v[208:211], v[36:39]
	v_mfma_f32_16x16x32_bf16 v[60:63], v[146:149], v[188:191], v[60:63]
	v_mfma_f32_16x16x32_bf16 v[56:59], v[180:183], v[168:171], v[56:59]
	v_mfma_f32_16x16x32_bf16 v[52:55], v[146:149], v[196:199], v[52:55]
	v_mfma_f32_16x16x32_bf16 v[48:51], v[180:183], v[192:195], v[48:51]
	v_mfma_f32_16x16x32_bf16 v[44:47], v[146:149], v[204:207], v[44:47]
	v_mfma_f32_16x16x32_bf16 v[40:43], v[180:183], v[200:203], v[40:43]
	v_mfma_f32_16x16x32_bf16 v[36:39], v[146:149], v[212:215], v[36:39]
	v_mfma_f32_16x16x32_bf16 v[32:35], v[180:183], v[208:211], v[32:35]
	v_mfma_f32_16x16x32_bf16 v[216:219], v[184:187], v[188:191], v[56:59]
	v_mfma_f32_16x16x32_bf16 v[232:235], v[184:187], v[196:199], v[48:51]
	v_mfma_f32_16x16x32_bf16 v[236:239], v[184:187], v[204:207], v[40:43]
	v_mfma_f32_16x16x32_bf16 v[142:145], v[184:187], v[212:215], v[32:35]
	v_mfma_f32_16x16x32_bf16 v[28:31], v[96:99], v[168:171], v[28:31]
	v_mfma_f32_16x16x32_bf16 v[24:27], v[112:115], v[168:171], v[24:27]
	v_mfma_f32_16x16x32_bf16 v[20:23], v[96:99], v[192:195], v[20:23]
	v_mfma_f32_16x16x32_bf16 v[16:19], v[112:115], v[192:195], v[16:19]
	v_mfma_f32_16x16x32_bf16 v[12:15], v[96:99], v[200:203], v[12:15]
	v_mfma_f32_16x16x32_bf16 v[8:11], v[112:115], v[200:203], v[8:11]
	v_mfma_f32_16x16x32_bf16 v[4:7], v[96:99], v[208:211], v[4:7]
	v_mfma_f32_16x16x32_bf16 v[0:3], v[112:115], v[208:211], v[0:3]
	v_mfma_f32_16x16x32_bf16 v[28:31], v[104:107], v[188:191], v[28:31]
	v_mfma_f32_16x16x32_bf16 v[24:27], v[120:123], v[188:191], v[24:27]
	v_mfma_f32_16x16x32_bf16 v[20:23], v[104:107], v[196:199], v[20:23]
	v_mfma_f32_16x16x32_bf16 v[16:19], v[120:123], v[196:199], v[16:19]
	v_mfma_f32_16x16x32_bf16 v[12:15], v[104:107], v[204:207], v[12:15]
	v_mfma_f32_16x16x32_bf16 v[8:11], v[120:123], v[204:207], v[8:11]
	v_mfma_f32_16x16x32_bf16 v[4:7], v[104:107], v[212:215], v[4:7]
	v_mfma_f32_16x16x32_bf16 v[0:3], v[120:123], v[212:215], v[0:3]
	s_barrier
	ds_read_b128 v[32:35], v163
	ds_read_b128 v[146:149], v163 offset:1024
	ds_read_b128 v[168:171], v163 offset:2048
	ds_read_b128 v[178:181], v163 offset:3072
	ds_read_b128 v[40:43], v161 offset:32768
	ds_read_b128 v[48:51], v161 offset:33792
	ds_read_b128 v[56:59], v160 offset:32768
	ds_read_b128 v[182:185], v160 offset:33792
	ds_read_b128 v[186:189], v159 offset:32768
	ds_read_b128 v[190:193], v159 offset:33792
	ds_read_b128 v[194:197], v158 offset:32768
	ds_read_b128 v[198:201], v158 offset:33792
	s_waitcnt vmcnt(2)
	s_barrier
	s_waitcnt lgkmcnt(0)
	v_mfma_f32_16x16x32_bf16 v[96:99], v[32:35], v[40:43], v[124:127]
	v_mfma_f32_16x16x32_bf16 v[120:123], v[146:149], v[48:51], v[96:99]
	v_mfma_f32_16x16x32_bf16 v[96:99], v[168:171], v[40:43], v[138:141]
	v_mfma_f32_16x16x32_bf16 v[124:127], v[178:181], v[48:51], v[96:99]
	v_mfma_f32_16x16x32_bf16 v[96:99], v[32:35], v[56:59], v[116:119]
	v_mfma_f32_16x16x32_bf16 v[112:115], v[146:149], v[182:185], v[96:99]
	v_mfma_f32_16x16x32_bf16 v[96:99], v[168:171], v[56:59], v[220:223]
	v_mfma_f32_16x16x32_bf16 v[116:119], v[178:181], v[182:185], v[96:99]
	v_mfma_f32_16x16x32_bf16 v[96:99], v[32:35], v[186:189], v[108:111]
	v_mfma_f32_16x16x32_bf16 v[104:107], v[146:149], v[190:193], v[96:99]
	v_mfma_f32_16x16x32_bf16 v[96:99], v[168:171], v[186:189], v[224:227]
	v_mfma_f32_16x16x32_bf16 v[108:111], v[178:181], v[190:193], v[96:99]
	v_mfma_f32_16x16x32_bf16 v[96:99], v[32:35], v[194:197], v[100:103]
	v_mfma_f32_16x16x32_bf16 v[100:103], v[168:171], v[194:197], v[228:231]
	v_mfma_f32_16x16x32_bf16 v[96:99], v[146:149], v[198:201], v[96:99]
	v_mfma_f32_16x16x32_bf16 v[100:103], v[178:181], v[198:201], v[100:103]
	s_barrier
	ds_read_b128 v[138:141], v162
	ds_read_b128 v[202:205], v162 offset:1024
	ds_read_b128 v[206:209], v162 offset:2048
	ds_read_b128 v[210:213], v162 offset:3072
	s_waitcnt vmcnt(0)
	s_barrier
	s_waitcnt lgkmcnt(0)
	v_mfma_f32_16x16x32_bf16 v[92:95], v[138:141], v[40:43], v[92:95]
	v_mfma_f32_16x16x32_bf16 v[40:43], v[206:209], v[40:43], v[88:91]
	v_mfma_f32_16x16x32_bf16 v[88:91], v[210:213], v[48:51], v[40:43]
	v_mfma_f32_16x16x32_bf16 v[40:43], v[138:141], v[56:59], v[84:87]
	v_mfma_f32_16x16x32_bf16 v[84:87], v[202:205], v[182:185], v[40:43]
	v_mfma_f32_16x16x32_bf16 v[40:43], v[206:209], v[56:59], v[80:83]
	v_mfma_f32_16x16x32_bf16 v[80:83], v[210:213], v[182:185], v[40:43]
	v_mfma_f32_16x16x32_bf16 v[40:43], v[138:141], v[186:189], v[76:79]
	v_mfma_f32_16x16x32_bf16 v[76:79], v[202:205], v[190:193], v[40:43]
	v_mfma_f32_16x16x32_bf16 v[40:43], v[206:209], v[186:189], v[72:75]
	v_mfma_f32_16x16x32_bf16 v[72:75], v[210:213], v[190:193], v[40:43]
	v_mfma_f32_16x16x32_bf16 v[40:43], v[138:141], v[194:197], v[68:71]
	v_mfma_f32_16x16x32_bf16 v[68:71], v[202:205], v[198:201], v[40:43]
	v_mfma_f32_16x16x32_bf16 v[40:43], v[206:209], v[194:197], v[64:67]
	v_mfma_f32_16x16x32_bf16 v[92:95], v[202:205], v[48:51], v[92:95]
	v_mfma_f32_16x16x32_bf16 v[64:67], v[210:213], v[198:201], v[40:43]
	s_barrier
	ds_read_b128 v[182:185], v161 offset:49152
	ds_read_b128 v[186:189], v161 offset:50176
	ds_read_b128 v[190:193], v160 offset:49152
	ds_read_b128 v[160:163], v160 offset:50176
	ds_read_b128 v[194:197], v159 offset:49152
	ds_read_b128 v[198:201], v159 offset:50176
	ds_read_b128 v[220:223], v158 offset:49152
	ds_read_b128 v[224:227], v158 offset:50176
	s_barrier
	s_waitcnt lgkmcnt(0)
	v_mfma_f32_16x16x32_bf16 v[40:43], v[32:35], v[182:185], v[60:63]
	v_mfma_f32_16x16x32_bf16 v[56:59], v[146:149], v[186:189], v[40:43]
	v_mfma_f32_16x16x32_bf16 v[40:43], v[168:171], v[182:185], v[216:219]
	v_mfma_f32_16x16x32_bf16 v[60:63], v[178:181], v[186:189], v[40:43]
	v_mfma_f32_16x16x32_bf16 v[40:43], v[32:35], v[190:193], v[52:55]
	v_mfma_f32_16x16x32_bf16 v[48:51], v[146:149], v[160:163], v[40:43]
	v_mfma_f32_16x16x32_bf16 v[40:43], v[168:171], v[190:193], v[232:235]
	v_mfma_f32_16x16x32_bf16 v[52:55], v[178:181], v[160:163], v[40:43]
	v_mfma_f32_16x16x32_bf16 v[40:43], v[32:35], v[194:197], v[44:47]
	v_mfma_f32_16x16x32_bf16 v[44:47], v[168:171], v[194:197], v[236:239]
	v_mfma_f32_16x16x32_bf16 v[32:35], v[32:35], v[220:223], v[36:39]
	v_mfma_f32_16x16x32_bf16 v[36:39], v[168:171], v[220:223], v[142:145]
	v_mfma_f32_16x16x32_bf16 v[40:43], v[146:149], v[198:201], v[40:43]
	v_mfma_f32_16x16x32_bf16 v[44:47], v[178:181], v[198:201], v[44:47]
	v_mfma_f32_16x16x32_bf16 v[32:35], v[146:149], v[224:227], v[32:35]
	v_mfma_f32_16x16x32_bf16 v[36:39], v[178:181], v[224:227], v[36:39]
	v_mfma_f32_16x16x32_bf16 v[28:31], v[138:141], v[182:185], v[28:31]
	v_mfma_f32_16x16x32_bf16 v[24:27], v[206:209], v[182:185], v[24:27]
	v_mfma_f32_16x16x32_bf16 v[20:23], v[138:141], v[190:193], v[20:23]
	v_mfma_f32_16x16x32_bf16 v[16:19], v[206:209], v[190:193], v[16:19]
	v_mfma_f32_16x16x32_bf16 v[12:15], v[138:141], v[194:197], v[12:15]
	v_mfma_f32_16x16x32_bf16 v[8:11], v[206:209], v[194:197], v[8:11]
	v_mfma_f32_16x16x32_bf16 v[4:7], v[138:141], v[220:223], v[4:7]
	v_mfma_f32_16x16x32_bf16 v[0:3], v[206:209], v[220:223], v[0:3]
	v_mfma_f32_16x16x32_bf16 v[28:31], v[202:205], v[186:189], v[28:31]
	v_mfma_f32_16x16x32_bf16 v[24:27], v[210:213], v[186:189], v[24:27]
	v_mfma_f32_16x16x32_bf16 v[20:23], v[202:205], v[160:163], v[20:23]
	v_mfma_f32_16x16x32_bf16 v[16:19], v[210:213], v[160:163], v[16:19]
	v_mfma_f32_16x16x32_bf16 v[12:15], v[202:205], v[198:201], v[12:15]
	v_mfma_f32_16x16x32_bf16 v[8:11], v[210:213], v[198:201], v[8:11]
	v_mfma_f32_16x16x32_bf16 v[4:7], v[202:205], v[224:227], v[4:7]
	v_mfma_f32_16x16x32_bf16 v[0:3], v[210:213], v[224:227], v[0:3]
	s_and_b64 vcc, exec, s[60:61]
	s_barrier
	s_cbranch_vccnz .LBB0_1845
	s_mul_hi_i32 s0, s79, 0x66666667
	s_lshr_b32 s1, s0, 31
	s_ashr_i32 s0, s0, 1
	s_add_i32 s0, s0, s1
	v_readlane_b32 s1, v255, 15
	s_add_i32 s1, s0, s1
	s_mul_i32 s0, s0, 5
	s_sub_i32 s0, s79, s0
	v_readlane_b32 s2, v255, 14
	s_add_i32 s2, s0, s2
	s_lshl_b32 s4, s2, 8
	s_ashr_i32 s5, s4, 31
	s_lshl_b32 s0, s1, 8
	s_lshl_b64 s[10:11], s[4:5], 11
	s_add_u32 s10, s65, s10
	s_addc_u32 s11, s66, s11
	v_lshl_add_u64 v[138:139], s[10:11], 0, v[130:131]
	v_readfirstlane_b32 s1, v153
	v_lshl_add_u64 v[138:139], v[138:139], 0, v[132:133]
	s_mov_b32 m0, s1
	v_readfirstlane_b32 s1, v173
	global_load_lds_dwordx4 v[138:139], off
	s_mov_b32 m0, s1
	s_ashr_i32 s1, s0, 31
	v_lshl_add_u64 v[138:139], s[10:11], 0, v[134:135]
	s_lshl_b64 s[10:11], s[0:1], 11
	s_add_u32 s10, s45, s10
	v_lshl_add_u64 v[138:139], v[138:139], 0, v[136:137]
	s_addc_u32 s11, s64, s11
	s_bitset1_b32 s4, 7
	global_load_lds_dwordx4 v[138:139], off
	v_lshl_add_u64 v[138:139], s[10:11], 0, v[130:131]
	v_readfirstlane_b32 s1, v152
	s_ashr_i32 s5, s4, 31
	v_lshl_add_u64 v[138:139], v[138:139], 0, v[132:133]
	s_mov_b32 m0, s1
	s_lshl_b64 s[4:5], s[4:5], 11
	global_load_lds_dwordx4 v[138:139], off
	v_lshl_add_u64 v[138:139], s[10:11], 0, v[134:135]
	v_readfirstlane_b32 s1, v174
	s_add_u32 s4, s65, s4
	v_lshl_add_u64 v[138:139], v[138:139], 0, v[136:137]
	s_mov_b32 m0, s1
	s_addc_u32 s5, s66, s5
	global_load_lds_dwordx4 v[138:139], off
	v_lshl_add_u64 v[138:139], s[4:5], 0, v[130:131]
	v_readfirstlane_b32 s1, v151
	v_lshl_add_u64 v[138:139], v[138:139], 0, v[132:133]
	s_mov_b32 m0, s1
	v_readfirstlane_b32 s1, v175
	s_bitset1_b32 s0, 7
	global_load_lds_dwordx4 v[138:139], off
	s_mov_b32 m0, s1
	s_ashr_i32 s1, s0, 31
	s_lshl_b64 s[0:1], s[0:1], 11
	s_add_u32 s0, s45, s0
	v_lshl_add_u64 v[138:139], s[4:5], 0, v[134:135]
	s_addc_u32 s1, s64, s1
	v_lshl_add_u64 v[138:139], v[138:139], 0, v[136:137]
	v_lshl_add_u64 v[130:131], s[0:1], 0, v[130:131]
	v_readfirstlane_b32 s2, v176
	global_load_lds_dwordx4 v[138:139], off
	v_lshl_add_u64 v[130:131], v[130:131], 0, v[132:133]
	s_mov_b32 m0, s2
	s_nop 0
	global_load_lds_dwordx4 v[130:131], off
	v_lshl_add_u64 v[130:131], s[0:1], 0, v[134:135]
	v_readfirstlane_b32 s0, v177
	v_lshl_add_u64 v[130:131], v[130:131], 0, v[136:137]
	s_mov_b32 m0, s0
	s_nop 0
	global_load_lds_dwordx4 v[130:131], off

.LBB0_2799:
	ds_read_b128 v[182:185], v180
	ds_read_b128 v[186:189], v180 offset:1024
	ds_read_b128 v[190:193], v180 offset:2048
	ds_read_b128 v[194:197], v180 offset:3072
	v_add_u32_e32 v0, 0xc000, v162
	v_lshl_add_u64 v[246:247], v[142:143], 0, s[48:49]
	v_readfirstlane_b32 s4, v0
	v_lshl_add_u64 v[2:3], v[246:247], 0, s[20:21]
	s_mov_b32 m0, s4
	ds_read_b128 v[198:201], v161
	ds_read_b128 v[202:205], v161 offset:1024
	ds_read_b128 v[206:209], v160
	ds_read_b128 v[210:213], v160 offset:1024
	ds_read_b128 v[214:217], v159
	ds_read_b128 v[218:221], v159 offset:1024
	ds_read_b128 v[222:225], v158
	ds_read_b128 v[226:229], v158 offset:1024
	global_load_lds_dwordx4 v[2:3], off
	v_add_u32_e32 v2, 0xe000, v162
	v_lshl_add_u64 v[248:249], v[144:145], 0, s[48:49]
	v_readfirstlane_b32 s4, v2
	v_lshl_add_u64 v[230:231], v[248:249], 0, s[20:21]
	s_mov_b32 m0, s4
	s_nop 0
	global_load_lds_dwordx4 v[230:231], off
	s_barrier
	s_waitcnt lgkmcnt(0)
	v_mfma_f32_16x16x32_bf16 v[128:131], v[182:185], v[198:201], v[128:131]
	v_mfma_f32_16x16x32_bf16 v[124:127], v[190:193], v[198:201], v[124:127]
	v_mfma_f32_16x16x32_bf16 v[120:123], v[182:185], v[206:209], v[120:123]
	v_mfma_f32_16x16x32_bf16 v[116:119], v[190:193], v[206:209], v[116:119]
	v_mfma_f32_16x16x32_bf16 v[112:115], v[182:185], v[214:217], v[112:115]
	v_mfma_f32_16x16x32_bf16 v[108:111], v[190:193], v[214:217], v[108:111]
	v_mfma_f32_16x16x32_bf16 v[104:107], v[182:185], v[222:225], v[104:107]
	v_mfma_f32_16x16x32_bf16 v[100:103], v[190:193], v[222:225], v[100:103]
	v_mfma_f32_16x16x32_bf16 v[128:131], v[186:189], v[202:205], v[128:131]
	v_mfma_f32_16x16x32_bf16 v[124:127], v[194:197], v[202:205], v[124:127]
	v_mfma_f32_16x16x32_bf16 v[120:123], v[186:189], v[210:213], v[120:123]
	v_mfma_f32_16x16x32_bf16 v[116:119], v[194:197], v[210:213], v[116:119]
	v_mfma_f32_16x16x32_bf16 v[112:115], v[186:189], v[218:221], v[112:115]
	v_mfma_f32_16x16x32_bf16 v[108:111], v[194:197], v[218:221], v[108:111]
	v_mfma_f32_16x16x32_bf16 v[104:107], v[186:189], v[226:229], v[104:107]
	v_mfma_f32_16x16x32_bf16 v[100:103], v[194:197], v[226:229], v[100:103]
	s_barrier
	v_lshl_add_u64 v[250:251], v[138:139], 0, s[48:49]
	v_readfirstlane_b32 s4, v147
	v_lshl_add_u64 v[252:253], v[250:251], 0, s[24:25]
	s_mov_b32 m0, s4
	v_add_u32_e32 v3, 0x2000, v147
	ds_read_b128 v[230:233], v178
	ds_read_b128 v[234:237], v178 offset:1024
	ds_read_b128 v[238:241], v178 offset:2048
	ds_read_b128 v[242:245], v178 offset:3072
	global_load_lds_dwordx4 v[252:253], off
	v_lshl_add_u64 v[252:253], v[140:141], 0, s[48:49]
	v_readfirstlane_b32 s4, v3
	v_lshl_add_u64 v[132:133], v[252:253], 0, s[24:25]
	s_mov_b32 m0, s4
	s_add_i32 s4, s2, 2
	global_load_lds_dwordx4 v[132:133], off
	s_barrier
	s_waitcnt lgkmcnt(0)
	v_mfma_f32_16x16x32_bf16 v[96:99], v[230:233], v[198:201], v[96:99]
	v_mfma_f32_16x16x32_bf16 v[92:95], v[238:241], v[198:201], v[92:95]
	v_mfma_f32_16x16x32_bf16 v[88:91], v[230:233], v[206:209], v[88:91]
	v_mfma_f32_16x16x32_bf16 v[84:87], v[238:241], v[206:209], v[84:87]
	v_mfma_f32_16x16x32_bf16 v[80:83], v[230:233], v[214:217], v[80:83]
	v_mfma_f32_16x16x32_bf16 v[76:79], v[238:241], v[214:217], v[76:79]
	v_mfma_f32_16x16x32_bf16 v[72:75], v[230:233], v[222:225], v[72:75]
	v_mfma_f32_16x16x32_bf16 v[68:71], v[238:241], v[222:225], v[68:71]
	v_mfma_f32_16x16x32_bf16 v[96:99], v[234:237], v[202:205], v[96:99]
	v_mfma_f32_16x16x32_bf16 v[92:95], v[242:245], v[202:205], v[92:95]
	v_mfma_f32_16x16x32_bf16 v[88:91], v[234:237], v[210:213], v[88:91]
	v_mfma_f32_16x16x32_bf16 v[84:87], v[242:245], v[210:213], v[84:87]
	v_mfma_f32_16x16x32_bf16 v[80:83], v[234:237], v[218:221], v[80:83]
	v_mfma_f32_16x16x32_bf16 v[76:79], v[242:245], v[218:221], v[76:79]
	v_mfma_f32_16x16x32_bf16 v[72:75], v[234:237], v[226:229], v[72:75]
	v_mfma_f32_16x16x32_bf16 v[68:71], v[242:245], v[226:229], v[68:71]
	v_readfirstlane_b32 s5, v162
	v_lshl_add_u64 v[132:133], v[246:247], 0, s[26:27]
	s_mov_b32 m0, s5
	v_readfirstlane_b32 s5, v163
	s_barrier
	ds_read_b128 v[198:201], v161 offset:16384
	ds_read_b128 v[202:205], v161 offset:17408
	ds_read_b128 v[206:209], v160 offset:16384
	ds_read_b128 v[210:213], v160 offset:17408
	ds_read_b128 v[214:217], v159 offset:16384
	ds_read_b128 v[218:221], v159 offset:17408
	ds_read_b128 v[222:225], v158 offset:16384
	ds_read_b128 v[226:229], v158 offset:17408
	global_load_lds_dwordx4 v[132:133], off
	v_lshl_add_u64 v[132:133], v[248:249], 0, s[26:27]
	s_mov_b32 m0, s5
	s_nop 0
	global_load_lds_dwordx4 v[132:133], off
	s_barrier
	s_waitcnt lgkmcnt(0)
	v_mfma_f32_16x16x32_bf16 v[64:67], v[182:185], v[198:201], v[64:67]
	v_mfma_f32_16x16x32_bf16 v[60:63], v[190:193], v[198:201], v[60:63]
	v_mfma_f32_16x16x32_bf16 v[56:59], v[182:185], v[206:209], v[56:59]
	v_mfma_f32_16x16x32_bf16 v[52:55], v[190:193], v[206:209], v[52:55]
	v_mfma_f32_16x16x32_bf16 v[48:51], v[182:185], v[214:217], v[48:51]
	v_mfma_f32_16x16x32_bf16 v[44:47], v[190:193], v[214:217], v[44:47]
	v_mfma_f32_16x16x32_bf16 v[40:43], v[182:185], v[222:225], v[40:43]
	v_mfma_f32_16x16x32_bf16 v[36:39], v[190:193], v[222:225], v[36:39]
	v_mfma_f32_16x16x32_bf16 v[64:67], v[186:189], v[202:205], v[64:67]
	v_mfma_f32_16x16x32_bf16 v[60:63], v[194:197], v[202:205], v[60:63]
	v_mfma_f32_16x16x32_bf16 v[56:59], v[186:189], v[210:213], v[56:59]
	v_mfma_f32_16x16x32_bf16 v[52:55], v[194:197], v[210:213], v[52:55]
	v_mfma_f32_16x16x32_bf16 v[48:51], v[186:189], v[218:221], v[48:51]
	v_mfma_f32_16x16x32_bf16 v[44:47], v[194:197], v[218:221], v[44:47]
	v_mfma_f32_16x16x32_bf16 v[40:43], v[186:189], v[226:229], v[40:43]
	v_mfma_f32_16x16x32_bf16 v[36:39], v[194:197], v[226:229], v[36:39]
	s_barrier
	v_readfirstlane_b32 s5, v168
	v_add_u32_e32 v3, 0x2000, v168
	v_lshl_add_u64 v[132:133], v[250:251], 0, s[28:29]
	s_mov_b32 m0, s5
	v_readfirstlane_b32 s5, v3
	global_load_lds_dwordx4 v[132:133], off
	v_lshl_add_u64 v[132:133], v[252:253], 0, s[28:29]
	s_mov_b32 m0, s5
	s_nop 0
	global_load_lds_dwordx4 v[132:133], off
	s_waitcnt vmcnt(6)
	s_barrier
	v_mfma_f32_16x16x32_bf16 v[32:35], v[230:233], v[198:201], v[32:35]
	v_mfma_f32_16x16x32_bf16 v[28:31], v[238:241], v[198:201], v[28:31]
	v_mfma_f32_16x16x32_bf16 v[24:27], v[230:233], v[206:209], v[24:27]
	v_mfma_f32_16x16x32_bf16 v[20:23], v[238:241], v[206:209], v[20:23]
	v_mfma_f32_16x16x32_bf16 v[16:19], v[230:233], v[214:217], v[16:19]
	v_mfma_f32_16x16x32_bf16 v[12:15], v[238:241], v[214:217], v[12:15]
	v_mfma_f32_16x16x32_bf16 v[8:11], v[230:233], v[222:225], v[8:11]
	v_mfma_f32_16x16x32_bf16 v[4:7], v[238:241], v[222:225], v[4:7]
	v_mfma_f32_16x16x32_bf16 v[32:35], v[234:237], v[202:205], v[32:35]
	v_mfma_f32_16x16x32_bf16 v[28:31], v[242:245], v[202:205], v[28:31]
	v_mfma_f32_16x16x32_bf16 v[24:27], v[234:237], v[210:213], v[24:27]
	v_mfma_f32_16x16x32_bf16 v[20:23], v[242:245], v[210:213], v[20:23]
	v_mfma_f32_16x16x32_bf16 v[16:19], v[234:237], v[218:221], v[16:19]
	v_mfma_f32_16x16x32_bf16 v[12:15], v[242:245], v[218:221], v[12:15]
	v_mfma_f32_16x16x32_bf16 v[8:11], v[234:237], v[226:229], v[8:11]
	v_mfma_f32_16x16x32_bf16 v[4:7], v[242:245], v[226:229], v[4:7]
	s_barrier
	ds_read_b128 v[182:185], v170
	ds_read_b128 v[186:189], v170 offset:1024
	ds_read_b128 v[190:193], v170 offset:2048
	ds_read_b128 v[194:197], v170 offset:3072
	v_readfirstlane_b32 s5, v169
	v_lshl_add_u64 v[132:133], v[246:247], 0, s[30:31]
	s_mov_b32 m0, s5
	v_readfirstlane_b32 s5, v171
	ds_read_b128 v[198:201], v161 offset:32768
	ds_read_b128 v[202:205], v161 offset:33792
	ds_read_b128 v[206:209], v160 offset:32768
	ds_read_b128 v[210:213], v160 offset:33792
	ds_read_b128 v[214:217], v159 offset:32768
	ds_read_b128 v[218:221], v159 offset:33792
	ds_read_b128 v[222:225], v158 offset:32768
	ds_read_b128 v[226:229], v158 offset:33792
	global_load_lds_dwordx4 v[132:133], off
	v_lshl_add_u64 v[132:133], v[248:249], 0, s[30:31]
	s_mov_b32 m0, s5
	s_nop 0
	global_load_lds_dwordx4 v[132:133], off
	s_barrier
	s_waitcnt lgkmcnt(0)
	v_mfma_f32_16x16x32_bf16 v[128:131], v[182:185], v[198:201], v[128:131]
	v_mfma_f32_16x16x32_bf16 v[124:127], v[190:193], v[198:201], v[124:127]
	v_mfma_f32_16x16x32_bf16 v[120:123], v[182:185], v[206:209], v[120:123]
	v_mfma_f32_16x16x32_bf16 v[116:119], v[190:193], v[206:209], v[116:119]
	v_mfma_f32_16x16x32_bf16 v[112:115], v[182:185], v[214:217], v[112:115]
	v_mfma_f32_16x16x32_bf16 v[108:111], v[190:193], v[214:217], v[108:111]
	v_mfma_f32_16x16x32_bf16 v[104:107], v[182:185], v[222:225], v[104:107]
	v_mfma_f32_16x16x32_bf16 v[100:103], v[190:193], v[222:225], v[100:103]
	v_mfma_f32_16x16x32_bf16 v[128:131], v[186:189], v[202:205], v[128:131]
	v_mfma_f32_16x16x32_bf16 v[124:127], v[194:197], v[202:205], v[124:127]
	v_mfma_f32_16x16x32_bf16 v[120:123], v[186:189], v[210:213], v[120:123]
	v_mfma_f32_16x16x32_bf16 v[116:119], v[194:197], v[210:213], v[116:119]
	v_mfma_f32_16x16x32_bf16 v[112:115], v[186:189], v[218:221], v[112:115]
	v_mfma_f32_16x16x32_bf16 v[108:111], v[194:197], v[218:221], v[108:111]
	v_mfma_f32_16x16x32_bf16 v[104:107], v[186:189], v[226:229], v[104:107]
	v_mfma_f32_16x16x32_bf16 v[100:103], v[194:197], v[226:229], v[100:103]
	s_barrier
	v_readfirstlane_b32 s5, v172
	v_lshl_add_u64 v[132:133], v[250:251], 0, s[34:35]
	s_mov_b32 m0, s5
	v_readfirstlane_b32 s5, v173
	ds_read_b128 v[230:233], v167
	ds_read_b128 v[234:237], v167 offset:1024
	ds_read_b128 v[238:241], v167 offset:2048
	ds_read_b128 v[242:245], v167 offset:3072
	global_load_lds_dwordx4 v[132:133], off
	v_lshl_add_u64 v[132:133], v[252:253], 0, s[34:35]
	s_mov_b32 m0, s5
	s_nop 0
	global_load_lds_dwordx4 v[132:133], off
	s_barrier
	s_waitcnt lgkmcnt(0)
	v_mfma_f32_16x16x32_bf16 v[96:99], v[230:233], v[198:201], v[96:99]
	v_mfma_f32_16x16x32_bf16 v[92:95], v[238:241], v[198:201], v[92:95]
	v_mfma_f32_16x16x32_bf16 v[88:91], v[230:233], v[206:209], v[88:91]
	v_mfma_f32_16x16x32_bf16 v[84:87], v[238:241], v[206:209], v[84:87]
	v_mfma_f32_16x16x32_bf16 v[80:83], v[230:233], v[214:217], v[80:83]
	v_mfma_f32_16x16x32_bf16 v[76:79], v[238:241], v[214:217], v[76:79]
	v_mfma_f32_16x16x32_bf16 v[72:75], v[230:233], v[222:225], v[72:75]
	v_mfma_f32_16x16x32_bf16 v[68:71], v[238:241], v[222:225], v[68:71]
	v_mfma_f32_16x16x32_bf16 v[96:99], v[234:237], v[202:205], v[96:99]
	v_mfma_f32_16x16x32_bf16 v[92:95], v[242:245], v[202:205], v[92:95]
	v_mfma_f32_16x16x32_bf16 v[88:91], v[234:237], v[210:213], v[88:91]
	v_mfma_f32_16x16x32_bf16 v[84:87], v[242:245], v[210:213], v[84:87]
	v_mfma_f32_16x16x32_bf16 v[80:83], v[234:237], v[218:221], v[80:83]
	v_mfma_f32_16x16x32_bf16 v[76:79], v[242:245], v[218:221], v[76:79]
	v_mfma_f32_16x16x32_bf16 v[72:75], v[234:237], v[226:229], v[72:75]
	v_mfma_f32_16x16x32_bf16 v[68:71], v[242:245], v[226:229], v[68:71]
	v_readfirstlane_b32 s5, v174
	v_lshl_add_u64 v[132:133], v[246:247], 0, s[36:37]
	s_mov_b32 m0, s5
	v_readfirstlane_b32 s5, v175
	s_barrier
	ds_read_b128 v[198:201], v161 offset:49152
	ds_read_b128 v[202:205], v161 offset:50176
	ds_read_b128 v[206:209], v160 offset:49152
	ds_read_b128 v[210:213], v160 offset:50176
	ds_read_b128 v[214:217], v159 offset:49152
	ds_read_b128 v[218:221], v159 offset:50176
	ds_read_b128 v[222:225], v158 offset:49152
	ds_read_b128 v[226:229], v158 offset:50176
	global_load_lds_dwordx4 v[132:133], off
	v_lshl_add_u64 v[132:133], v[248:249], 0, s[36:37]
	s_mov_b32 m0, s5
	s_nop 0
	global_load_lds_dwordx4 v[132:133], off
	s_barrier
	s_waitcnt lgkmcnt(0)
	v_mfma_f32_16x16x32_bf16 v[64:67], v[182:185], v[198:201], v[64:67]
	v_mfma_f32_16x16x32_bf16 v[60:63], v[190:193], v[198:201], v[60:63]
	v_mfma_f32_16x16x32_bf16 v[56:59], v[182:185], v[206:209], v[56:59]
	v_mfma_f32_16x16x32_bf16 v[52:55], v[190:193], v[206:209], v[52:55]
	v_mfma_f32_16x16x32_bf16 v[48:51], v[182:185], v[214:217], v[48:51]
	v_mfma_f32_16x16x32_bf16 v[44:47], v[190:193], v[214:217], v[44:47]
	v_mfma_f32_16x16x32_bf16 v[40:43], v[182:185], v[222:225], v[40:43]
	v_mfma_f32_16x16x32_bf16 v[36:39], v[190:193], v[222:225], v[36:39]
	v_mfma_f32_16x16x32_bf16 v[64:67], v[186:189], v[202:205], v[64:67]
	v_mfma_f32_16x16x32_bf16 v[60:63], v[194:197], v[202:205], v[60:63]
	v_mfma_f32_16x16x32_bf16 v[56:59], v[186:189], v[210:213], v[56:59]
	v_mfma_f32_16x16x32_bf16 v[52:55], v[194:197], v[210:213], v[52:55]
	v_mfma_f32_16x16x32_bf16 v[48:51], v[186:189], v[218:221], v[48:51]
	v_mfma_f32_16x16x32_bf16 v[44:47], v[194:197], v[218:221], v[44:47]
	v_mfma_f32_16x16x32_bf16 v[40:43], v[186:189], v[226:229], v[40:43]
	v_mfma_f32_16x16x32_bf16 v[36:39], v[194:197], v[226:229], v[36:39]
	s_barrier
	v_readfirstlane_b32 s5, v176
	v_lshl_add_u64 v[132:133], v[250:251], 0, s[38:39]
	s_mov_b32 m0, s5
	v_readfirstlane_b32 s5, v177
	global_load_lds_dwordx4 v[132:133], off
	v_lshl_add_u64 v[132:133], v[252:253], 0, s[38:39]
	s_mov_b32 m0, s5
	s_nop 0
	global_load_lds_dwordx4 v[132:133], off
	s_waitcnt vmcnt(6)
	s_barrier
	v_mfma_f32_16x16x32_bf16 v[32:35], v[230:233], v[198:201], v[32:35]
	v_mfma_f32_16x16x32_bf16 v[28:31], v[238:241], v[198:201], v[28:31]
	v_mfma_f32_16x16x32_bf16 v[24:27], v[230:233], v[206:209], v[24:27]
	v_mfma_f32_16x16x32_bf16 v[20:23], v[238:241], v[206:209], v[20:23]
	v_mfma_f32_16x16x32_bf16 v[16:19], v[230:233], v[214:217], v[16:19]
	v_mfma_f32_16x16x32_bf16 v[12:15], v[238:241], v[214:217], v[12:15]
	v_mfma_f32_16x16x32_bf16 v[8:11], v[230:233], v[222:225], v[8:11]
	v_mfma_f32_16x16x32_bf16 v[4:7], v[238:241], v[222:225], v[4:7]
	v_mfma_f32_16x16x32_bf16 v[32:35], v[234:237], v[202:205], v[32:35]
	v_mfma_f32_16x16x32_bf16 v[28:31], v[242:245], v[202:205], v[28:31]
	v_mfma_f32_16x16x32_bf16 v[24:27], v[234:237], v[210:213], v[24:27]
	v_mfma_f32_16x16x32_bf16 v[20:23], v[242:245], v[210:213], v[20:23]
	v_mfma_f32_16x16x32_bf16 v[16:19], v[234:237], v[218:221], v[16:19]
	v_mfma_f32_16x16x32_bf16 v[12:15], v[242:245], v[218:221], v[12:15]
	v_mfma_f32_16x16x32_bf16 v[8:11], v[234:237], v[226:229], v[8:11]
	v_mfma_f32_16x16x32_bf16 v[4:7], v[242:245], v[226:229], v[4:7]
	s_add_u32 s48, s48, 0x100
	s_addc_u32 s49, s49, 0
	s_cmp_gt_u32 s2, 11
	s_barrier
	s_cbranch_scc1 .LBB0_2802
	s_mov_b32 s2, s4
	s_cmp_lt_i32 s2, 12
	s_cbranch_scc1 .LBB0_2763

.LBB0_2916:
	ds_read_b128 v[180:183], v172
	ds_read_b128 v[184:187], v172 offset:1024
	ds_read_b128 v[188:191], v172 offset:2048
	ds_read_b128 v[192:195], v172 offset:3072
	v_add_u32_e32 v178, 0xc000, v152
	v_lshl_add_u64 v[244:245], s[6:7], 0, v[146:147]
	v_readfirstlane_b32 s4, v178
	v_add_u32_e32 v179, 0xe000, v152
	v_lshl_add_u64 v[224:225], v[244:245], 0, s[12:13]
	s_mov_b32 m0, s4
	v_lshl_add_u64 v[246:247], s[6:7], 0, v[148:149]
	v_readfirstlane_b32 s4, v179
	ds_read_b128 v[174:177], v161
	ds_read_b128 v[196:199], v161 offset:1024
	ds_read_b128 v[200:203], v160
	ds_read_b128 v[204:207], v160 offset:1024
	ds_read_b128 v[208:211], v159
	ds_read_b128 v[212:215], v159 offset:1024
	ds_read_b128 v[216:219], v158
	ds_read_b128 v[220:223], v158 offset:1024
	global_load_lds_dwordx4 v[224:225], off
	v_lshl_add_u64 v[224:225], v[246:247], 0, s[12:13]
	s_mov_b32 m0, s4
	s_nop 0
	global_load_lds_dwordx4 v[224:225], off
	s_barrier
	s_waitcnt lgkmcnt(0)
	v_mfma_f32_16x16x32_bf16 v[124:127], v[180:183], v[174:177], v[124:127]
	v_mfma_f32_16x16x32_bf16 v[120:123], v[188:191], v[174:177], v[120:123]
	v_mfma_f32_16x16x32_bf16 v[116:119], v[180:183], v[200:203], v[116:119]
	v_mfma_f32_16x16x32_bf16 v[112:115], v[188:191], v[200:203], v[112:115]
	v_mfma_f32_16x16x32_bf16 v[108:111], v[180:183], v[208:211], v[108:111]
	v_mfma_f32_16x16x32_bf16 v[104:107], v[188:191], v[208:211], v[104:107]
	v_mfma_f32_16x16x32_bf16 v[100:103], v[180:183], v[216:219], v[100:103]
	v_mfma_f32_16x16x32_bf16 v[96:99], v[188:191], v[216:219], v[96:99]
	v_mfma_f32_16x16x32_bf16 v[124:127], v[184:187], v[196:199], v[124:127]
	v_mfma_f32_16x16x32_bf16 v[120:123], v[192:195], v[196:199], v[120:123]
	v_mfma_f32_16x16x32_bf16 v[116:119], v[184:187], v[204:207], v[116:119]
	v_mfma_f32_16x16x32_bf16 v[112:115], v[192:195], v[204:207], v[112:115]
	v_mfma_f32_16x16x32_bf16 v[108:111], v[184:187], v[212:215], v[108:111]
	v_mfma_f32_16x16x32_bf16 v[104:107], v[192:195], v[212:215], v[104:107]
	v_mfma_f32_16x16x32_bf16 v[100:103], v[184:187], v[220:223], v[100:103]
	v_mfma_f32_16x16x32_bf16 v[96:99], v[192:195], v[220:223], v[96:99]
	s_barrier
	v_lshl_add_u64 v[248:249], s[6:7], 0, v[142:143]
	v_readfirstlane_b32 s4, v153
	v_add_u32_e32 v173, 0x2000, v153
	v_lshl_add_u64 v[240:241], v[248:249], 0, s[14:15]
	s_mov_b32 m0, s4
	v_lshl_add_u64 v[250:251], s[6:7], 0, v[144:145]
	v_readfirstlane_b32 s4, v173
	ds_read_b128 v[224:227], v168
	ds_read_b128 v[228:231], v168 offset:1024
	ds_read_b128 v[232:235], v168 offset:2048
	ds_read_b128 v[236:239], v168 offset:3072
	global_load_lds_dwordx4 v[240:241], off
	v_lshl_add_u64 v[240:241], v[250:251], 0, s[14:15]
	s_mov_b32 m0, s4
	s_nop 0
	global_load_lds_dwordx4 v[240:241], off
	s_barrier
	s_waitcnt lgkmcnt(0)
	v_mfma_f32_16x16x32_bf16 v[92:95], v[224:227], v[174:177], v[92:95]
	v_mfma_f32_16x16x32_bf16 v[88:91], v[232:235], v[174:177], v[88:91]
	v_mfma_f32_16x16x32_bf16 v[84:87], v[224:227], v[200:203], v[84:87]
	v_mfma_f32_16x16x32_bf16 v[80:83], v[232:235], v[200:203], v[80:83]
	v_mfma_f32_16x16x32_bf16 v[76:79], v[224:227], v[208:211], v[76:79]
	v_mfma_f32_16x16x32_bf16 v[72:75], v[232:235], v[208:211], v[72:75]
	v_mfma_f32_16x16x32_bf16 v[68:71], v[224:227], v[216:219], v[68:71]
	v_mfma_f32_16x16x32_bf16 v[64:67], v[232:235], v[216:219], v[64:67]
	v_mfma_f32_16x16x32_bf16 v[92:95], v[228:231], v[196:199], v[92:95]
	v_mfma_f32_16x16x32_bf16 v[88:91], v[236:239], v[196:199], v[88:91]
	v_mfma_f32_16x16x32_bf16 v[84:87], v[228:231], v[204:207], v[84:87]
	v_mfma_f32_16x16x32_bf16 v[80:83], v[236:239], v[204:207], v[80:83]
	v_mfma_f32_16x16x32_bf16 v[76:79], v[228:231], v[212:215], v[76:79]
	v_mfma_f32_16x16x32_bf16 v[72:75], v[236:239], v[212:215], v[72:75]
	v_mfma_f32_16x16x32_bf16 v[68:71], v[228:231], v[220:223], v[68:71]
	v_mfma_f32_16x16x32_bf16 v[64:67], v[236:239], v[220:223], v[64:67]
	v_readfirstlane_b32 s4, v152
	v_lshl_add_u64 v[174:175], v[244:245], 0, s[16:17]
	s_mov_b32 m0, s4
	s_barrier
	ds_read_b128 v[196:199], v161 offset:16384
	ds_read_b128 v[200:203], v161 offset:17408
	ds_read_b128 v[204:207], v160 offset:16384
	ds_read_b128 v[208:211], v160 offset:17408
	ds_read_b128 v[212:215], v159 offset:16384
	ds_read_b128 v[216:219], v159 offset:17408
	ds_read_b128 v[220:223], v158 offset:16384
	ds_read_b128 v[240:243], v158 offset:17408
	global_load_lds_dwordx4 v[174:175], off
	v_add_u32_e32 v174, 0x2000, v152
	v_lshl_add_u64 v[176:177], v[246:247], 0, s[16:17]
	v_readfirstlane_b32 s4, v174
	s_mov_b32 m0, s4
	s_nop 0
	global_load_lds_dwordx4 v[176:177], off
	s_barrier
	s_waitcnt lgkmcnt(0)
	v_mfma_f32_16x16x32_bf16 v[60:63], v[180:183], v[196:199], v[60:63]
	v_mfma_f32_16x16x32_bf16 v[56:59], v[188:191], v[196:199], v[56:59]
	v_mfma_f32_16x16x32_bf16 v[52:55], v[180:183], v[204:207], v[52:55]
	v_mfma_f32_16x16x32_bf16 v[48:51], v[188:191], v[204:207], v[48:51]
	v_mfma_f32_16x16x32_bf16 v[44:47], v[180:183], v[212:215], v[44:47]
	v_mfma_f32_16x16x32_bf16 v[40:43], v[188:191], v[212:215], v[40:43]
	v_mfma_f32_16x16x32_bf16 v[36:39], v[180:183], v[220:223], v[36:39]
	v_mfma_f32_16x16x32_bf16 v[32:35], v[188:191], v[220:223], v[32:35]
	v_mfma_f32_16x16x32_bf16 v[60:63], v[184:187], v[200:203], v[60:63]
	v_mfma_f32_16x16x32_bf16 v[56:59], v[192:195], v[200:203], v[56:59]
	v_mfma_f32_16x16x32_bf16 v[52:55], v[184:187], v[208:211], v[52:55]
	v_mfma_f32_16x16x32_bf16 v[48:51], v[192:195], v[208:211], v[48:51]
	v_mfma_f32_16x16x32_bf16 v[44:47], v[184:187], v[216:219], v[44:47]
	v_mfma_f32_16x16x32_bf16 v[40:43], v[192:195], v[216:219], v[40:43]
	v_mfma_f32_16x16x32_bf16 v[36:39], v[184:187], v[240:243], v[36:39]
	v_mfma_f32_16x16x32_bf16 v[32:35], v[192:195], v[240:243], v[32:35]
	s_barrier
	v_readfirstlane_b32 s4, v151
	v_add_u32_e32 v175, 0x2000, v151
	v_lshl_add_u64 v[176:177], v[248:249], 0, s[18:19]
	s_mov_b32 m0, s4
	v_readfirstlane_b32 s4, v175
	global_load_lds_dwordx4 v[176:177], off
	v_lshl_add_u64 v[176:177], v[250:251], 0, s[18:19]
	s_mov_b32 m0, s4
	s_nop 0
	global_load_lds_dwordx4 v[176:177], off
	s_waitcnt vmcnt(6)
	s_barrier
	v_mfma_f32_16x16x32_bf16 v[28:31], v[224:227], v[196:199], v[28:31]
	v_mfma_f32_16x16x32_bf16 v[24:27], v[232:235], v[196:199], v[24:27]
	v_mfma_f32_16x16x32_bf16 v[20:23], v[224:227], v[204:207], v[20:23]
	v_mfma_f32_16x16x32_bf16 v[16:19], v[232:235], v[204:207], v[16:19]
	v_mfma_f32_16x16x32_bf16 v[12:15], v[224:227], v[212:215], v[12:15]
	v_mfma_f32_16x16x32_bf16 v[8:11], v[232:235], v[212:215], v[8:11]
	v_mfma_f32_16x16x32_bf16 v[4:7], v[224:227], v[220:223], v[4:7]
	v_mfma_f32_16x16x32_bf16 v[0:3], v[232:235], v[220:223], v[0:3]
	v_mfma_f32_16x16x32_bf16 v[28:31], v[228:231], v[200:203], v[28:31]
	v_mfma_f32_16x16x32_bf16 v[24:27], v[236:239], v[200:203], v[24:27]
	v_mfma_f32_16x16x32_bf16 v[20:23], v[228:231], v[208:211], v[20:23]
	v_mfma_f32_16x16x32_bf16 v[16:19], v[236:239], v[208:211], v[16:19]
	v_mfma_f32_16x16x32_bf16 v[12:15], v[228:231], v[216:219], v[12:15]
	v_mfma_f32_16x16x32_bf16 v[8:11], v[236:239], v[216:219], v[8:11]
	v_mfma_f32_16x16x32_bf16 v[4:7], v[228:231], v[240:243], v[4:7]
	v_mfma_f32_16x16x32_bf16 v[0:3], v[236:239], v[240:243], v[0:3]
	s_barrier
	ds_read_b128 v[180:183], v163
	ds_read_b128 v[184:187], v163 offset:1024
	ds_read_b128 v[188:191], v163 offset:2048
	ds_read_b128 v[192:195], v163 offset:3072
	v_add_u32_e32 v176, 0x4000, v152
	v_add_u32_e32 v177, 0x6000, v152
	v_readfirstlane_b32 s4, v176
	v_lshl_add_u64 v[228:229], v[244:245], 0, s[20:21]
	s_mov_b32 m0, s4
	v_readfirstlane_b32 s4, v177
	ds_read_b128 v[196:199], v161 offset:32768
	ds_read_b128 v[200:203], v161 offset:33792
	ds_read_b128 v[204:207], v160 offset:32768
	ds_read_b128 v[208:211], v160 offset:33792
	ds_read_b128 v[212:215], v159 offset:32768
	ds_read_b128 v[216:219], v159 offset:33792
	ds_read_b128 v[220:223], v158 offset:32768
	ds_read_b128 v[224:227], v158 offset:33792
	global_load_lds_dwordx4 v[228:229], off
	v_lshl_add_u64 v[228:229], v[246:247], 0, s[20:21]
	s_mov_b32 m0, s4
	s_nop 0
	global_load_lds_dwordx4 v[228:229], off
	s_barrier
	s_waitcnt lgkmcnt(0)
	v_mfma_f32_16x16x32_bf16 v[124:127], v[180:183], v[196:199], v[124:127]
	v_mfma_f32_16x16x32_bf16 v[120:123], v[188:191], v[196:199], v[120:123]
	v_mfma_f32_16x16x32_bf16 v[116:119], v[180:183], v[204:207], v[116:119]
	v_mfma_f32_16x16x32_bf16 v[112:115], v[188:191], v[204:207], v[112:115]
	v_mfma_f32_16x16x32_bf16 v[108:111], v[180:183], v[212:215], v[108:111]
	v_mfma_f32_16x16x32_bf16 v[104:107], v[188:191], v[212:215], v[104:107]
	v_mfma_f32_16x16x32_bf16 v[100:103], v[180:183], v[220:223], v[100:103]
	v_mfma_f32_16x16x32_bf16 v[96:99], v[188:191], v[220:223], v[96:99]
	v_mfma_f32_16x16x32_bf16 v[124:127], v[184:187], v[200:203], v[124:127]
	v_mfma_f32_16x16x32_bf16 v[120:123], v[192:195], v[200:203], v[120:123]
	v_mfma_f32_16x16x32_bf16 v[116:119], v[184:187], v[208:211], v[116:119]
	v_mfma_f32_16x16x32_bf16 v[112:115], v[192:195], v[208:211], v[112:115]
	v_mfma_f32_16x16x32_bf16 v[108:111], v[184:187], v[216:219], v[108:111]
	v_mfma_f32_16x16x32_bf16 v[104:107], v[192:195], v[216:219], v[104:107]
	v_mfma_f32_16x16x32_bf16 v[100:103], v[184:187], v[224:227], v[100:103]
	v_mfma_f32_16x16x32_bf16 v[96:99], v[192:195], v[224:227], v[96:99]
	s_barrier
	v_readfirstlane_b32 s4, v167
	v_add_u32_e32 v254, 0x2000, v167
	v_lshl_add_u64 v[252:253], v[248:249], 0, s[24:25]
	s_mov_b32 m0, s4
	v_readfirstlane_b32 s4, v254
	ds_read_b128 v[228:231], v162
	ds_read_b128 v[232:235], v162 offset:1024
	ds_read_b128 v[236:239], v162 offset:2048
	ds_read_b128 v[240:243], v162 offset:3072
	global_load_lds_dwordx4 v[252:253], off
	v_lshl_add_u64 v[252:253], v[250:251], 0, s[24:25]
	s_mov_b32 m0, s4
	s_nop 0
	global_load_lds_dwordx4 v[252:253], off
	s_barrier
	s_waitcnt lgkmcnt(0)
	v_mfma_f32_16x16x32_bf16 v[92:95], v[228:231], v[196:199], v[92:95]
	v_mfma_f32_16x16x32_bf16 v[88:91], v[236:239], v[196:199], v[88:91]
	v_mfma_f32_16x16x32_bf16 v[84:87], v[228:231], v[204:207], v[84:87]
	v_mfma_f32_16x16x32_bf16 v[80:83], v[236:239], v[204:207], v[80:83]
	v_mfma_f32_16x16x32_bf16 v[76:79], v[228:231], v[212:215], v[76:79]
	v_mfma_f32_16x16x32_bf16 v[72:75], v[236:239], v[212:215], v[72:75]
	v_mfma_f32_16x16x32_bf16 v[68:71], v[228:231], v[220:223], v[68:71]
	v_mfma_f32_16x16x32_bf16 v[64:67], v[236:239], v[220:223], v[64:67]
	v_mfma_f32_16x16x32_bf16 v[92:95], v[232:235], v[200:203], v[92:95]
	v_mfma_f32_16x16x32_bf16 v[88:91], v[240:243], v[200:203], v[88:91]
	v_mfma_f32_16x16x32_bf16 v[84:87], v[232:235], v[208:211], v[84:87]
	v_mfma_f32_16x16x32_bf16 v[80:83], v[240:243], v[208:211], v[80:83]
	v_mfma_f32_16x16x32_bf16 v[76:79], v[232:235], v[216:219], v[76:79]
	v_mfma_f32_16x16x32_bf16 v[72:75], v[240:243], v[216:219], v[72:75]
	v_mfma_f32_16x16x32_bf16 v[68:71], v[232:235], v[224:227], v[68:71]
	v_mfma_f32_16x16x32_bf16 v[64:67], v[240:243], v[224:227], v[64:67]
	v_readfirstlane_b32 s4, v169
	v_lshl_add_u64 v[244:245], v[244:245], 0, s[26:27]
	s_mov_b32 m0, s4
	v_readfirstlane_b32 s4, v170
	s_barrier
	ds_read_b128 v[196:199], v161 offset:49152
	ds_read_b128 v[200:203], v161 offset:50176
	ds_read_b128 v[204:207], v160 offset:49152
	ds_read_b128 v[208:211], v160 offset:50176
	ds_read_b128 v[212:215], v159 offset:49152
	ds_read_b128 v[216:219], v159 offset:50176
	ds_read_b128 v[220:223], v158 offset:49152
	ds_read_b128 v[224:227], v158 offset:50176
	global_load_lds_dwordx4 v[244:245], off
	v_lshl_add_u64 v[244:245], v[246:247], 0, s[26:27]
	s_mov_b32 m0, s4
	s_nop 0
	global_load_lds_dwordx4 v[244:245], off
	s_barrier
	s_waitcnt lgkmcnt(0)
	v_mfma_f32_16x16x32_bf16 v[60:63], v[180:183], v[196:199], v[60:63]
	v_mfma_f32_16x16x32_bf16 v[56:59], v[188:191], v[196:199], v[56:59]
	v_mfma_f32_16x16x32_bf16 v[52:55], v[180:183], v[204:207], v[52:55]
	v_mfma_f32_16x16x32_bf16 v[48:51], v[188:191], v[204:207], v[48:51]
	v_mfma_f32_16x16x32_bf16 v[44:47], v[180:183], v[212:215], v[44:47]
	v_mfma_f32_16x16x32_bf16 v[40:43], v[188:191], v[212:215], v[40:43]
	v_mfma_f32_16x16x32_bf16 v[36:39], v[180:183], v[220:223], v[36:39]
	v_mfma_f32_16x16x32_bf16 v[32:35], v[188:191], v[220:223], v[32:35]
	v_mfma_f32_16x16x32_bf16 v[60:63], v[184:187], v[200:203], v[60:63]
	v_mfma_f32_16x16x32_bf16 v[56:59], v[192:195], v[200:203], v[56:59]
	v_mfma_f32_16x16x32_bf16 v[52:55], v[184:187], v[208:211], v[52:55]
	v_mfma_f32_16x16x32_bf16 v[48:51], v[192:195], v[208:211], v[48:51]
	v_mfma_f32_16x16x32_bf16 v[44:47], v[184:187], v[216:219], v[44:47]
	v_mfma_f32_16x16x32_bf16 v[40:43], v[192:195], v[216:219], v[40:43]
	v_mfma_f32_16x16x32_bf16 v[36:39], v[184:187], v[224:227], v[36:39]
	v_mfma_f32_16x16x32_bf16 v[32:35], v[192:195], v[224:227], v[32:35]
	s_barrier
	v_readfirstlane_b32 s4, v171
	v_add_u32_e32 v182, 0x2000, v171
	v_lshl_add_u64 v[180:181], v[248:249], 0, s[28:29]
	s_mov_b32 m0, s4
	v_readfirstlane_b32 s4, v182
	global_load_lds_dwordx4 v[180:181], off
	v_lshl_add_u64 v[180:181], v[250:251], 0, s[28:29]
	s_mov_b32 m0, s4
	s_nop 0
	global_load_lds_dwordx4 v[180:181], off
	s_waitcnt vmcnt(6)
	s_barrier
	v_mfma_f32_16x16x32_bf16 v[28:31], v[228:231], v[196:199], v[28:31]
	v_mfma_f32_16x16x32_bf16 v[24:27], v[236:239], v[196:199], v[24:27]
	v_mfma_f32_16x16x32_bf16 v[20:23], v[228:231], v[204:207], v[20:23]
	v_mfma_f32_16x16x32_bf16 v[16:19], v[236:239], v[204:207], v[16:19]
	v_mfma_f32_16x16x32_bf16 v[12:15], v[228:231], v[212:215], v[12:15]
	v_mfma_f32_16x16x32_bf16 v[8:11], v[236:239], v[212:215], v[8:11]
	v_mfma_f32_16x16x32_bf16 v[4:7], v[228:231], v[220:223], v[4:7]
	v_mfma_f32_16x16x32_bf16 v[0:3], v[236:239], v[220:223], v[0:3]
	v_mfma_f32_16x16x32_bf16 v[28:31], v[232:235], v[200:203], v[28:31]
	v_mfma_f32_16x16x32_bf16 v[24:27], v[240:243], v[200:203], v[24:27]
	v_mfma_f32_16x16x32_bf16 v[20:23], v[232:235], v[208:211], v[20:23]
	v_mfma_f32_16x16x32_bf16 v[16:19], v[240:243], v[208:211], v[16:19]
	v_mfma_f32_16x16x32_bf16 v[12:15], v[232:235], v[216:219], v[12:15]
	v_mfma_f32_16x16x32_bf16 v[8:11], v[240:243], v[216:219], v[8:11]
	v_mfma_f32_16x16x32_bf16 v[4:7], v[232:235], v[224:227], v[4:7]
	v_mfma_f32_16x16x32_bf16 v[0:3], v[240:243], v[224:227], v[0:3]
	s_add_i32 s2, s2, 2
	v_lshl_add_u64 v[142:143], v[142:143], 0, s[30:31]
	v_lshl_add_u64 v[144:145], v[144:145], 0, s[30:31]
	v_lshl_add_u64 v[146:147], v[146:147], 0, s[30:31]
	s_cmp_lt_u32 s2, 12
	v_lshl_add_u64 v[148:149], v[148:149], 0, s[30:31]
	s_barrier
	s_cbranch_scc1 .LBB0_2916
	s_or_b32 s4, s36, 0x80
	s_ashr_i32 s5, s4, 31
	s_lshl_b64 s[4:5], s[4:5], 11
	s_add_u32 s4, s1, s4
	s_addc_u32 s5, s23, s5
	v_lshl_add_u64 v[170:171], s[4:5], 0, v[130:131]
	v_lshl_add_u64 v[138:139], v[138:139], 1, v[170:171]
	v_readfirstlane_b32 s2, v178
	v_lshl_add_u64 v[138:139], v[138:139], 0, s[34:35]
	s_mov_b32 m0, s2
	ds_read_b128 v[142:145], v172
	ds_read_b128 v[146:149], v172 offset:1024
	ds_read_b128 v[180:183], v172 offset:2048
	ds_read_b128 v[184:187], v172 offset:3072
	ds_read_b128 v[188:191], v161
	ds_read_b128 v[192:195], v161 offset:1024
	ds_read_b128 v[196:199], v160
	ds_read_b128 v[200:203], v160 offset:1024
	ds_read_b128 v[204:207], v159
	ds_read_b128 v[208:211], v159 offset:1024
	ds_read_b128 v[212:215], v158
	ds_read_b128 v[216:219], v158 offset:1024
	global_load_lds_dwordx4 v[138:139], off
	v_lshl_add_u64 v[138:139], s[4:5], 0, v[134:135]
	v_lshl_add_u64 v[138:139], v[140:141], 1, v[138:139]
	v_readfirstlane_b32 s2, v179
	v_lshl_add_u64 v[138:139], v[138:139], 0, s[34:35]
	s_mov_b32 m0, s2
	v_readlane_b32 s2, v255, 11
	global_load_lds_dwordx4 v[138:139], off
	s_add_i32 s60, s60, s2
	s_barrier
	s_waitcnt lgkmcnt(0)
	s_cmpk_gt_i32 s60, 0x7f
	s_cselect_b64 s[38:39], -1, 0
	s_waitcnt lgkmcnt(0)
	v_mfma_f32_16x16x32_bf16 v[124:127], v[142:145], v[188:191], v[124:127]
	v_mfma_f32_16x16x32_bf16 v[120:123], v[180:183], v[188:191], v[120:123]
	v_mfma_f32_16x16x32_bf16 v[116:119], v[142:145], v[196:199], v[116:119]
	v_mfma_f32_16x16x32_bf16 v[112:115], v[180:183], v[196:199], v[112:115]
	v_mfma_f32_16x16x32_bf16 v[108:111], v[142:145], v[204:207], v[108:111]
	v_mfma_f32_16x16x32_bf16 v[104:107], v[180:183], v[204:207], v[104:107]
	v_mfma_f32_16x16x32_bf16 v[100:103], v[142:145], v[212:215], v[100:103]
	v_mfma_f32_16x16x32_bf16 v[96:99], v[180:183], v[212:215], v[96:99]
	v_mfma_f32_16x16x32_bf16 v[124:127], v[146:149], v[192:195], v[124:127]
	v_mfma_f32_16x16x32_bf16 v[120:123], v[184:187], v[192:195], v[120:123]
	v_mfma_f32_16x16x32_bf16 v[116:119], v[146:149], v[200:203], v[116:119]
	v_mfma_f32_16x16x32_bf16 v[112:115], v[184:187], v[200:203], v[112:115]
	v_mfma_f32_16x16x32_bf16 v[108:111], v[146:149], v[208:211], v[108:111]
	v_mfma_f32_16x16x32_bf16 v[104:107], v[184:187], v[208:211], v[104:107]
	v_mfma_f32_16x16x32_bf16 v[100:103], v[146:149], v[216:219], v[100:103]
	v_mfma_f32_16x16x32_bf16 v[96:99], v[184:187], v[216:219], v[96:99]
	s_barrier
	ds_read_b128 v[138:141], v168
	ds_read_b128 v[220:223], v168 offset:1024
	ds_read_b128 v[224:227], v168 offset:2048
	ds_read_b128 v[168:171], v168 offset:3072
	s_barrier
	s_waitcnt lgkmcnt(0)
	v_mfma_f32_16x16x32_bf16 v[92:95], v[138:141], v[188:191], v[92:95]
	v_mfma_f32_16x16x32_bf16 v[88:91], v[224:227], v[188:191], v[88:91]
	v_mfma_f32_16x16x32_bf16 v[84:87], v[138:141], v[196:199], v[84:87]
	v_mfma_f32_16x16x32_bf16 v[80:83], v[224:227], v[196:199], v[80:83]
	v_mfma_f32_16x16x32_bf16 v[76:79], v[138:141], v[204:207], v[76:79]
	v_mfma_f32_16x16x32_bf16 v[72:75], v[224:227], v[204:207], v[72:75]
	v_mfma_f32_16x16x32_bf16 v[68:71], v[138:141], v[212:215], v[68:71]
	v_mfma_f32_16x16x32_bf16 v[64:67], v[224:227], v[212:215], v[64:67]
	v_mfma_f32_16x16x32_bf16 v[92:95], v[220:223], v[192:195], v[92:95]
	v_mfma_f32_16x16x32_bf16 v[88:91], v[168:171], v[192:195], v[88:91]
	v_mfma_f32_16x16x32_bf16 v[84:87], v[220:223], v[200:203], v[84:87]
	v_mfma_f32_16x16x32_bf16 v[80:83], v[168:171], v[200:203], v[80:83]
	v_mfma_f32_16x16x32_bf16 v[76:79], v[220:223], v[208:211], v[76:79]
	v_mfma_f32_16x16x32_bf16 v[72:75], v[168:171], v[208:211], v[72:75]
	v_mfma_f32_16x16x32_bf16 v[68:71], v[220:223], v[216:219], v[68:71]
	v_mfma_f32_16x16x32_bf16 v[64:67], v[168:171], v[216:219], v[64:67]
	s_barrier
	ds_read_b128 v[188:191], v161 offset:16384
	ds_read_b128 v[192:195], v161 offset:17408
	ds_read_b128 v[196:199], v160 offset:16384
	ds_read_b128 v[200:203], v160 offset:17408
	ds_read_b128 v[204:207], v159 offset:16384
	ds_read_b128 v[208:211], v159 offset:17408
	ds_read_b128 v[212:215], v158 offset:16384
	ds_read_b128 v[216:219], v158 offset:17408
	s_waitcnt vmcnt(4)
	s_barrier
	s_waitcnt lgkmcnt(0)
	v_mfma_f32_16x16x32_bf16 v[60:63], v[142:145], v[188:191], v[60:63]
	v_mfma_f32_16x16x32_bf16 v[56:59], v[180:183], v[188:191], v[56:59]
	v_mfma_f32_16x16x32_bf16 v[52:55], v[142:145], v[196:199], v[52:55]
	v_mfma_f32_16x16x32_bf16 v[48:51], v[180:183], v[196:199], v[48:51]
	v_mfma_f32_16x16x32_bf16 v[44:47], v[142:145], v[204:207], v[44:47]
	v_mfma_f32_16x16x32_bf16 v[40:43], v[180:183], v[204:207], v[40:43]
	v_mfma_f32_16x16x32_bf16 v[36:39], v[142:145], v[212:215], v[36:39]
	v_mfma_f32_16x16x32_bf16 v[32:35], v[180:183], v[212:215], v[32:35]
	v_mfma_f32_16x16x32_bf16 v[60:63], v[146:149], v[192:195], v[60:63]
	v_mfma_f32_16x16x32_bf16 v[56:59], v[184:187], v[192:195], v[56:59]
	v_mfma_f32_16x16x32_bf16 v[52:55], v[146:149], v[200:203], v[52:55]
	v_mfma_f32_16x16x32_bf16 v[48:51], v[184:187], v[200:203], v[48:51]
	v_mfma_f32_16x16x32_bf16 v[44:47], v[146:149], v[208:211], v[44:47]
	v_mfma_f32_16x16x32_bf16 v[40:43], v[184:187], v[208:211], v[40:43]
	v_mfma_f32_16x16x32_bf16 v[36:39], v[146:149], v[216:219], v[36:39]
	v_mfma_f32_16x16x32_bf16 v[32:35], v[184:187], v[216:219], v[32:35]
	v_mfma_f32_16x16x32_bf16 v[28:31], v[138:141], v[188:191], v[28:31]
	v_mfma_f32_16x16x32_bf16 v[24:27], v[224:227], v[188:191], v[24:27]
	v_mfma_f32_16x16x32_bf16 v[20:23], v[138:141], v[196:199], v[20:23]
	v_mfma_f32_16x16x32_bf16 v[16:19], v[224:227], v[196:199], v[16:19]
	v_mfma_f32_16x16x32_bf16 v[12:15], v[138:141], v[204:207], v[12:15]
	v_mfma_f32_16x16x32_bf16 v[8:11], v[224:227], v[204:207], v[8:11]
	v_mfma_f32_16x16x32_bf16 v[4:7], v[138:141], v[212:215], v[4:7]
	v_mfma_f32_16x16x32_bf16 v[0:3], v[224:227], v[212:215], v[0:3]
	v_mfma_f32_16x16x32_bf16 v[28:31], v[220:223], v[192:195], v[28:31]
	v_mfma_f32_16x16x32_bf16 v[24:27], v[168:171], v[192:195], v[24:27]
	v_mfma_f32_16x16x32_bf16 v[20:23], v[220:223], v[200:203], v[20:23]
	v_mfma_f32_16x16x32_bf16 v[16:19], v[168:171], v[200:203], v[16:19]
	v_mfma_f32_16x16x32_bf16 v[12:15], v[220:223], v[208:211], v[12:15]
	v_mfma_f32_16x16x32_bf16 v[8:11], v[168:171], v[208:211], v[8:11]
	v_mfma_f32_16x16x32_bf16 v[4:7], v[220:223], v[216:219], v[4:7]
	v_mfma_f32_16x16x32_bf16 v[0:3], v[168:171], v[216:219], v[0:3]
	s_barrier
	ds_read_b128 v[138:141], v163
	ds_read_b128 v[142:145], v163 offset:1024
	ds_read_b128 v[146:149], v163 offset:2048
	ds_read_b128 v[168:171], v163 offset:3072
	ds_read_b128 v[178:181], v161 offset:32768
	ds_read_b128 v[182:185], v161 offset:33792
	ds_read_b128 v[186:189], v160 offset:32768
	ds_read_b128 v[190:193], v160 offset:33792
	ds_read_b128 v[194:197], v159 offset:32768
	ds_read_b128 v[198:201], v159 offset:33792
	ds_read_b128 v[202:205], v158 offset:32768
	ds_read_b128 v[206:209], v158 offset:33792
	s_waitcnt vmcnt(2)
	s_barrier
	s_waitcnt lgkmcnt(0)
	v_mfma_f32_16x16x32_bf16 v[124:127], v[138:141], v[178:181], v[124:127]
	v_mfma_f32_16x16x32_bf16 v[120:123], v[146:149], v[178:181], v[120:123]
	v_mfma_f32_16x16x32_bf16 v[116:119], v[138:141], v[186:189], v[116:119]
	v_mfma_f32_16x16x32_bf16 v[112:115], v[146:149], v[186:189], v[112:115]
	v_mfma_f32_16x16x32_bf16 v[108:111], v[138:141], v[194:197], v[108:111]
	v_mfma_f32_16x16x32_bf16 v[104:107], v[146:149], v[194:197], v[104:107]
	v_mfma_f32_16x16x32_bf16 v[100:103], v[138:141], v[202:205], v[100:103]
	v_mfma_f32_16x16x32_bf16 v[96:99], v[146:149], v[202:205], v[96:99]
	v_mfma_f32_16x16x32_bf16 v[124:127], v[142:145], v[182:185], v[124:127]
	v_mfma_f32_16x16x32_bf16 v[120:123], v[168:171], v[182:185], v[120:123]
	v_mfma_f32_16x16x32_bf16 v[116:119], v[142:145], v[190:193], v[116:119]
	v_mfma_f32_16x16x32_bf16 v[112:115], v[168:171], v[190:193], v[112:115]
	v_mfma_f32_16x16x32_bf16 v[108:111], v[142:145], v[198:201], v[108:111]
	v_mfma_f32_16x16x32_bf16 v[104:107], v[168:171], v[198:201], v[104:107]
	v_mfma_f32_16x16x32_bf16 v[100:103], v[142:145], v[206:209], v[100:103]
	v_mfma_f32_16x16x32_bf16 v[96:99], v[168:171], v[206:209], v[96:99]
	s_barrier
	ds_read_b128 v[210:213], v162
	ds_read_b128 v[214:217], v162 offset:1024
	ds_read_b128 v[218:221], v162 offset:2048
	ds_read_b128 v[222:225], v162 offset:3072
	s_waitcnt vmcnt(0)
	s_barrier
	s_waitcnt lgkmcnt(0)
	v_mfma_f32_16x16x32_bf16 v[92:95], v[210:213], v[178:181], v[92:95]
	v_mfma_f32_16x16x32_bf16 v[88:91], v[218:221], v[178:181], v[88:91]
	v_mfma_f32_16x16x32_bf16 v[84:87], v[210:213], v[186:189], v[84:87]
	v_mfma_f32_16x16x32_bf16 v[80:83], v[218:221], v[186:189], v[80:83]
	v_mfma_f32_16x16x32_bf16 v[76:79], v[210:213], v[194:197], v[76:79]
	v_mfma_f32_16x16x32_bf16 v[72:75], v[218:221], v[194:197], v[72:75]
	v_mfma_f32_16x16x32_bf16 v[68:71], v[210:213], v[202:205], v[68:71]
	v_mfma_f32_16x16x32_bf16 v[64:67], v[218:221], v[202:205], v[64:67]
	v_mfma_f32_16x16x32_bf16 v[92:95], v[214:217], v[182:185], v[92:95]
	v_mfma_f32_16x16x32_bf16 v[88:91], v[222:225], v[182:185], v[88:91]
	v_mfma_f32_16x16x32_bf16 v[84:87], v[214:217], v[190:193], v[84:87]
	v_mfma_f32_16x16x32_bf16 v[80:83], v[222:225], v[190:193], v[80:83]
	v_mfma_f32_16x16x32_bf16 v[76:79], v[214:217], v[198:201], v[76:79]
	v_mfma_f32_16x16x32_bf16 v[72:75], v[222:225], v[198:201], v[72:75]
	v_mfma_f32_16x16x32_bf16 v[68:71], v[214:217], v[206:209], v[68:71]
	v_mfma_f32_16x16x32_bf16 v[64:67], v[222:225], v[206:209], v[64:67]
	s_barrier
	ds_read_b128 v[178:181], v161 offset:49152
	ds_read_b128 v[182:185], v161 offset:50176
	ds_read_b128 v[186:189], v160 offset:49152
	ds_read_b128 v[160:163], v160 offset:50176
	ds_read_b128 v[190:193], v159 offset:49152
	ds_read_b128 v[194:197], v159 offset:50176
	ds_read_b128 v[198:201], v158 offset:49152
	ds_read_b128 v[202:205], v158 offset:50176
	s_barrier
	s_waitcnt lgkmcnt(0)
	v_mfma_f32_16x16x32_bf16 v[60:63], v[138:141], v[178:181], v[60:63]
	v_mfma_f32_16x16x32_bf16 v[56:59], v[146:149], v[178:181], v[56:59]
	v_mfma_f32_16x16x32_bf16 v[52:55], v[138:141], v[186:189], v[52:55]
	v_mfma_f32_16x16x32_bf16 v[48:51], v[146:149], v[186:189], v[48:51]
	v_mfma_f32_16x16x32_bf16 v[44:47], v[138:141], v[190:193], v[44:47]
	v_mfma_f32_16x16x32_bf16 v[40:43], v[146:149], v[190:193], v[40:43]
	v_mfma_f32_16x16x32_bf16 v[36:39], v[138:141], v[198:201], v[36:39]
	v_mfma_f32_16x16x32_bf16 v[32:35], v[146:149], v[198:201], v[32:35]
	v_mfma_f32_16x16x32_bf16 v[60:63], v[142:145], v[182:185], v[60:63]
	v_mfma_f32_16x16x32_bf16 v[56:59], v[168:171], v[182:185], v[56:59]
	v_mfma_f32_16x16x32_bf16 v[52:55], v[142:145], v[160:163], v[52:55]
	v_mfma_f32_16x16x32_bf16 v[48:51], v[168:171], v[160:163], v[48:51]
	v_mfma_f32_16x16x32_bf16 v[44:47], v[142:145], v[194:197], v[44:47]
	v_mfma_f32_16x16x32_bf16 v[40:43], v[168:171], v[194:197], v[40:43]
	v_mfma_f32_16x16x32_bf16 v[36:39], v[142:145], v[202:205], v[36:39]
	v_mfma_f32_16x16x32_bf16 v[32:35], v[168:171], v[202:205], v[32:35]
	v_mfma_f32_16x16x32_bf16 v[28:31], v[210:213], v[178:181], v[28:31]
	v_mfma_f32_16x16x32_bf16 v[24:27], v[218:221], v[178:181], v[24:27]
	v_mfma_f32_16x16x32_bf16 v[20:23], v[210:213], v[186:189], v[20:23]
	v_mfma_f32_16x16x32_bf16 v[16:19], v[218:221], v[186:189], v[16:19]
	v_mfma_f32_16x16x32_bf16 v[12:15], v[210:213], v[190:193], v[12:15]
	v_mfma_f32_16x16x32_bf16 v[8:11], v[218:221], v[190:193], v[8:11]
	v_mfma_f32_16x16x32_bf16 v[4:7], v[210:213], v[198:201], v[4:7]
	v_mfma_f32_16x16x32_bf16 v[0:3], v[218:221], v[198:201], v[0:3]
	v_mfma_f32_16x16x32_bf16 v[28:31], v[214:217], v[182:185], v[28:31]
	v_mfma_f32_16x16x32_bf16 v[24:27], v[222:225], v[182:185], v[24:27]
	v_mfma_f32_16x16x32_bf16 v[20:23], v[214:217], v[160:163], v[20:23]
	v_mfma_f32_16x16x32_bf16 v[16:19], v[222:225], v[160:163], v[16:19]
	v_mfma_f32_16x16x32_bf16 v[12:15], v[214:217], v[194:197], v[12:15]
	v_mfma_f32_16x16x32_bf16 v[8:11], v[222:225], v[194:197], v[8:11]
	v_mfma_f32_16x16x32_bf16 v[4:7], v[214:217], v[202:205], v[4:7]
	v_mfma_f32_16x16x32_bf16 v[0:3], v[222:225], v[202:205], v[0:3]
	s_and_b64 vcc, exec, s[38:39]
	s_barrier
	s_cbranch_vccnz .LBB0_2919
	s_lshr_b32 s2, s60, 2
	s_and_b32 s4, s60, 3
	s_add_i32 s2, s2, s56
	s_or_b32 s5, s4, s53
	s_lshl_b32 s4, s2, 8
	s_lshl_b32 s2, s5, 19
	s_add_u32 s42, s40, s2
	s_addc_u32 s43, s46, 0
	v_lshl_add_u64 v[138:139], s[42:43], 0, v[130:131]
	v_readfirstlane_b32 s2, v153
	s_ashr_i32 s5, s4, 31
	v_lshl_add_u64 v[138:139], v[138:139], 0, v[132:133]
	s_mov_b32 m0, s2
	s_lshl_b64 s[44:45], s[4:5], 11
	global_load_lds_dwordx4 v[138:139], off
	v_lshl_add_u64 v[138:139], s[42:43], 0, v[134:135]
	v_readfirstlane_b32 s2, v173
	s_add_u32 s44, s1, s44
	v_lshl_add_u64 v[138:139], v[138:139], 0, v[136:137]
	s_mov_b32 m0, s2
	s_addc_u32 s45, s23, s45
	global_load_lds_dwordx4 v[138:139], off
	v_lshl_add_u64 v[138:139], s[44:45], 0, v[130:131]
	v_readfirstlane_b32 s2, v152
	v_lshl_add_u64 v[138:139], v[138:139], 0, v[132:133]
	s_mov_b32 m0, s2
	s_add_u32 s42, s42, 0x40000
	global_load_lds_dwordx4 v[138:139], off
	v_lshl_add_u64 v[138:139], s[44:45], 0, v[134:135]
	v_readfirstlane_b32 s2, v174
	s_addc_u32 s43, s43, 0
	s_bitset1_b32 s4, 7
	v_lshl_add_u64 v[138:139], v[138:139], 0, v[136:137]
	s_mov_b32 m0, s2
	s_ashr_i32 s5, s4, 31
	global_load_lds_dwordx4 v[138:139], off
	v_lshl_add_u64 v[138:139], s[42:43], 0, v[130:131]
	v_readfirstlane_b32 s2, v151
	s_lshl_b64 s[4:5], s[4:5], 11
	v_lshl_add_u64 v[138:139], v[138:139], 0, v[132:133]
	s_mov_b32 m0, s2
	s_add_u32 s4, s1, s4
	global_load_lds_dwordx4 v[138:139], off
	v_lshl_add_u64 v[138:139], s[42:43], 0, v[134:135]
	v_readfirstlane_b32 s2, v175
	s_addc_u32 s5, s23, s5
	v_lshl_add_u64 v[138:139], v[138:139], 0, v[136:137]
	s_mov_b32 m0, s2
	v_lshl_add_u64 v[130:131], s[4:5], 0, v[130:131]
	v_readfirstlane_b32 s2, v176
	global_load_lds_dwordx4 v[138:139], off
	v_lshl_add_u64 v[130:131], v[130:131], 0, v[132:133]
	s_mov_b32 m0, s2
	v_readfirstlane_b32 s2, v177
	global_load_lds_dwordx4 v[130:131], off
	v_lshl_add_u64 v[130:131], s[4:5], 0, v[134:135]
	v_lshl_add_u64 v[130:131], v[130:131], 0, v[136:137]
	s_mov_b32 m0, s2
	s_nop 0
	global_load_lds_dwordx4 v[130:131], off

.LBB0_2971:
	ds_read_b128 v[176:179], v173
	ds_read_b128 v[180:183], v173 offset:1024
	ds_read_b128 v[184:187], v173 offset:2048
	ds_read_b128 v[188:191], v173 offset:3072
	v_add_u32_e32 v174, 0xc000, v157
	v_lshl_add_u64 v[240:241], s[2:3], 0, v[142:143]
	v_readfirstlane_b32 s31, v174
	v_add_u32_e32 v175, 0xe000, v157
	v_lshl_add_u64 v[224:225], v[240:241], 0, s[10:11]
	s_mov_b32 m0, s31
	v_lshl_add_u64 v[242:243], s[2:3], 0, v[144:145]
	v_readfirstlane_b32 s31, v175
	ds_read_b128 v[192:195], v155
	ds_read_b128 v[196:199], v155 offset:1024
	ds_read_b128 v[200:203], v154
	ds_read_b128 v[204:207], v154 offset:1024
	ds_read_b128 v[208:211], v153
	ds_read_b128 v[212:215], v153 offset:1024
	ds_read_b128 v[216:219], v152
	ds_read_b128 v[220:223], v152 offset:1024
	global_load_lds_dwordx4 v[224:225], off
	v_lshl_add_u64 v[224:225], v[242:243], 0, s[10:11]
	s_mov_b32 m0, s31
	s_nop 0
	global_load_lds_dwordx4 v[224:225], off
	s_barrier
	s_waitcnt lgkmcnt(0)
	v_mfma_f32_16x16x32_bf16 v[124:127], v[176:179], v[192:195], v[124:127]
	v_mfma_f32_16x16x32_bf16 v[120:123], v[184:187], v[192:195], v[120:123]
	v_mfma_f32_16x16x32_bf16 v[116:119], v[176:179], v[200:203], v[116:119]
	v_mfma_f32_16x16x32_bf16 v[112:115], v[184:187], v[200:203], v[112:115]
	v_mfma_f32_16x16x32_bf16 v[108:111], v[176:179], v[208:211], v[108:111]
	v_mfma_f32_16x16x32_bf16 v[104:107], v[184:187], v[208:211], v[104:107]
	v_mfma_f32_16x16x32_bf16 v[100:103], v[176:179], v[216:219], v[100:103]
	v_mfma_f32_16x16x32_bf16 v[96:99], v[184:187], v[216:219], v[96:99]
	v_mfma_f32_16x16x32_bf16 v[124:127], v[180:183], v[196:199], v[124:127]
	v_mfma_f32_16x16x32_bf16 v[120:123], v[188:191], v[196:199], v[120:123]
	v_mfma_f32_16x16x32_bf16 v[116:119], v[180:183], v[204:207], v[116:119]
	v_mfma_f32_16x16x32_bf16 v[112:115], v[188:191], v[204:207], v[112:115]
	v_mfma_f32_16x16x32_bf16 v[108:111], v[180:183], v[212:215], v[108:111]
	v_mfma_f32_16x16x32_bf16 v[104:107], v[188:191], v[212:215], v[104:107]
	v_mfma_f32_16x16x32_bf16 v[100:103], v[180:183], v[220:223], v[100:103]
	v_mfma_f32_16x16x32_bf16 v[96:99], v[188:191], v[220:223], v[96:99]
	s_barrier
	v_lshl_add_u64 v[244:245], s[2:3], 0, v[138:139]
	v_readfirstlane_b32 s31, v151
	v_lshl_add_u64 v[246:247], v[244:245], 0, s[12:13]
	s_mov_b32 m0, s31
	v_add_u32_e32 v250, 0x2000, v151
	ds_read_b128 v[224:227], v170
	ds_read_b128 v[228:231], v170 offset:1024
	ds_read_b128 v[232:235], v170 offset:2048
	ds_read_b128 v[236:239], v170 offset:3072
	global_load_lds_dwordx4 v[246:247], off
	v_lshl_add_u64 v[246:247], s[2:3], 0, v[140:141]
	v_readfirstlane_b32 s31, v250
	v_lshl_add_u64 v[248:249], v[246:247], 0, s[12:13]
	s_mov_b32 m0, s31
	s_nop 0
	global_load_lds_dwordx4 v[248:249], off
	s_barrier
	s_waitcnt lgkmcnt(0)
	v_mfma_f32_16x16x32_bf16 v[92:95], v[224:227], v[192:195], v[92:95]
	v_mfma_f32_16x16x32_bf16 v[88:91], v[232:235], v[192:195], v[88:91]
	v_mfma_f32_16x16x32_bf16 v[84:87], v[224:227], v[200:203], v[84:87]
	v_mfma_f32_16x16x32_bf16 v[80:83], v[232:235], v[200:203], v[80:83]
	v_mfma_f32_16x16x32_bf16 v[76:79], v[224:227], v[208:211], v[76:79]
	v_mfma_f32_16x16x32_bf16 v[72:75], v[232:235], v[208:211], v[72:75]
	v_mfma_f32_16x16x32_bf16 v[68:71], v[224:227], v[216:219], v[68:71]
	v_mfma_f32_16x16x32_bf16 v[64:67], v[232:235], v[216:219], v[64:67]
	v_mfma_f32_16x16x32_bf16 v[92:95], v[228:231], v[196:199], v[92:95]
	v_mfma_f32_16x16x32_bf16 v[88:91], v[236:239], v[196:199], v[88:91]
	v_mfma_f32_16x16x32_bf16 v[84:87], v[228:231], v[204:207], v[84:87]
	v_mfma_f32_16x16x32_bf16 v[80:83], v[236:239], v[204:207], v[80:83]
	v_mfma_f32_16x16x32_bf16 v[76:79], v[228:231], v[212:215], v[76:79]
	v_mfma_f32_16x16x32_bf16 v[72:75], v[236:239], v[212:215], v[72:75]
	v_mfma_f32_16x16x32_bf16 v[68:71], v[228:231], v[220:223], v[68:71]
	v_mfma_f32_16x16x32_bf16 v[64:67], v[236:239], v[220:223], v[64:67]
	v_readfirstlane_b32 s31, v157
	v_lshl_add_u64 v[248:249], v[240:241], 0, s[14:15]
	s_mov_b32 m0, s31
	v_readfirstlane_b32 s31, v158
	s_barrier
	ds_read_b128 v[192:195], v155 offset:16384
	ds_read_b128 v[196:199], v155 offset:17408
	ds_read_b128 v[200:203], v154 offset:16384
	ds_read_b128 v[204:207], v154 offset:17408
	ds_read_b128 v[208:211], v153 offset:16384
	ds_read_b128 v[212:215], v153 offset:17408
	ds_read_b128 v[216:219], v152 offset:16384
	ds_read_b128 v[220:223], v152 offset:17408
	global_load_lds_dwordx4 v[248:249], off
	v_lshl_add_u64 v[248:249], v[242:243], 0, s[14:15]
	s_mov_b32 m0, s31
	s_nop 0
	global_load_lds_dwordx4 v[248:249], off
	s_barrier
	s_waitcnt lgkmcnt(0)
	v_mfma_f32_16x16x32_bf16 v[60:63], v[176:179], v[192:195], v[60:63]
	v_mfma_f32_16x16x32_bf16 v[56:59], v[184:187], v[192:195], v[56:59]
	v_mfma_f32_16x16x32_bf16 v[52:55], v[176:179], v[200:203], v[52:55]
	v_mfma_f32_16x16x32_bf16 v[48:51], v[184:187], v[200:203], v[48:51]
	v_mfma_f32_16x16x32_bf16 v[44:47], v[176:179], v[208:211], v[44:47]
	v_mfma_f32_16x16x32_bf16 v[40:43], v[184:187], v[208:211], v[40:43]
	v_mfma_f32_16x16x32_bf16 v[36:39], v[176:179], v[216:219], v[36:39]
	v_mfma_f32_16x16x32_bf16 v[32:35], v[184:187], v[216:219], v[32:35]
	v_mfma_f32_16x16x32_bf16 v[60:63], v[180:183], v[196:199], v[60:63]
	v_mfma_f32_16x16x32_bf16 v[56:59], v[188:191], v[196:199], v[56:59]
	v_mfma_f32_16x16x32_bf16 v[52:55], v[180:183], v[204:207], v[52:55]
	v_mfma_f32_16x16x32_bf16 v[48:51], v[188:191], v[204:207], v[48:51]
	v_mfma_f32_16x16x32_bf16 v[44:47], v[180:183], v[212:215], v[44:47]
	v_mfma_f32_16x16x32_bf16 v[40:43], v[188:191], v[212:215], v[40:43]
	v_mfma_f32_16x16x32_bf16 v[36:39], v[180:183], v[220:223], v[36:39]
	v_mfma_f32_16x16x32_bf16 v[32:35], v[188:191], v[220:223], v[32:35]
	s_barrier
	v_readfirstlane_b32 s31, v159
	v_add_u32_e32 v178, 0x2000, v159
	v_lshl_add_u64 v[176:177], v[244:245], 0, s[16:17]
	s_mov_b32 m0, s31
	v_readfirstlane_b32 s31, v178
	global_load_lds_dwordx4 v[176:177], off
	v_lshl_add_u64 v[176:177], v[246:247], 0, s[16:17]
	s_mov_b32 m0, s31
	s_nop 0
	global_load_lds_dwordx4 v[176:177], off
	s_waitcnt vmcnt(6)
	s_barrier
	v_mfma_f32_16x16x32_bf16 v[28:31], v[224:227], v[192:195], v[28:31]
	v_mfma_f32_16x16x32_bf16 v[24:27], v[232:235], v[192:195], v[24:27]
	v_mfma_f32_16x16x32_bf16 v[20:23], v[224:227], v[200:203], v[20:23]
	v_mfma_f32_16x16x32_bf16 v[16:19], v[232:235], v[200:203], v[16:19]
	v_mfma_f32_16x16x32_bf16 v[12:15], v[224:227], v[208:211], v[12:15]
	v_mfma_f32_16x16x32_bf16 v[8:11], v[232:235], v[208:211], v[8:11]
	v_mfma_f32_16x16x32_bf16 v[4:7], v[224:227], v[216:219], v[4:7]
	v_mfma_f32_16x16x32_bf16 v[0:3], v[232:235], v[216:219], v[0:3]
	v_mfma_f32_16x16x32_bf16 v[28:31], v[228:231], v[196:199], v[28:31]
	v_mfma_f32_16x16x32_bf16 v[24:27], v[236:239], v[196:199], v[24:27]
	v_mfma_f32_16x16x32_bf16 v[20:23], v[228:231], v[204:207], v[20:23]
	v_mfma_f32_16x16x32_bf16 v[16:19], v[236:239], v[204:207], v[16:19]
	v_mfma_f32_16x16x32_bf16 v[12:15], v[228:231], v[212:215], v[12:15]
	v_mfma_f32_16x16x32_bf16 v[8:11], v[236:239], v[212:215], v[8:11]
	v_mfma_f32_16x16x32_bf16 v[4:7], v[228:231], v[220:223], v[4:7]
	v_mfma_f32_16x16x32_bf16 v[0:3], v[236:239], v[220:223], v[0:3]
	s_barrier
	ds_read_b128 v[176:179], v160
	ds_read_b128 v[180:183], v160 offset:1024
	ds_read_b128 v[184:187], v160 offset:2048
	ds_read_b128 v[188:191], v160 offset:3072
	v_readfirstlane_b32 s31, v161
	v_lshl_add_u64 v[224:225], v[240:241], 0, s[18:19]
	s_mov_b32 m0, s31
	v_readfirstlane_b32 s31, v162
	ds_read_b128 v[192:195], v155 offset:32768
	ds_read_b128 v[196:199], v155 offset:33792
	ds_read_b128 v[200:203], v154 offset:32768
	ds_read_b128 v[204:207], v154 offset:33792
	ds_read_b128 v[208:211], v153 offset:32768
	ds_read_b128 v[212:215], v153 offset:33792
	ds_read_b128 v[216:219], v152 offset:32768
	ds_read_b128 v[220:223], v152 offset:33792
	global_load_lds_dwordx4 v[224:225], off
	v_lshl_add_u64 v[224:225], v[242:243], 0, s[18:19]
	s_mov_b32 m0, s31
	s_nop 0
	global_load_lds_dwordx4 v[224:225], off
	s_barrier
	s_waitcnt lgkmcnt(0)
	v_mfma_f32_16x16x32_bf16 v[124:127], v[176:179], v[192:195], v[124:127]
	v_mfma_f32_16x16x32_bf16 v[120:123], v[184:187], v[192:195], v[120:123]
	v_mfma_f32_16x16x32_bf16 v[116:119], v[176:179], v[200:203], v[116:119]
	v_mfma_f32_16x16x32_bf16 v[112:115], v[184:187], v[200:203], v[112:115]
	v_mfma_f32_16x16x32_bf16 v[108:111], v[176:179], v[208:211], v[108:111]
	v_mfma_f32_16x16x32_bf16 v[104:107], v[184:187], v[208:211], v[104:107]
	v_mfma_f32_16x16x32_bf16 v[100:103], v[176:179], v[216:219], v[100:103]
	v_mfma_f32_16x16x32_bf16 v[96:99], v[184:187], v[216:219], v[96:99]
	v_mfma_f32_16x16x32_bf16 v[124:127], v[180:183], v[196:199], v[124:127]
	v_mfma_f32_16x16x32_bf16 v[120:123], v[188:191], v[196:199], v[120:123]
	v_mfma_f32_16x16x32_bf16 v[116:119], v[180:183], v[204:207], v[116:119]
	v_mfma_f32_16x16x32_bf16 v[112:115], v[188:191], v[204:207], v[112:115]
	v_mfma_f32_16x16x32_bf16 v[108:111], v[180:183], v[212:215], v[108:111]
	v_mfma_f32_16x16x32_bf16 v[104:107], v[188:191], v[212:215], v[104:107]
	v_mfma_f32_16x16x32_bf16 v[100:103], v[180:183], v[220:223], v[100:103]
	v_mfma_f32_16x16x32_bf16 v[96:99], v[188:191], v[220:223], v[96:99]
	s_barrier
	v_readfirstlane_b32 s31, v163
	v_lshl_add_u64 v[248:249], v[244:245], 0, s[20:21]
	s_mov_b32 m0, s31
	v_readfirstlane_b32 s31, v167
	ds_read_b128 v[224:227], v156
	ds_read_b128 v[228:231], v156 offset:1024
	ds_read_b128 v[232:235], v156 offset:2048
	ds_read_b128 v[236:239], v156 offset:3072
	global_load_lds_dwordx4 v[248:249], off
	v_lshl_add_u64 v[248:249], v[246:247], 0, s[20:21]
	s_mov_b32 m0, s31
	s_nop 0
	global_load_lds_dwordx4 v[248:249], off
	s_barrier
	s_waitcnt lgkmcnt(0)
	v_mfma_f32_16x16x32_bf16 v[92:95], v[224:227], v[192:195], v[92:95]
	v_mfma_f32_16x16x32_bf16 v[88:91], v[232:235], v[192:195], v[88:91]
	v_mfma_f32_16x16x32_bf16 v[84:87], v[224:227], v[200:203], v[84:87]
	v_mfma_f32_16x16x32_bf16 v[80:83], v[232:235], v[200:203], v[80:83]
	v_mfma_f32_16x16x32_bf16 v[76:79], v[224:227], v[208:211], v[76:79]
	v_mfma_f32_16x16x32_bf16 v[72:75], v[232:235], v[208:211], v[72:75]
	v_mfma_f32_16x16x32_bf16 v[68:71], v[224:227], v[216:219], v[68:71]
	v_mfma_f32_16x16x32_bf16 v[64:67], v[232:235], v[216:219], v[64:67]
	v_mfma_f32_16x16x32_bf16 v[92:95], v[228:231], v[196:199], v[92:95]
	v_mfma_f32_16x16x32_bf16 v[88:91], v[236:239], v[196:199], v[88:91]
	v_mfma_f32_16x16x32_bf16 v[84:87], v[228:231], v[204:207], v[84:87]
	v_mfma_f32_16x16x32_bf16 v[80:83], v[236:239], v[204:207], v[80:83]
	v_mfma_f32_16x16x32_bf16 v[76:79], v[228:231], v[212:215], v[76:79]
	v_mfma_f32_16x16x32_bf16 v[72:75], v[236:239], v[212:215], v[72:75]
	v_mfma_f32_16x16x32_bf16 v[68:71], v[228:231], v[220:223], v[68:71]
	v_mfma_f32_16x16x32_bf16 v[64:67], v[236:239], v[220:223], v[64:67]
	v_readfirstlane_b32 s31, v168
	v_lshl_add_u64 v[240:241], v[240:241], 0, s[24:25]
	s_mov_b32 m0, s31
	v_readfirstlane_b32 s31, v169
	s_barrier
	ds_read_b128 v[192:195], v155 offset:49152
	ds_read_b128 v[196:199], v155 offset:50176
	ds_read_b128 v[200:203], v154 offset:49152
	ds_read_b128 v[204:207], v154 offset:50176
	ds_read_b128 v[208:211], v153 offset:49152
	ds_read_b128 v[212:215], v153 offset:50176
	ds_read_b128 v[216:219], v152 offset:49152
	ds_read_b128 v[220:223], v152 offset:50176
	global_load_lds_dwordx4 v[240:241], off
	v_lshl_add_u64 v[240:241], v[242:243], 0, s[24:25]
	s_mov_b32 m0, s31
	s_nop 0
	global_load_lds_dwordx4 v[240:241], off
	s_barrier
	s_waitcnt lgkmcnt(0)
	v_mfma_f32_16x16x32_bf16 v[60:63], v[176:179], v[192:195], v[60:63]
	v_mfma_f32_16x16x32_bf16 v[56:59], v[184:187], v[192:195], v[56:59]
	v_mfma_f32_16x16x32_bf16 v[52:55], v[176:179], v[200:203], v[52:55]
	v_mfma_f32_16x16x32_bf16 v[48:51], v[184:187], v[200:203], v[48:51]
	v_mfma_f32_16x16x32_bf16 v[44:47], v[176:179], v[208:211], v[44:47]
	v_mfma_f32_16x16x32_bf16 v[40:43], v[184:187], v[208:211], v[40:43]
	v_mfma_f32_16x16x32_bf16 v[36:39], v[176:179], v[216:219], v[36:39]
	v_mfma_f32_16x16x32_bf16 v[32:35], v[184:187], v[216:219], v[32:35]
	v_mfma_f32_16x16x32_bf16 v[60:63], v[180:183], v[196:199], v[60:63]
	v_mfma_f32_16x16x32_bf16 v[56:59], v[188:191], v[196:199], v[56:59]
	v_mfma_f32_16x16x32_bf16 v[52:55], v[180:183], v[204:207], v[52:55]
	v_mfma_f32_16x16x32_bf16 v[48:51], v[188:191], v[204:207], v[48:51]
	v_mfma_f32_16x16x32_bf16 v[44:47], v[180:183], v[212:215], v[44:47]
	v_mfma_f32_16x16x32_bf16 v[40:43], v[188:191], v[212:215], v[40:43]
	v_mfma_f32_16x16x32_bf16 v[36:39], v[180:183], v[220:223], v[36:39]
	v_mfma_f32_16x16x32_bf16 v[32:35], v[188:191], v[220:223], v[32:35]
	s_barrier
	v_readfirstlane_b32 s31, v171
	v_lshl_add_u64 v[176:177], v[244:245], 0, s[26:27]
	s_mov_b32 m0, s31
	v_readfirstlane_b32 s31, v172
	global_load_lds_dwordx4 v[176:177], off
	v_lshl_add_u64 v[176:177], v[246:247], 0, s[26:27]
	s_mov_b32 m0, s31
	s_nop 0
	global_load_lds_dwordx4 v[176:177], off
	s_waitcnt vmcnt(6)
	s_barrier
	v_mfma_f32_16x16x32_bf16 v[28:31], v[224:227], v[192:195], v[28:31]
	v_mfma_f32_16x16x32_bf16 v[24:27], v[232:235], v[192:195], v[24:27]
	v_mfma_f32_16x16x32_bf16 v[20:23], v[224:227], v[200:203], v[20:23]
	v_mfma_f32_16x16x32_bf16 v[16:19], v[232:235], v[200:203], v[16:19]
	v_mfma_f32_16x16x32_bf16 v[12:15], v[224:227], v[208:211], v[12:15]
	v_mfma_f32_16x16x32_bf16 v[8:11], v[232:235], v[208:211], v[8:11]
	v_mfma_f32_16x16x32_bf16 v[4:7], v[224:227], v[216:219], v[4:7]
	v_mfma_f32_16x16x32_bf16 v[0:3], v[232:235], v[216:219], v[0:3]
	v_mfma_f32_16x16x32_bf16 v[28:31], v[228:231], v[196:199], v[28:31]
	v_mfma_f32_16x16x32_bf16 v[24:27], v[236:239], v[196:199], v[24:27]
	v_mfma_f32_16x16x32_bf16 v[20:23], v[228:231], v[204:207], v[20:23]
	v_mfma_f32_16x16x32_bf16 v[16:19], v[236:239], v[204:207], v[16:19]
	v_mfma_f32_16x16x32_bf16 v[12:15], v[228:231], v[212:215], v[12:15]
	v_mfma_f32_16x16x32_bf16 v[8:11], v[236:239], v[212:215], v[8:11]
	v_mfma_f32_16x16x32_bf16 v[4:7], v[228:231], v[220:223], v[4:7]
	v_mfma_f32_16x16x32_bf16 v[0:3], v[236:239], v[220:223], v[0:3]
	s_add_i32 s6, s6, 2
	v_lshl_add_u64 v[138:139], v[138:139], 0, s[28:29]
	v_lshl_add_u64 v[140:141], v[140:141], 0, s[28:29]
	v_lshl_add_u64 v[142:143], v[142:143], 0, s[28:29]
	s_cmp_lt_u32 s6, 60
	v_lshl_add_u64 v[144:145], v[144:145], 0, s[28:29]
	s_barrier
	s_cbranch_scc1 .LBB0_2971
	s_add_u32 s34, s34, 0x1f80
	s_addc_u32 s35, s35, 0
	v_lshl_add_u64 v[132:133], s[34:35], 0, v[132:133]
	v_readfirstlane_b32 s6, v174
	v_lshl_add_u64 v[130:131], v[130:131], 1, v[132:133]
	s_mov_b32 m0, s6
	ds_read_b128 v[138:141], v173
	ds_read_b128 v[142:145], v173 offset:1024
	ds_read_b128 v[176:179], v173 offset:2048
	ds_read_b128 v[180:183], v173 offset:3072
	ds_read_b128 v[184:187], v155
	ds_read_b128 v[188:191], v155 offset:1024
	ds_read_b128 v[192:195], v154
	ds_read_b128 v[196:199], v154 offset:1024
	ds_read_b128 v[200:203], v153
	ds_read_b128 v[204:207], v153 offset:1024
	ds_read_b128 v[208:211], v152
	ds_read_b128 v[212:215], v152 offset:1024
	global_load_lds_dwordx4 v[130:131], off
	v_lshl_add_u64 v[130:131], s[34:35], 0, v[136:137]
	v_readfirstlane_b32 s6, v175
	v_lshl_add_u64 v[130:131], v[134:135], 1, v[130:131]
	s_mov_b32 m0, s6
	s_nop 0
	global_load_lds_dwordx4 v[130:131], off
	s_barrier
	s_waitcnt lgkmcnt(0)
	v_mfma_f32_16x16x32_bf16 v[124:127], v[138:141], v[184:187], v[124:127]
	v_mfma_f32_16x16x32_bf16 v[116:119], v[138:141], v[192:195], v[116:119]
	v_mfma_f32_16x16x32_bf16 v[108:111], v[138:141], v[200:203], v[108:111]
	v_mfma_f32_16x16x32_bf16 v[100:103], v[138:141], v[208:211], v[100:103]
	v_mfma_f32_16x16x32_bf16 v[124:127], v[142:145], v[188:191], v[124:127]
	v_mfma_f32_16x16x32_bf16 v[120:123], v[176:179], v[184:187], v[120:123]
	v_mfma_f32_16x16x32_bf16 v[116:119], v[142:145], v[196:199], v[116:119]
	v_mfma_f32_16x16x32_bf16 v[112:115], v[176:179], v[192:195], v[112:115]
	v_mfma_f32_16x16x32_bf16 v[108:111], v[142:145], v[204:207], v[108:111]
	v_mfma_f32_16x16x32_bf16 v[104:107], v[176:179], v[200:203], v[104:107]
	v_mfma_f32_16x16x32_bf16 v[100:103], v[142:145], v[212:215], v[100:103]
	v_mfma_f32_16x16x32_bf16 v[96:99], v[176:179], v[208:211], v[96:99]
	v_mfma_f32_16x16x32_bf16 v[130:133], v[180:183], v[188:191], v[120:123]
	v_mfma_f32_16x16x32_bf16 v[134:137], v[180:183], v[196:199], v[112:115]
	v_mfma_f32_16x16x32_bf16 v[172:175], v[180:183], v[204:207], v[104:107]
	v_mfma_f32_16x16x32_bf16 v[216:219], v[180:183], v[212:215], v[96:99]
	s_barrier
	s_nop 1
	ds_read_b128 v[96:99], v170
	ds_read_b128 v[104:107], v170 offset:1024
	ds_read_b128 v[112:115], v170 offset:2048
	ds_read_b128 v[120:123], v170 offset:3072
	s_barrier
	s_waitcnt lgkmcnt(0)
	v_mfma_f32_16x16x32_bf16 v[92:95], v[96:99], v[184:187], v[92:95]
	v_mfma_f32_16x16x32_bf16 v[84:87], v[96:99], v[192:195], v[84:87]
	v_mfma_f32_16x16x32_bf16 v[76:79], v[96:99], v[200:203], v[76:79]
	v_mfma_f32_16x16x32_bf16 v[68:71], v[96:99], v[208:211], v[68:71]
	v_mfma_f32_16x16x32_bf16 v[92:95], v[104:107], v[188:191], v[92:95]
	v_mfma_f32_16x16x32_bf16 v[88:91], v[112:115], v[184:187], v[88:91]
	v_mfma_f32_16x16x32_bf16 v[84:87], v[104:107], v[196:199], v[84:87]
	v_mfma_f32_16x16x32_bf16 v[80:83], v[112:115], v[192:195], v[80:83]
	v_mfma_f32_16x16x32_bf16 v[76:79], v[104:107], v[204:207], v[76:79]
	v_mfma_f32_16x16x32_bf16 v[72:75], v[112:115], v[200:203], v[72:75]
	v_mfma_f32_16x16x32_bf16 v[68:71], v[104:107], v[212:215], v[68:71]
	v_mfma_f32_16x16x32_bf16 v[64:67], v[112:115], v[208:211], v[64:67]
	v_mfma_f32_16x16x32_bf16 v[168:171], v[120:123], v[188:191], v[88:91]
	v_mfma_f32_16x16x32_bf16 v[184:187], v[120:123], v[196:199], v[80:83]
	v_mfma_f32_16x16x32_bf16 v[188:191], v[120:123], v[204:207], v[72:75]
	v_mfma_f32_16x16x32_bf16 v[192:195], v[120:123], v[212:215], v[64:67]
	s_barrier
	s_nop 1
	ds_read_b128 v[64:67], v155 offset:16384
	ds_read_b128 v[72:75], v155 offset:17408
	ds_read_b128 v[80:83], v154 offset:16384
	ds_read_b128 v[88:91], v154 offset:17408
	ds_read_b128 v[196:199], v153 offset:16384
	ds_read_b128 v[200:203], v153 offset:17408
	ds_read_b128 v[204:207], v152 offset:16384
	ds_read_b128 v[208:211], v152 offset:17408
	s_waitcnt vmcnt(4)
	s_barrier
	s_waitcnt lgkmcnt(0)
	v_mfma_f32_16x16x32_bf16 v[60:63], v[138:141], v[64:67], v[60:63]
	v_mfma_f32_16x16x32_bf16 v[52:55], v[138:141], v[80:83], v[52:55]
	v_mfma_f32_16x16x32_bf16 v[44:47], v[138:141], v[196:199], v[44:47]
	v_mfma_f32_16x16x32_bf16 v[36:39], v[138:141], v[204:207], v[36:39]
	v_mfma_f32_16x16x32_bf16 v[60:63], v[142:145], v[72:75], v[60:63]
	v_mfma_f32_16x16x32_bf16 v[56:59], v[176:179], v[64:67], v[56:59]
	v_mfma_f32_16x16x32_bf16 v[52:55], v[142:145], v[88:91], v[52:55]
	v_mfma_f32_16x16x32_bf16 v[48:51], v[176:179], v[80:83], v[48:51]
	v_mfma_f32_16x16x32_bf16 v[44:47], v[142:145], v[200:203], v[44:47]
	v_mfma_f32_16x16x32_bf16 v[40:43], v[176:179], v[196:199], v[40:43]
	v_mfma_f32_16x16x32_bf16 v[36:39], v[142:145], v[208:211], v[36:39]
	v_mfma_f32_16x16x32_bf16 v[32:35], v[176:179], v[204:207], v[32:35]
	v_mfma_f32_16x16x32_bf16 v[212:215], v[180:183], v[72:75], v[56:59]
	v_mfma_f32_16x16x32_bf16 v[220:223], v[180:183], v[88:91], v[48:51]
	v_mfma_f32_16x16x32_bf16 v[224:227], v[180:183], v[200:203], v[40:43]
	v_mfma_f32_16x16x32_bf16 v[138:141], v[180:183], v[208:211], v[32:35]
	v_mfma_f32_16x16x32_bf16 v[28:31], v[96:99], v[64:67], v[28:31]
	v_mfma_f32_16x16x32_bf16 v[20:23], v[96:99], v[80:83], v[20:23]
	v_mfma_f32_16x16x32_bf16 v[12:15], v[96:99], v[196:199], v[12:15]
	v_mfma_f32_16x16x32_bf16 v[4:7], v[96:99], v[204:207], v[4:7]
	v_mfma_f32_16x16x32_bf16 v[28:31], v[104:107], v[72:75], v[28:31]
	v_mfma_f32_16x16x32_bf16 v[24:27], v[112:115], v[64:67], v[24:27]
	v_mfma_f32_16x16x32_bf16 v[20:23], v[104:107], v[88:91], v[20:23]
	v_mfma_f32_16x16x32_bf16 v[16:19], v[112:115], v[80:83], v[16:19]
	v_mfma_f32_16x16x32_bf16 v[12:15], v[104:107], v[200:203], v[12:15]
	v_mfma_f32_16x16x32_bf16 v[8:11], v[112:115], v[196:199], v[8:11]
	v_mfma_f32_16x16x32_bf16 v[4:7], v[104:107], v[208:211], v[4:7]
	v_mfma_f32_16x16x32_bf16 v[0:3], v[112:115], v[204:207], v[0:3]
	v_mfma_f32_16x16x32_bf16 v[142:145], v[120:123], v[72:75], v[24:27]
	v_mfma_f32_16x16x32_bf16 v[176:179], v[120:123], v[88:91], v[16:19]
	v_mfma_f32_16x16x32_bf16 v[180:183], v[120:123], v[200:203], v[8:11]
	v_mfma_f32_16x16x32_bf16 v[196:199], v[120:123], v[208:211], v[0:3]
	s_barrier
	s_nop 1
	ds_read_b128 v[0:3], v160
	ds_read_b128 v[8:11], v160 offset:1024
	ds_read_b128 v[16:19], v160 offset:2048
	ds_read_b128 v[24:27], v160 offset:3072
	ds_read_b128 v[32:35], v155 offset:32768
	ds_read_b128 v[40:43], v155 offset:33792
	ds_read_b128 v[48:51], v154 offset:32768
	ds_read_b128 v[56:59], v154 offset:33792
	ds_read_b128 v[64:67], v153 offset:32768
	ds_read_b128 v[158:161], v153 offset:33792
	ds_read_b128 v[200:203], v152 offset:32768
	ds_read_b128 v[204:207], v152 offset:33792
	s_waitcnt vmcnt(2)
	s_barrier
	s_waitcnt lgkmcnt(0)
	v_mfma_f32_16x16x32_bf16 v[72:75], v[0:3], v[32:35], v[124:127]
	v_mfma_f32_16x16x32_bf16 v[120:123], v[8:11], v[40:43], v[72:75]
	v_mfma_f32_16x16x32_bf16 v[72:75], v[16:19], v[32:35], v[130:133]
	v_mfma_f32_16x16x32_bf16 v[124:127], v[24:27], v[40:43], v[72:75]
	v_mfma_f32_16x16x32_bf16 v[72:75], v[0:3], v[48:51], v[116:119]
	v_mfma_f32_16x16x32_bf16 v[112:115], v[8:11], v[56:59], v[72:75]
	v_mfma_f32_16x16x32_bf16 v[72:75], v[16:19], v[48:51], v[134:137]
	v_mfma_f32_16x16x32_bf16 v[116:119], v[24:27], v[56:59], v[72:75]
	v_mfma_f32_16x16x32_bf16 v[72:75], v[0:3], v[64:67], v[108:111]
	v_mfma_f32_16x16x32_bf16 v[104:107], v[8:11], v[158:161], v[72:75]
	v_mfma_f32_16x16x32_bf16 v[72:75], v[16:19], v[64:67], v[172:175]
	v_mfma_f32_16x16x32_bf16 v[108:111], v[24:27], v[158:161], v[72:75]
	v_mfma_f32_16x16x32_bf16 v[72:75], v[0:3], v[200:203], v[100:103]
	v_mfma_f32_16x16x32_bf16 v[96:99], v[8:11], v[204:207], v[72:75]
	v_mfma_f32_16x16x32_bf16 v[72:75], v[16:19], v[200:203], v[216:219]
	v_mfma_f32_16x16x32_bf16 v[100:103], v[24:27], v[204:207], v[72:75]
	s_barrier
	ds_read_b128 v[130:133], v156
	ds_read_b128 v[134:137], v156 offset:1024
	ds_read_b128 v[172:175], v156 offset:2048
	ds_read_b128 v[208:211], v156 offset:3072
	s_waitcnt vmcnt(0)
	s_barrier
	s_waitcnt lgkmcnt(0)
	v_mfma_f32_16x16x32_bf16 v[72:75], v[130:133], v[32:35], v[92:95]
	v_mfma_f32_16x16x32_bf16 v[32:35], v[172:175], v[32:35], v[168:171]
	v_mfma_f32_16x16x32_bf16 v[92:95], v[208:211], v[40:43], v[32:35]
	v_mfma_f32_16x16x32_bf16 v[32:35], v[130:133], v[48:51], v[84:87]
	v_mfma_f32_16x16x32_bf16 v[80:83], v[134:137], v[56:59], v[32:35]
	v_mfma_f32_16x16x32_bf16 v[32:35], v[172:175], v[48:51], v[184:187]
	v_mfma_f32_16x16x32_bf16 v[84:87], v[208:211], v[56:59], v[32:35]
	v_mfma_f32_16x16x32_bf16 v[32:35], v[130:133], v[64:67], v[76:79]
	v_mfma_f32_16x16x32_bf16 v[88:91], v[134:137], v[40:43], v[72:75]
	v_mfma_f32_16x16x32_bf16 v[72:75], v[134:137], v[158:161], v[32:35]
	v_mfma_f32_16x16x32_bf16 v[32:35], v[172:175], v[64:67], v[188:191]
	v_mfma_f32_16x16x32_bf16 v[76:79], v[208:211], v[158:161], v[32:35]
	v_mfma_f32_16x16x32_bf16 v[32:35], v[130:133], v[200:203], v[68:71]
	v_mfma_f32_16x16x32_bf16 v[64:67], v[134:137], v[204:207], v[32:35]
	v_mfma_f32_16x16x32_bf16 v[32:35], v[172:175], v[200:203], v[192:195]
	v_mfma_f32_16x16x32_bf16 v[68:71], v[208:211], v[204:207], v[32:35]
	s_barrier
	ds_read_b128 v[156:159], v155 offset:49152
	ds_read_b128 v[160:163], v155 offset:50176
	ds_read_b128 v[168:171], v154 offset:49152
	ds_read_b128 v[184:187], v154 offset:50176
	ds_read_b128 v[188:191], v153 offset:49152
	ds_read_b128 v[192:195], v153 offset:50176
	ds_read_b128 v[200:203], v152 offset:49152
	ds_read_b128 v[152:155], v152 offset:50176
	s_barrier
	s_waitcnt lgkmcnt(0)
	v_mfma_f32_16x16x32_bf16 v[32:35], v[0:3], v[156:159], v[60:63]
	v_mfma_f32_16x16x32_bf16 v[56:59], v[8:11], v[160:163], v[32:35]
	v_mfma_f32_16x16x32_bf16 v[32:35], v[16:19], v[156:159], v[212:215]
	v_mfma_f32_16x16x32_bf16 v[60:63], v[24:27], v[160:163], v[32:35]
	v_mfma_f32_16x16x32_bf16 v[32:35], v[0:3], v[168:171], v[52:55]
	v_mfma_f32_16x16x32_bf16 v[48:51], v[8:11], v[184:187], v[32:35]
	v_mfma_f32_16x16x32_bf16 v[32:35], v[16:19], v[168:171], v[220:223]
	v_mfma_f32_16x16x32_bf16 v[52:55], v[24:27], v[184:187], v[32:35]
	v_mfma_f32_16x16x32_bf16 v[32:35], v[0:3], v[188:191], v[44:47]
	v_mfma_f32_16x16x32_bf16 v[40:43], v[8:11], v[192:195], v[32:35]
	v_mfma_f32_16x16x32_bf16 v[32:35], v[16:19], v[188:191], v[224:227]
	v_mfma_f32_16x16x32_bf16 v[0:3], v[0:3], v[200:203], v[36:39]
	v_mfma_f32_16x16x32_bf16 v[44:47], v[24:27], v[192:195], v[32:35]
	v_mfma_f32_16x16x32_bf16 v[32:35], v[8:11], v[152:155], v[0:3]
	v_mfma_f32_16x16x32_bf16 v[0:3], v[16:19], v[200:203], v[138:141]
	v_mfma_f32_16x16x32_bf16 v[36:39], v[24:27], v[152:155], v[0:3]
	v_mfma_f32_16x16x32_bf16 v[0:3], v[130:133], v[156:159], v[28:31]
	v_mfma_f32_16x16x32_bf16 v[24:27], v[134:137], v[160:163], v[0:3]
	v_mfma_f32_16x16x32_bf16 v[0:3], v[172:175], v[156:159], v[142:145]
	v_mfma_f32_16x16x32_bf16 v[28:31], v[208:211], v[160:163], v[0:3]
	v_mfma_f32_16x16x32_bf16 v[0:3], v[130:133], v[168:171], v[20:23]
	v_mfma_f32_16x16x32_bf16 v[16:19], v[134:137], v[184:187], v[0:3]
	v_mfma_f32_16x16x32_bf16 v[0:3], v[172:175], v[168:171], v[176:179]
	v_mfma_f32_16x16x32_bf16 v[20:23], v[208:211], v[184:187], v[0:3]
	v_mfma_f32_16x16x32_bf16 v[0:3], v[130:133], v[188:191], v[12:15]
	v_mfma_f32_16x16x32_bf16 v[8:11], v[134:137], v[192:195], v[0:3]
	v_mfma_f32_16x16x32_bf16 v[0:3], v[172:175], v[188:191], v[180:183]
	v_mfma_f32_16x16x32_bf16 v[12:15], v[208:211], v[192:195], v[0:3]
	v_mfma_f32_16x16x32_bf16 v[0:3], v[130:133], v[200:203], v[4:7]
	v_mfma_f32_16x16x32_bf16 v[4:7], v[172:175], v[200:203], v[196:199]
	v_mfma_f32_16x16x32_bf16 v[0:3], v[134:137], v[152:155], v[0:3]
	v_mfma_f32_16x16x32_bf16 v[4:7], v[208:211], v[152:155], v[4:7]
	v_cmp_gt_u32_e32 vcc, s56, v128
	s_barrier
	s_and_saveexec_b64 s[34:35], vcc
	s_cbranch_execz .LBB0_2967
	s_barrier
	s_branch .LBB0_2967
